# g2 + PEER u-side: dot accumulator chains start with v_dot2_f32_bf16 src2=0 (VOP3P form throughout), no zero-init movs
# speedup vs baseline: 1.0033x; 1.0033x over previous
; #define P4_FOR16(M) M(0) M(1) M(2) M(3) M(4) M(5) M(6) M(7) M(8) M(9) M(10) M(11) M(12) M(13) M(14) M(15)
; #define P4_U(i) { P4_DOT(b##i, part[i]); const int nk_ = __builtin_amdgcn_readlane(ksel, nb + i); P4_LOAD(b##i, Ug, nk_); }
; #define P4_U(i) { P4_DOT(b##i, part[i]); const int nk_ = __builtin_amdgcn_readlane(kn, i); P4_LOAD(b##i, nbase, nk_); }
; __device__ __forceinline__ void peer_gather_f4p(const float* X, const int* __restrict__ IDX, const float* __restrict__ G, ...
;     ...
;         for (int bt = 0; bt < 7; ++bt) {
;             const int ksel = (bt + 1 < 4) ? k0 : k1;
;             const int nb = (16 * (bt + 1)) & 63;
;     ...
;             P4_FOR16(P4_U)
;     ...
;             P4_RED(bt);
.LBB0_533:
	s_mov_b32 s87, s86
	s_waitcnt vmcnt(15)
	v_cvt_scalef32_pk_bf16_fp4 v48, v64, 1.0
	v_cvt_scalef32_pk_bf16_fp4 v50, v64, 1.0 op_sel:[1,0,0]
	v_cvt_scalef32_pk_bf16_fp4 v52, v64, 1.0 op_sel:[0,1,0]
	v_cvt_scalef32_pk_bf16_fp4 v54, v64, 1.0 op_sel:[1,1,0]
	v_dot2_f32_bf16 v56, v48, v6, 0
	v_dot2_f32_bf16 v48, v50, v4, 0
	v_dot2_f32_bf16 v56, v52, v10, v56
	s_cmp_lt_u32 s29, 3
	v_dot2_f32_bf16 v48, v54, v8, v48
	v_cvt_scalef32_pk_bf16_fp4 v50, v65, 1.0
	v_cvt_scalef32_pk_bf16_fp4 v52, v65, 1.0 op_sel:[1,0,0]
	v_cvt_scalef32_pk_bf16_fp4 v54, v65, 1.0 op_sel:[0,1,0]
	v_cvt_scalef32_pk_bf16_fp4 v58, v65, 1.0 op_sel:[1,1,0]
	s_cselect_b64 s[50:51], -1, 0
	v_dot2_f32_bf16 v56, v50, v14, v56
	v_dot2_f32_bf16 v48, v52, v12, v48
	s_waitcnt lgkmcnt(1)
	v_cndmask_b32_e64 v46, v39, v38, s[50:51]
	v_dot2_f32_bf16 v56, v54, v18, v56
	v_dot2_f32_bf16 v48, v58, v16, v48
	v_cvt_scalef32_pk_bf16_fp4 v50, v66, 1.0
	v_cvt_scalef32_pk_bf16_fp4 v52, v66, 1.0 op_sel:[1,0,0]
	v_cvt_scalef32_pk_bf16_fp4 v54, v66, 1.0 op_sel:[0,1,0]
	v_cvt_scalef32_pk_bf16_fp4 v58, v66, 1.0 op_sel:[1,1,0]
	s_add_i32 s12, s28, -15
	v_dot2_f32_bf16 v56, v50, v22, v56
	v_dot2_f32_bf16 v48, v52, v20, v48
	v_readlane_b32 s12, v46, s12
	v_dot2_f32_bf16 v56, v54, v26, v56
	v_dot2_f32_bf16 v48, v58, v24, v48
	v_cvt_scalef32_pk_bf16_fp4 v50, v67, 1.0
	v_cvt_scalef32_pk_bf16_fp4 v52, v67, 1.0 op_sel:[1,0,0]
	v_cvt_scalef32_pk_bf16_fp4 v54, v67, 1.0 op_sel:[0,1,0]
	v_cvt_scalef32_pk_bf16_fp4 v58, v67, 1.0 op_sel:[1,1,0]
	s_lshr_b32 s12, s12, 7
	v_dot2_f32_bf16 v56, v50, v30, v56
	v_dot2_f32_bf16 v48, v52, v28, v48
	s_mov_b32 s13, s86
	v_dot2_f32_bf16 v56, v54, v36, v56
	v_dot2_f32_bf16 v48, v58, v34, v48
	s_lshl_b64 s[12:13], s[12:13], 10
	s_nop 2
	v_add_f32_e32 v47, v56, v48
	v_lshl_add_u64 v[48:49], v[40:41], 0, s[12:13]
	global_load_dwordx4 v[64:67], v[48:49], off
	s_waitcnt vmcnt(15)
	v_cvt_scalef32_pk_bf16_fp4 v48, v68, 1.0
	v_cvt_scalef32_pk_bf16_fp4 v50, v68, 1.0 op_sel:[1,0,0]
	v_cvt_scalef32_pk_bf16_fp4 v52, v68, 1.0 op_sel:[0,1,0]
	v_cvt_scalef32_pk_bf16_fp4 v54, v68, 1.0 op_sel:[1,1,0]
	v_dot2_f32_bf16 v56, v48, v6, 0
	v_dot2_f32_bf16 v48, v50, v4, 0
	v_dot2_f32_bf16 v56, v52, v10, v56
	s_add_i32 s12, s28, -14
	v_dot2_f32_bf16 v48, v54, v8, v48
	v_cvt_scalef32_pk_bf16_fp4 v50, v69, 1.0
	v_cvt_scalef32_pk_bf16_fp4 v52, v69, 1.0 op_sel:[1,0,0]
	v_cvt_scalef32_pk_bf16_fp4 v54, v69, 1.0 op_sel:[0,1,0]
	v_cvt_scalef32_pk_bf16_fp4 v58, v69, 1.0 op_sel:[1,1,0]
	v_readlane_b32 s12, v46, s12
	v_dot2_f32_bf16 v56, v50, v14, v56
	v_dot2_f32_bf16 v48, v52, v12, v48
	s_lshr_b32 s12, s12, 7
	v_dot2_f32_bf16 v56, v54, v18, v56
	v_dot2_f32_bf16 v48, v58, v16, v48
	v_cvt_scalef32_pk_bf16_fp4 v50, v70, 1.0
	v_cvt_scalef32_pk_bf16_fp4 v52, v70, 1.0 op_sel:[1,0,0]
	v_cvt_scalef32_pk_bf16_fp4 v54, v70, 1.0 op_sel:[0,1,0]
	v_cvt_scalef32_pk_bf16_fp4 v58, v70, 1.0 op_sel:[1,1,0]
	s_mov_b32 s13, s86
	v_dot2_f32_bf16 v56, v50, v22, v56
	v_dot2_f32_bf16 v48, v52, v20, v48
	s_lshl_b64 s[12:13], s[12:13], 10
	v_dot2_f32_bf16 v56, v54, v26, v56
	v_dot2_f32_bf16 v48, v58, v24, v48
	v_cvt_scalef32_pk_bf16_fp4 v50, v71, 1.0
	v_cvt_scalef32_pk_bf16_fp4 v52, v71, 1.0 op_sel:[1,0,0]
	v_cvt_scalef32_pk_bf16_fp4 v54, v71, 1.0 op_sel:[0,1,0]
	v_cvt_scalef32_pk_bf16_fp4 v58, v71, 1.0 op_sel:[1,1,0]
	v_mov_b32_e32 v100, 0
	v_dot2_f32_bf16 v56, v50, v30, v56
	v_dot2_f32_bf16 v48, v52, v28, v48
	v_mov_b32_e32 v42, 0
	v_dot2_f32_bf16 v56, v54, v36, v56
	v_dot2_f32_bf16 v48, v58, v34, v48
	s_nop 2
	v_add_f32_e32 v48, v56, v48
	v_lshl_add_u64 v[50:51], v[40:41], 0, s[12:13]
	global_load_dwordx4 v[68:71], v[50:51], off
	s_waitcnt vmcnt(15)
	v_cvt_scalef32_pk_bf16_fp4 v50, v72, 1.0
	v_cvt_scalef32_pk_bf16_fp4 v52, v72, 1.0 op_sel:[1,0,0]
	v_cvt_scalef32_pk_bf16_fp4 v54, v72, 1.0 op_sel:[0,1,0]
	v_cvt_scalef32_pk_bf16_fp4 v56, v72, 1.0 op_sel:[1,1,0]
	s_add_i32 s12, s28, -13
	v_dot2_f32_bf16 v58, v50, v6, 0
	v_dot2_f32_bf16 v50, v52, v4, 0
	v_dot2_f32_bf16 v58, v54, v10, v58
	v_readlane_b32 s12, v46, s12
	v_dot2_f32_bf16 v50, v56, v8, v50
	v_cvt_scalef32_pk_bf16_fp4 v52, v73, 1.0
	v_cvt_scalef32_pk_bf16_fp4 v54, v73, 1.0 op_sel:[1,0,0]
	v_cvt_scalef32_pk_bf16_fp4 v56, v73, 1.0 op_sel:[0,1,0]
	v_cvt_scalef32_pk_bf16_fp4 v60, v73, 1.0 op_sel:[1,1,0]
	s_lshr_b32 s12, s12, 7
	v_dot2_f32_bf16 v58, v52, v14, v58
	v_dot2_f32_bf16 v50, v54, v12, v50
	s_mov_b32 s13, s86
	v_dot2_f32_bf16 v58, v56, v18, v58
	v_dot2_f32_bf16 v50, v60, v16, v50
	v_cvt_scalef32_pk_bf16_fp4 v52, v74, 1.0
	v_cvt_scalef32_pk_bf16_fp4 v54, v74, 1.0 op_sel:[1,0,0]
	v_cvt_scalef32_pk_bf16_fp4 v56, v74, 1.0 op_sel:[0,1,0]
	v_cvt_scalef32_pk_bf16_fp4 v60, v74, 1.0 op_sel:[1,1,0]
	s_lshl_b64 s[12:13], s[12:13], 10
	v_dot2_f32_bf16 v58, v52, v22, v58
	v_dot2_f32_bf16 v50, v54, v20, v50
	s_nop 0
	v_dot2_f32_bf16 v58, v56, v26, v58
	v_dot2_f32_bf16 v50, v60, v24, v50
	v_cvt_scalef32_pk_bf16_fp4 v52, v75, 1.0
	v_cvt_scalef32_pk_bf16_fp4 v54, v75, 1.0 op_sel:[1,0,0]
	v_cvt_scalef32_pk_bf16_fp4 v56, v75, 1.0 op_sel:[0,1,0]
	v_cvt_scalef32_pk_bf16_fp4 v60, v75, 1.0 op_sel:[1,1,0]
	s_nop 0
	v_dot2_f32_bf16 v58, v52, v30, v58
	v_dot2_f32_bf16 v50, v54, v28, v50
	s_nop 0
	v_dot2_f32_bf16 v58, v56, v36, v58
	v_dot2_f32_bf16 v50, v60, v34, v50
	s_nop 0
	s_nop 2
	v_add_f32_e32 v49, v58, v50
	v_lshl_add_u64 v[50:51], v[40:41], 0, s[12:13]
	global_load_dwordx4 v[72:75], v[50:51], off
	s_waitcnt vmcnt(15)
; #define P4_FOR16(M) M(0) M(1) M(2) M(3) M(4) M(5) M(6) M(7) M(8) M(9) M(10) M(11) M(12) M(13) M(14) M(15)
; #define P4_U(i) { P4_DOT(b##i, part[i]); const int nk_ = __builtin_amdgcn_readlane(ksel, nb + i); P4_LOAD(b##i, Ug, nk_); }
; #define P4_U(i) { P4_DOT(b##i, part[i]); const int nk_ = __builtin_amdgcn_readlane(kn, i); P4_LOAD(b##i, nbase, nk_); }
; __device__ __forceinline__ void peer_gather_f4p(const float* X, const int* __restrict__ IDX, const float* __restrict__ G, ...
;     ...
;         for (int bt = 0; bt < 7; ++bt) {
;             const int ksel = (bt + 1 < 4) ? k0 : k1;
;             const int nb = (16 * (bt + 1)) & 63;
;     ...
;             P4_FOR16(P4_U)
;     ...
;             P4_RED(bt);
	v_cvt_scalef32_pk_bf16_fp4 v50, v76, 1.0
	v_cvt_scalef32_pk_bf16_fp4 v52, v76, 1.0 op_sel:[1,0,0]
	v_cvt_scalef32_pk_bf16_fp4 v54, v76, 1.0 op_sel:[0,1,0]
	v_cvt_scalef32_pk_bf16_fp4 v56, v76, 1.0 op_sel:[1,1,0]
	v_dot2_f32_bf16 v58, v50, v6, 0
	v_dot2_f32_bf16 v50, v52, v4, 0
	v_dot2_f32_bf16 v58, v54, v10, v58
	s_add_i32 s12, s28, -12
	v_dot2_f32_bf16 v50, v56, v8, v50
	v_cvt_scalef32_pk_bf16_fp4 v52, v77, 1.0
	v_cvt_scalef32_pk_bf16_fp4 v54, v77, 1.0 op_sel:[1,0,0]
	v_cvt_scalef32_pk_bf16_fp4 v56, v77, 1.0 op_sel:[0,1,0]
	v_cvt_scalef32_pk_bf16_fp4 v60, v77, 1.0 op_sel:[1,1,0]
	v_readlane_b32 s12, v46, s12
	v_dot2_f32_bf16 v58, v52, v14, v58
	v_dot2_f32_bf16 v50, v54, v12, v50
	s_lshr_b32 s12, s12, 7
	v_dot2_f32_bf16 v58, v56, v18, v58
	v_dot2_f32_bf16 v50, v60, v16, v50
	v_cvt_scalef32_pk_bf16_fp4 v52, v78, 1.0
	v_cvt_scalef32_pk_bf16_fp4 v54, v78, 1.0 op_sel:[1,0,0]
	v_cvt_scalef32_pk_bf16_fp4 v56, v78, 1.0 op_sel:[0,1,0]
	v_cvt_scalef32_pk_bf16_fp4 v60, v78, 1.0 op_sel:[1,1,0]
	s_mov_b32 s13, s86
	v_dot2_f32_bf16 v58, v52, v22, v58
	v_dot2_f32_bf16 v50, v54, v20, v50
	s_lshl_b64 s[12:13], s[12:13], 10
	v_dot2_f32_bf16 v58, v56, v26, v58
	v_dot2_f32_bf16 v50, v60, v24, v50
	v_cvt_scalef32_pk_bf16_fp4 v52, v79, 1.0
	v_cvt_scalef32_pk_bf16_fp4 v54, v79, 1.0 op_sel:[1,0,0]
	v_cvt_scalef32_pk_bf16_fp4 v56, v79, 1.0 op_sel:[0,1,0]
	v_cvt_scalef32_pk_bf16_fp4 v60, v79, 1.0 op_sel:[1,1,0]
	s_nop 0
	v_dot2_f32_bf16 v58, v52, v30, v58
	v_dot2_f32_bf16 v50, v54, v28, v50
	s_nop 0
	v_dot2_f32_bf16 v58, v56, v36, v58
	v_dot2_f32_bf16 v50, v60, v34, v50
	s_nop 2
	v_add_f32_e32 v50, v58, v50
	v_lshl_add_u64 v[52:53], v[40:41], 0, s[12:13]
	global_load_dwordx4 v[76:79], v[52:53], off
	s_waitcnt vmcnt(15)
	v_cvt_scalef32_pk_bf16_fp4 v52, v80, 1.0
	v_cvt_scalef32_pk_bf16_fp4 v54, v80, 1.0 op_sel:[1,0,0]
	v_cvt_scalef32_pk_bf16_fp4 v56, v80, 1.0 op_sel:[0,1,0]
	v_cvt_scalef32_pk_bf16_fp4 v58, v80, 1.0 op_sel:[1,1,0]
	s_add_i32 s12, s28, -11
	v_dot2_f32_bf16 v60, v52, v6, 0
	v_dot2_f32_bf16 v52, v54, v4, 0
	v_dot2_f32_bf16 v60, v56, v10, v60
	v_readlane_b32 s12, v46, s12
	v_dot2_f32_bf16 v52, v58, v8, v52
	v_cvt_scalef32_pk_bf16_fp4 v54, v81, 1.0
	v_cvt_scalef32_pk_bf16_fp4 v56, v81, 1.0 op_sel:[1,0,0]
	v_cvt_scalef32_pk_bf16_fp4 v58, v81, 1.0 op_sel:[0,1,0]
	v_cvt_scalef32_pk_bf16_fp4 v62, v81, 1.0 op_sel:[1,1,0]
	s_lshr_b32 s12, s12, 7
	v_dot2_f32_bf16 v60, v54, v14, v60
	v_dot2_f32_bf16 v52, v56, v12, v52
	s_mov_b32 s13, s86
	v_dot2_f32_bf16 v60, v58, v18, v60
	v_dot2_f32_bf16 v52, v62, v16, v52
	v_cvt_scalef32_pk_bf16_fp4 v54, v82, 1.0
	v_cvt_scalef32_pk_bf16_fp4 v56, v82, 1.0 op_sel:[1,0,0]
	v_cvt_scalef32_pk_bf16_fp4 v58, v82, 1.0 op_sel:[0,1,0]
	v_cvt_scalef32_pk_bf16_fp4 v62, v82, 1.0 op_sel:[1,1,0]
	s_lshl_b64 s[12:13], s[12:13], 10
	v_dot2_f32_bf16 v60, v54, v22, v60
	v_dot2_f32_bf16 v52, v56, v20, v52
	s_nop 0
	v_dot2_f32_bf16 v60, v58, v26, v60
	v_dot2_f32_bf16 v52, v62, v24, v52
	v_cvt_scalef32_pk_bf16_fp4 v54, v83, 1.0
	v_cvt_scalef32_pk_bf16_fp4 v56, v83, 1.0 op_sel:[1,0,0]
	v_cvt_scalef32_pk_bf16_fp4 v58, v83, 1.0 op_sel:[0,1,0]
	v_cvt_scalef32_pk_bf16_fp4 v62, v83, 1.0 op_sel:[1,1,0]
	s_nop 0
	v_dot2_f32_bf16 v60, v54, v30, v60
	v_dot2_f32_bf16 v52, v56, v28, v52
	s_nop 0
	v_dot2_f32_bf16 v60, v58, v36, v60
	v_dot2_f32_bf16 v52, v62, v34, v52
	s_nop 0
	s_nop 2
	v_add_f32_e32 v51, v60, v52
	v_lshl_add_u64 v[52:53], v[40:41], 0, s[12:13]
	global_load_dwordx4 v[80:83], v[52:53], off
	s_waitcnt vmcnt(15)
	v_cvt_scalef32_pk_bf16_fp4 v52, v84, 1.0
	v_cvt_scalef32_pk_bf16_fp4 v54, v84, 1.0 op_sel:[1,0,0]
	v_cvt_scalef32_pk_bf16_fp4 v56, v84, 1.0 op_sel:[0,1,0]
	v_cvt_scalef32_pk_bf16_fp4 v58, v84, 1.0 op_sel:[1,1,0]
	v_dot2_f32_bf16 v60, v52, v6, 0
	v_dot2_f32_bf16 v52, v54, v4, 0
	v_dot2_f32_bf16 v60, v56, v10, v60
	s_add_i32 s12, s28, -10
	v_dot2_f32_bf16 v52, v58, v8, v52
	v_cvt_scalef32_pk_bf16_fp4 v54, v85, 1.0
	v_cvt_scalef32_pk_bf16_fp4 v56, v85, 1.0 op_sel:[1,0,0]
	v_cvt_scalef32_pk_bf16_fp4 v58, v85, 1.0 op_sel:[0,1,0]
	v_cvt_scalef32_pk_bf16_fp4 v62, v85, 1.0 op_sel:[1,1,0]
	v_readlane_b32 s12, v46, s12
	v_dot2_f32_bf16 v60, v54, v14, v60
	v_dot2_f32_bf16 v52, v56, v12, v52
	s_lshr_b32 s12, s12, 7
	v_dot2_f32_bf16 v60, v58, v18, v60
	v_dot2_f32_bf16 v52, v62, v16, v52
	v_cvt_scalef32_pk_bf16_fp4 v54, v86, 1.0
	v_cvt_scalef32_pk_bf16_fp4 v56, v86, 1.0 op_sel:[1,0,0]
	v_cvt_scalef32_pk_bf16_fp4 v58, v86, 1.0 op_sel:[0,1,0]
	v_cvt_scalef32_pk_bf16_fp4 v62, v86, 1.0 op_sel:[1,1,0]
	s_mov_b32 s13, s86
	v_dot2_f32_bf16 v60, v54, v22, v60
	v_dot2_f32_bf16 v52, v56, v20, v52
	s_lshl_b64 s[12:13], s[12:13], 10
	v_dot2_f32_bf16 v60, v58, v26, v60
	v_dot2_f32_bf16 v52, v62, v24, v52
	v_cvt_scalef32_pk_bf16_fp4 v54, v87, 1.0
	v_cvt_scalef32_pk_bf16_fp4 v56, v87, 1.0 op_sel:[1,0,0]
	v_cvt_scalef32_pk_bf16_fp4 v58, v87, 1.0 op_sel:[0,1,0]
	v_cvt_scalef32_pk_bf16_fp4 v62, v87, 1.0 op_sel:[1,1,0]
	s_nop 0
	v_dot2_f32_bf16 v60, v54, v30, v60
	v_dot2_f32_bf16 v52, v56, v28, v52
	s_nop 0
	v_dot2_f32_bf16 v60, v58, v36, v60
	v_dot2_f32_bf16 v52, v62, v34, v52
	s_nop 2
	v_add_f32_e32 v52, v60, v52
	v_lshl_add_u64 v[54:55], v[40:41], 0, s[12:13]
	global_load_dwordx4 v[84:87], v[54:55], off
	s_waitcnt vmcnt(15)
; #define P4_FOR16(M) M(0) M(1) M(2) M(3) M(4) M(5) M(6) M(7) M(8) M(9) M(10) M(11) M(12) M(13) M(14) M(15)
; #define P4_U(i) { P4_DOT(b##i, part[i]); const int nk_ = __builtin_amdgcn_readlane(ksel, nb + i); P4_LOAD(b##i, Ug, nk_); }
; #define P4_U(i) { P4_DOT(b##i, part[i]); const int nk_ = __builtin_amdgcn_readlane(kn, i); P4_LOAD(b##i, nbase, nk_); }
; __device__ __forceinline__ void peer_gather_f4p(const float* X, const int* __restrict__ IDX, const float* __restrict__ G, ...
;     ...
;         for (int bt = 0; bt < 7; ++bt) {
;             const int ksel = (bt + 1 < 4) ? k0 : k1;
;             const int nb = (16 * (bt + 1)) & 63;
;     ...
;             P4_FOR16(P4_U)
;     ...
;             P4_RED(bt);
	v_cvt_scalef32_pk_bf16_fp4 v54, v88, 1.0
	v_cvt_scalef32_pk_bf16_fp4 v56, v88, 1.0 op_sel:[1,0,0]
	v_cvt_scalef32_pk_bf16_fp4 v58, v88, 1.0 op_sel:[0,1,0]
	v_cvt_scalef32_pk_bf16_fp4 v60, v88, 1.0 op_sel:[1,1,0]
	s_add_i32 s12, s28, -9
	v_dot2_f32_bf16 v62, v54, v6, 0
	v_dot2_f32_bf16 v54, v56, v4, 0
	v_dot2_f32_bf16 v62, v58, v10, v62
	v_readlane_b32 s12, v46, s12
	v_dot2_f32_bf16 v54, v60, v8, v54
	v_cvt_scalef32_pk_bf16_fp4 v56, v89, 1.0
	v_cvt_scalef32_pk_bf16_fp4 v58, v89, 1.0 op_sel:[1,0,0]
	v_cvt_scalef32_pk_bf16_fp4 v60, v89, 1.0 op_sel:[0,1,0]
	v_cvt_scalef32_pk_bf16_fp4 v88, v89, 1.0 op_sel:[1,1,0]
	s_lshr_b32 s12, s12, 7
	v_dot2_f32_bf16 v62, v56, v14, v62
	v_dot2_f32_bf16 v54, v58, v12, v54
	s_mov_b32 s13, s86
	v_dot2_f32_bf16 v62, v60, v18, v62
	v_dot2_f32_bf16 v54, v88, v16, v54
	v_cvt_scalef32_pk_bf16_fp4 v56, v90, 1.0
	v_cvt_scalef32_pk_bf16_fp4 v58, v90, 1.0 op_sel:[1,0,0]
	v_cvt_scalef32_pk_bf16_fp4 v60, v90, 1.0 op_sel:[0,1,0]
	v_cvt_scalef32_pk_bf16_fp4 v88, v90, 1.0 op_sel:[1,1,0]
	s_lshl_b64 s[12:13], s[12:13], 10
	v_dot2_f32_bf16 v62, v56, v22, v62
	v_dot2_f32_bf16 v54, v58, v20, v54
	s_nop 0
	v_dot2_f32_bf16 v62, v60, v26, v62
	v_dot2_f32_bf16 v54, v88, v24, v54
	v_cvt_scalef32_pk_bf16_fp4 v56, v91, 1.0
	v_cvt_scalef32_pk_bf16_fp4 v58, v91, 1.0 op_sel:[1,0,0]
	v_cvt_scalef32_pk_bf16_fp4 v60, v91, 1.0 op_sel:[0,1,0]
	v_cvt_scalef32_pk_bf16_fp4 v88, v91, 1.0 op_sel:[1,1,0]
	s_nop 0
	v_dot2_f32_bf16 v62, v56, v30, v62
	v_dot2_f32_bf16 v54, v58, v28, v54
	s_nop 0
	v_dot2_f32_bf16 v62, v60, v36, v62
	v_dot2_f32_bf16 v54, v88, v34, v54
	s_nop 0
	s_nop 2
	v_add_f32_e32 v53, v62, v54
	v_lshl_add_u64 v[54:55], v[40:41], 0, s[12:13]
	global_load_dwordx4 v[88:91], v[54:55], off
	s_waitcnt vmcnt(15)
	v_cvt_scalef32_pk_bf16_fp4 v54, v92, 1.0
	v_cvt_scalef32_pk_bf16_fp4 v56, v92, 1.0 op_sel:[1,0,0]
	v_cvt_scalef32_pk_bf16_fp4 v58, v92, 1.0 op_sel:[0,1,0]
	v_cvt_scalef32_pk_bf16_fp4 v60, v92, 1.0 op_sel:[1,1,0]
	v_dot2_f32_bf16 v62, v54, v6, 0
	v_dot2_f32_bf16 v54, v56, v4, 0
	v_dot2_f32_bf16 v62, v58, v10, v62
	s_add_i32 s12, s28, -8
	v_dot2_f32_bf16 v54, v60, v8, v54
	v_cvt_scalef32_pk_bf16_fp4 v56, v93, 1.0
	v_cvt_scalef32_pk_bf16_fp4 v58, v93, 1.0 op_sel:[1,0,0]
	v_cvt_scalef32_pk_bf16_fp4 v60, v93, 1.0 op_sel:[0,1,0]
	v_cvt_scalef32_pk_bf16_fp4 v92, v93, 1.0 op_sel:[1,1,0]
	v_readlane_b32 s12, v46, s12
	v_dot2_f32_bf16 v62, v56, v14, v62
	v_dot2_f32_bf16 v54, v58, v12, v54
	s_lshr_b32 s12, s12, 7
	v_dot2_f32_bf16 v62, v60, v18, v62
	v_dot2_f32_bf16 v54, v92, v16, v54
	v_cvt_scalef32_pk_bf16_fp4 v56, v94, 1.0
	v_cvt_scalef32_pk_bf16_fp4 v58, v94, 1.0 op_sel:[1,0,0]
	v_cvt_scalef32_pk_bf16_fp4 v60, v94, 1.0 op_sel:[0,1,0]
	v_cvt_scalef32_pk_bf16_fp4 v92, v94, 1.0 op_sel:[1,1,0]
	s_mov_b32 s13, s86
	v_dot2_f32_bf16 v62, v56, v22, v62
	v_dot2_f32_bf16 v54, v58, v20, v54
	s_lshl_b64 s[12:13], s[12:13], 10
	v_dot2_f32_bf16 v62, v60, v26, v62
	v_dot2_f32_bf16 v54, v92, v24, v54
	v_cvt_scalef32_pk_bf16_fp4 v56, v95, 1.0
	v_cvt_scalef32_pk_bf16_fp4 v58, v95, 1.0 op_sel:[1,0,0]
	v_cvt_scalef32_pk_bf16_fp4 v60, v95, 1.0 op_sel:[0,1,0]
	v_cvt_scalef32_pk_bf16_fp4 v92, v95, 1.0 op_sel:[1,1,0]
	s_nop 0
	v_dot2_f32_bf16 v62, v56, v30, v62
	v_dot2_f32_bf16 v54, v58, v28, v54
	s_nop 0
	v_dot2_f32_bf16 v62, v60, v36, v62
	v_dot2_f32_bf16 v54, v92, v34, v54
	s_nop 0
	s_nop 2
	v_add_f32_e32 v54, v62, v54
	v_lshl_add_u64 v[56:57], v[40:41], 0, s[12:13]
	global_load_dwordx4 v[92:95], v[56:57], off
	s_waitcnt vmcnt(15)
	v_cvt_scalef32_pk_bf16_fp4 v56, v96, 1.0
	v_cvt_scalef32_pk_bf16_fp4 v58, v96, 1.0 op_sel:[1,0,0]
	v_cvt_scalef32_pk_bf16_fp4 v60, v96, 1.0 op_sel:[0,1,0]
	v_cvt_scalef32_pk_bf16_fp4 v62, v96, 1.0 op_sel:[1,1,0]
	s_add_i32 s12, s28, -7
	v_dot2c_f32_bf16_e32 v100, v56, v6
	v_dot2_f32_bf16 v56, v58, v4, 0
	v_dot2c_f32_bf16_e32 v100, v60, v10
	v_readlane_b32 s12, v46, s12
	v_dot2_f32_bf16 v56, v62, v8, v56
	v_cvt_scalef32_pk_bf16_fp4 v58, v97, 1.0
	v_cvt_scalef32_pk_bf16_fp4 v60, v97, 1.0 op_sel:[1,0,0]
	v_cvt_scalef32_pk_bf16_fp4 v62, v97, 1.0 op_sel:[0,1,0]
	v_cvt_scalef32_pk_bf16_fp4 v96, v97, 1.0 op_sel:[1,1,0]
	s_lshr_b32 s12, s12, 7
	v_dot2c_f32_bf16_e32 v100, v58, v14
	v_dot2_f32_bf16 v56, v60, v12, v56
	s_mov_b32 s13, s86
	v_dot2c_f32_bf16_e32 v100, v62, v18
	v_dot2_f32_bf16 v56, v96, v16, v56
	v_cvt_scalef32_pk_bf16_fp4 v58, v98, 1.0
	v_cvt_scalef32_pk_bf16_fp4 v60, v98, 1.0 op_sel:[1,0,0]
	v_cvt_scalef32_pk_bf16_fp4 v62, v98, 1.0 op_sel:[0,1,0]
	v_cvt_scalef32_pk_bf16_fp4 v96, v98, 1.0 op_sel:[1,1,0]
	s_lshl_b64 s[12:13], s[12:13], 10
	v_dot2c_f32_bf16_e32 v100, v58, v22
	v_dot2_f32_bf16 v56, v60, v20, v56
	s_nop 0
	v_dot2c_f32_bf16_e32 v100, v62, v26
	v_dot2_f32_bf16 v56, v96, v24, v56
	v_cvt_scalef32_pk_bf16_fp4 v58, v99, 1.0
	v_cvt_scalef32_pk_bf16_fp4 v60, v99, 1.0 op_sel:[1,0,0]
	v_cvt_scalef32_pk_bf16_fp4 v62, v99, 1.0 op_sel:[0,1,0]
	v_cvt_scalef32_pk_bf16_fp4 v96, v99, 1.0 op_sel:[1,1,0]
	s_nop 0
	v_dot2c_f32_bf16_e32 v100, v58, v30
	v_dot2_f32_bf16 v56, v60, v28, v56
	s_nop 0
	v_dot2c_f32_bf16_e32 v100, v62, v36
	v_dot2_f32_bf16 v56, v96, v34, v56
	s_nop 0
	s_nop 2
	v_add_f32_e32 v55, v100, v56
	v_lshl_add_u64 v[56:57], v[40:41], 0, s[12:13]
	global_load_dwordx4 v[96:99], v[56:57], off
	s_waitcnt vmcnt(15)
; #define P4_FOR16(M) M(0) M(1) M(2) M(3) M(4) M(5) M(6) M(7) M(8) M(9) M(10) M(11) M(12) M(13) M(14) M(15)
; #define P4_U(i) { P4_DOT(b##i, part[i]); const int nk_ = __builtin_amdgcn_readlane(ksel, nb + i); P4_LOAD(b##i, Ug, nk_); }
; #define P4_U(i) { P4_DOT(b##i, part[i]); const int nk_ = __builtin_amdgcn_readlane(kn, i); P4_LOAD(b##i, nbase, nk_); }
; __device__ __forceinline__ void peer_gather_f4p(const float* X, const int* __restrict__ IDX, const float* __restrict__ G, ...
;     ...
; #pragma unroll 1
;         for (int bt = 0; bt < 7; ++bt) {
;             const int ksel = (bt + 1 < 4) ? k0 : k1;
;             const int nb = (16 * (bt + 1)) & 63;
;     ...
;             P4_FOR16(P4_U)
;     ...
;             P4_RED(bt);
	v_cvt_scalef32_pk_bf16_fp4 v56, v104, 1.0
	v_cvt_scalef32_pk_bf16_fp4 v58, v104, 1.0 op_sel:[1,0,0]
	v_cvt_scalef32_pk_bf16_fp4 v60, v104, 1.0 op_sel:[0,1,0]
	v_cvt_scalef32_pk_bf16_fp4 v62, v104, 1.0 op_sel:[1,1,0]
	v_dot2_f32_bf16 v100, v56, v6, 0
	v_dot2_f32_bf16 v56, v58, v4, 0
	v_dot2_f32_bf16 v100, v60, v10, v100
	s_add_i32 s12, s28, -6
	v_dot2_f32_bf16 v56, v62, v8, v56
	v_cvt_scalef32_pk_bf16_fp4 v58, v105, 1.0
	v_cvt_scalef32_pk_bf16_fp4 v60, v105, 1.0 op_sel:[1,0,0]
	v_cvt_scalef32_pk_bf16_fp4 v62, v105, 1.0 op_sel:[0,1,0]
	v_cvt_scalef32_pk_bf16_fp4 v102, v105, 1.0 op_sel:[1,1,0]
	v_readlane_b32 s12, v46, s12
	v_dot2_f32_bf16 v100, v58, v14, v100
	v_dot2_f32_bf16 v56, v60, v12, v56
	s_lshr_b32 s12, s12, 7
	v_dot2_f32_bf16 v100, v62, v18, v100
	v_dot2_f32_bf16 v56, v102, v16, v56
	v_cvt_scalef32_pk_bf16_fp4 v58, v106, 1.0
	v_cvt_scalef32_pk_bf16_fp4 v60, v106, 1.0 op_sel:[1,0,0]
	v_cvt_scalef32_pk_bf16_fp4 v62, v106, 1.0 op_sel:[0,1,0]
	v_cvt_scalef32_pk_bf16_fp4 v102, v106, 1.0 op_sel:[1,1,0]
	s_mov_b32 s13, s86
	v_dot2_f32_bf16 v100, v58, v22, v100
	v_dot2_f32_bf16 v56, v60, v20, v56
	s_lshl_b64 s[12:13], s[12:13], 10
	v_dot2_f32_bf16 v100, v62, v26, v100
	v_dot2_f32_bf16 v56, v102, v24, v56
	v_cvt_scalef32_pk_bf16_fp4 v58, v107, 1.0
	v_cvt_scalef32_pk_bf16_fp4 v60, v107, 1.0 op_sel:[1,0,0]
	v_cvt_scalef32_pk_bf16_fp4 v62, v107, 1.0 op_sel:[0,1,0]
	v_cvt_scalef32_pk_bf16_fp4 v102, v107, 1.0 op_sel:[1,1,0]
	s_nop 0
	v_dot2_f32_bf16 v100, v58, v30, v100
	v_dot2_f32_bf16 v56, v60, v28, v56
	s_nop 0
	v_dot2_f32_bf16 v100, v62, v36, v100
	v_dot2_f32_bf16 v56, v102, v34, v56
	s_nop 2
	v_add_f32_e32 v56, v100, v56
	v_lshl_add_u64 v[58:59], v[40:41], 0, s[12:13]
	global_load_dwordx4 v[104:107], v[58:59], off
	s_waitcnt vmcnt(15)
	v_cvt_scalef32_pk_bf16_fp4 v58, v108, 1.0
	v_cvt_scalef32_pk_bf16_fp4 v60, v108, 1.0 op_sel:[1,0,0]
	v_cvt_scalef32_pk_bf16_fp4 v62, v108, 1.0 op_sel:[0,1,0]
	v_cvt_scalef32_pk_bf16_fp4 v100, v108, 1.0 op_sel:[1,1,0]
	s_add_i32 s12, s28, -5
	v_dot2_f32_bf16 v102, v58, v6, 0
	v_dot2_f32_bf16 v58, v60, v4, 0
	v_dot2_f32_bf16 v102, v62, v10, v102
	v_readlane_b32 s12, v46, s12
	v_dot2_f32_bf16 v58, v100, v8, v58
	v_cvt_scalef32_pk_bf16_fp4 v60, v109, 1.0
	v_cvt_scalef32_pk_bf16_fp4 v62, v109, 1.0 op_sel:[1,0,0]
	v_cvt_scalef32_pk_bf16_fp4 v100, v109, 1.0 op_sel:[0,1,0]
	v_cvt_scalef32_pk_bf16_fp4 v108, v109, 1.0 op_sel:[1,1,0]
	s_lshr_b32 s12, s12, 7
	v_dot2_f32_bf16 v102, v60, v14, v102
	v_dot2_f32_bf16 v58, v62, v12, v58
	s_mov_b32 s13, s86
	v_dot2_f32_bf16 v102, v100, v18, v102
	v_dot2_f32_bf16 v58, v108, v16, v58
	v_cvt_scalef32_pk_bf16_fp4 v60, v110, 1.0
	v_cvt_scalef32_pk_bf16_fp4 v62, v110, 1.0 op_sel:[1,0,0]
	v_cvt_scalef32_pk_bf16_fp4 v100, v110, 1.0 op_sel:[0,1,0]
	v_cvt_scalef32_pk_bf16_fp4 v108, v110, 1.0 op_sel:[1,1,0]
	s_lshl_b64 s[12:13], s[12:13], 10
	v_dot2_f32_bf16 v102, v60, v22, v102
	v_dot2_f32_bf16 v58, v62, v20, v58
	s_nop 0
	v_dot2_f32_bf16 v102, v100, v26, v102
	v_dot2_f32_bf16 v58, v108, v24, v58
	v_cvt_scalef32_pk_bf16_fp4 v60, v111, 1.0
	v_cvt_scalef32_pk_bf16_fp4 v62, v111, 1.0 op_sel:[1,0,0]
	v_cvt_scalef32_pk_bf16_fp4 v100, v111, 1.0 op_sel:[0,1,0]
	v_cvt_scalef32_pk_bf16_fp4 v108, v111, 1.0 op_sel:[1,1,0]
	s_nop 0
	v_dot2_f32_bf16 v102, v60, v30, v102
	v_dot2_f32_bf16 v58, v62, v28, v58
	s_nop 0
	v_dot2_f32_bf16 v102, v100, v36, v102
	v_dot2_f32_bf16 v58, v108, v34, v58
	s_nop 0
	s_nop 2
	v_add_f32_e32 v57, v102, v58
	v_lshl_add_u64 v[58:59], v[40:41], 0, s[12:13]
	global_load_dwordx4 v[108:111], v[58:59], off
	s_waitcnt vmcnt(15)
	v_cvt_scalef32_pk_bf16_fp4 v58, v112, 1.0
	v_cvt_scalef32_pk_bf16_fp4 v60, v112, 1.0 op_sel:[1,0,0]
	v_cvt_scalef32_pk_bf16_fp4 v62, v112, 1.0 op_sel:[0,1,0]
	v_cvt_scalef32_pk_bf16_fp4 v100, v112, 1.0 op_sel:[1,1,0]
	v_dot2_f32_bf16 v102, v58, v6, 0
	v_dot2_f32_bf16 v58, v60, v4, 0
	v_dot2_f32_bf16 v102, v62, v10, v102
	s_add_i32 s12, s28, -4
	v_dot2_f32_bf16 v58, v100, v8, v58
	v_cvt_scalef32_pk_bf16_fp4 v60, v113, 1.0
	v_cvt_scalef32_pk_bf16_fp4 v62, v113, 1.0 op_sel:[1,0,0]
	v_cvt_scalef32_pk_bf16_fp4 v100, v113, 1.0 op_sel:[0,1,0]
	v_cvt_scalef32_pk_bf16_fp4 v112, v113, 1.0 op_sel:[1,1,0]
	v_readlane_b32 s12, v46, s12
	v_dot2_f32_bf16 v102, v60, v14, v102
	v_dot2_f32_bf16 v58, v62, v12, v58
	s_lshr_b32 s12, s12, 7
	v_dot2_f32_bf16 v102, v100, v18, v102
	v_dot2_f32_bf16 v58, v112, v16, v58
	v_cvt_scalef32_pk_bf16_fp4 v60, v114, 1.0
	v_cvt_scalef32_pk_bf16_fp4 v62, v114, 1.0 op_sel:[1,0,0]
	v_cvt_scalef32_pk_bf16_fp4 v100, v114, 1.0 op_sel:[0,1,0]
	v_cvt_scalef32_pk_bf16_fp4 v112, v114, 1.0 op_sel:[1,1,0]
	s_mov_b32 s13, s86
	v_dot2_f32_bf16 v102, v60, v22, v102
	v_dot2_f32_bf16 v58, v62, v20, v58
	s_lshl_b64 s[12:13], s[12:13], 10
	v_dot2_f32_bf16 v102, v100, v26, v102
	v_dot2_f32_bf16 v58, v112, v24, v58
	v_cvt_scalef32_pk_bf16_fp4 v60, v115, 1.0
	v_cvt_scalef32_pk_bf16_fp4 v62, v115, 1.0 op_sel:[1,0,0]
	v_cvt_scalef32_pk_bf16_fp4 v100, v115, 1.0 op_sel:[0,1,0]
	v_cvt_scalef32_pk_bf16_fp4 v112, v115, 1.0 op_sel:[1,1,0]
	s_nop 0
	v_dot2_f32_bf16 v102, v60, v30, v102
	v_dot2_f32_bf16 v58, v62, v28, v58
	s_nop 0
	v_dot2_f32_bf16 v102, v100, v36, v102
	v_dot2_f32_bf16 v58, v112, v34, v58
	s_nop 0
	s_nop 2
	v_add_f32_e32 v132, v102, v58
	v_lshl_add_u64 v[58:59], v[40:41], 0, s[12:13]
	global_load_dwordx4 v[112:115], v[58:59], off
	s_waitcnt vmcnt(15)
; #define P4_FOR16(M) M(0) M(1) M(2) M(3) M(4) M(5) M(6) M(7) M(8) M(9) M(10) M(11) M(12) M(13) M(14) M(15)
; #define P4_U(i) { P4_DOT(b##i, part[i]); const int nk_ = __builtin_amdgcn_readlane(ksel, nb + i); P4_LOAD(b##i, Ug, nk_); }
; #define P4_U(i) { P4_DOT(b##i, part[i]); const int nk_ = __builtin_amdgcn_readlane(kn, i); P4_LOAD(b##i, nbase, nk_); }
; __device__ __forceinline__ void peer_gather_f4p(const float* X, const int* __restrict__ IDX, const float* __restrict__ G, ...
;     ...
; #pragma unroll 1
;         for (int bt = 0; bt < 7; ++bt) {
;             const int ksel = (bt + 1 < 4) ? k0 : k1;
;             const int nb = (16 * (bt + 1)) & 63;
;     ...
;             P4_FOR16(P4_U)
;     ...
;             P4_RED(bt);
	v_cvt_scalef32_pk_bf16_fp4 v58, v116, 1.0
	v_cvt_scalef32_pk_bf16_fp4 v60, v116, 1.0 op_sel:[1,0,0]
	v_cvt_scalef32_pk_bf16_fp4 v62, v116, 1.0 op_sel:[0,1,0]
	v_cvt_scalef32_pk_bf16_fp4 v100, v116, 1.0 op_sel:[1,1,0]
	v_dot2_f32_bf16 v102, v58, v6, 0
	v_dot2_f32_bf16 v58, v60, v4, 0
	v_dot2_f32_bf16 v102, v62, v10, v102
	s_add_i32 s12, s28, -3
	v_dot2_f32_bf16 v58, v100, v8, v58
	v_cvt_scalef32_pk_bf16_fp4 v60, v117, 1.0
	v_cvt_scalef32_pk_bf16_fp4 v62, v117, 1.0 op_sel:[1,0,0]
	v_cvt_scalef32_pk_bf16_fp4 v100, v117, 1.0 op_sel:[0,1,0]
	v_cvt_scalef32_pk_bf16_fp4 v116, v117, 1.0 op_sel:[1,1,0]
	v_readlane_b32 s12, v46, s12
	v_dot2_f32_bf16 v102, v60, v14, v102
	v_dot2_f32_bf16 v58, v62, v12, v58
	s_lshr_b32 s12, s12, 7
	v_dot2_f32_bf16 v102, v100, v18, v102
	v_dot2_f32_bf16 v58, v116, v16, v58
	v_cvt_scalef32_pk_bf16_fp4 v60, v118, 1.0
	v_cvt_scalef32_pk_bf16_fp4 v62, v118, 1.0 op_sel:[1,0,0]
	v_cvt_scalef32_pk_bf16_fp4 v100, v118, 1.0 op_sel:[0,1,0]
	v_cvt_scalef32_pk_bf16_fp4 v116, v118, 1.0 op_sel:[1,1,0]
	s_mov_b32 s13, s86
	v_dot2_f32_bf16 v102, v60, v22, v102
	v_dot2_f32_bf16 v58, v62, v20, v58
	s_lshl_b64 s[12:13], s[12:13], 10
	v_dot2_f32_bf16 v102, v100, v26, v102
	v_dot2_f32_bf16 v58, v116, v24, v58
	v_cvt_scalef32_pk_bf16_fp4 v60, v119, 1.0
	v_cvt_scalef32_pk_bf16_fp4 v62, v119, 1.0 op_sel:[1,0,0]
	v_cvt_scalef32_pk_bf16_fp4 v100, v119, 1.0 op_sel:[0,1,0]
	v_cvt_scalef32_pk_bf16_fp4 v116, v119, 1.0 op_sel:[1,1,0]
	s_nop 0
	v_dot2_f32_bf16 v102, v60, v30, v102
	v_dot2_f32_bf16 v58, v62, v28, v58
	s_nop 0
	v_dot2_f32_bf16 v102, v100, v36, v102
	v_dot2_f32_bf16 v58, v116, v34, v58
	s_nop 0
	s_nop 2
	v_add_f32_e32 v133, v102, v58
	v_lshl_add_u64 v[58:59], v[40:41], 0, s[12:13]
	global_load_dwordx4 v[116:119], v[58:59], off
	s_waitcnt vmcnt(15)
	v_cvt_scalef32_pk_bf16_fp4 v58, v120, 1.0
	v_cvt_scalef32_pk_bf16_fp4 v60, v120, 1.0 op_sel:[1,0,0]
	v_cvt_scalef32_pk_bf16_fp4 v62, v120, 1.0 op_sel:[0,1,0]
	v_cvt_scalef32_pk_bf16_fp4 v100, v120, 1.0 op_sel:[1,1,0]
	v_dot2_f32_bf16 v102, v58, v6, 0
	v_dot2_f32_bf16 v58, v60, v4, 0
	v_dot2_f32_bf16 v102, v62, v10, v102
	s_add_i32 s12, s28, -2
	v_dot2_f32_bf16 v58, v100, v8, v58
	v_cvt_scalef32_pk_bf16_fp4 v60, v121, 1.0
	v_cvt_scalef32_pk_bf16_fp4 v62, v121, 1.0 op_sel:[1,0,0]
	v_cvt_scalef32_pk_bf16_fp4 v100, v121, 1.0 op_sel:[0,1,0]
	v_cvt_scalef32_pk_bf16_fp4 v120, v121, 1.0 op_sel:[1,1,0]
	v_readlane_b32 s12, v46, s12
	v_dot2_f32_bf16 v102, v60, v14, v102
	v_dot2_f32_bf16 v58, v62, v12, v58
	s_lshr_b32 s12, s12, 7
	v_dot2_f32_bf16 v102, v100, v18, v102
	v_dot2_f32_bf16 v58, v120, v16, v58
	v_cvt_scalef32_pk_bf16_fp4 v60, v122, 1.0
	v_cvt_scalef32_pk_bf16_fp4 v62, v122, 1.0 op_sel:[1,0,0]
	v_cvt_scalef32_pk_bf16_fp4 v100, v122, 1.0 op_sel:[0,1,0]
	v_cvt_scalef32_pk_bf16_fp4 v120, v122, 1.0 op_sel:[1,1,0]
	s_mov_b32 s13, s86
	v_dot2_f32_bf16 v102, v60, v22, v102
	v_dot2_f32_bf16 v58, v62, v20, v58
	s_lshl_b64 s[12:13], s[12:13], 10
	v_dot2_f32_bf16 v102, v100, v26, v102
	v_dot2_f32_bf16 v58, v120, v24, v58
	v_cvt_scalef32_pk_bf16_fp4 v60, v123, 1.0
	v_cvt_scalef32_pk_bf16_fp4 v62, v123, 1.0 op_sel:[1,0,0]
	v_cvt_scalef32_pk_bf16_fp4 v100, v123, 1.0 op_sel:[0,1,0]
	v_cvt_scalef32_pk_bf16_fp4 v120, v123, 1.0 op_sel:[1,1,0]
	s_nop 0
	v_dot2_f32_bf16 v102, v60, v30, v102
	v_dot2_f32_bf16 v58, v62, v28, v58
	s_nop 0
	v_dot2_f32_bf16 v102, v100, v36, v102
	v_dot2_f32_bf16 v58, v120, v34, v58
	s_nop 0
	s_nop 2
	v_add_f32_e32 v134, v102, v58
	v_lshl_add_u64 v[58:59], v[40:41], 0, s[12:13]
	global_load_dwordx4 v[120:123], v[58:59], off
	s_waitcnt vmcnt(15)
	v_cvt_scalef32_pk_bf16_fp4 v58, v124, 1.0
	v_cvt_scalef32_pk_bf16_fp4 v60, v124, 1.0 op_sel:[1,0,0]
	v_cvt_scalef32_pk_bf16_fp4 v62, v124, 1.0 op_sel:[0,1,0]
	v_cvt_scalef32_pk_bf16_fp4 v100, v124, 1.0 op_sel:[1,1,0]
	v_dot2_f32_bf16 v102, v58, v6, 0
	v_dot2_f32_bf16 v58, v60, v4, 0
	v_dot2_f32_bf16 v102, v62, v10, v102
	s_add_i32 s12, s28, -1
	v_dot2_f32_bf16 v58, v100, v8, v58
	v_cvt_scalef32_pk_bf16_fp4 v60, v125, 1.0
	v_cvt_scalef32_pk_bf16_fp4 v62, v125, 1.0 op_sel:[1,0,0]
	v_cvt_scalef32_pk_bf16_fp4 v100, v125, 1.0 op_sel:[0,1,0]
	v_cvt_scalef32_pk_bf16_fp4 v124, v125, 1.0 op_sel:[1,1,0]
	v_readlane_b32 s12, v46, s12
	v_dot2_f32_bf16 v102, v60, v14, v102
	v_dot2_f32_bf16 v58, v62, v12, v58
	s_lshr_b32 s12, s12, 7
	v_dot2_f32_bf16 v102, v100, v18, v102
	v_dot2_f32_bf16 v58, v124, v16, v58
	v_cvt_scalef32_pk_bf16_fp4 v60, v126, 1.0
	v_cvt_scalef32_pk_bf16_fp4 v62, v126, 1.0 op_sel:[1,0,0]
	v_cvt_scalef32_pk_bf16_fp4 v100, v126, 1.0 op_sel:[0,1,0]
	v_cvt_scalef32_pk_bf16_fp4 v124, v126, 1.0 op_sel:[1,1,0]
	s_mov_b32 s13, s86
	v_dot2_f32_bf16 v102, v60, v22, v102
	v_dot2_f32_bf16 v58, v62, v20, v58
	s_lshl_b64 s[12:13], s[12:13], 10
	v_dot2_f32_bf16 v102, v100, v26, v102
	v_dot2_f32_bf16 v58, v124, v24, v58
	v_cvt_scalef32_pk_bf16_fp4 v60, v127, 1.0
	v_cvt_scalef32_pk_bf16_fp4 v62, v127, 1.0 op_sel:[1,0,0]
	v_cvt_scalef32_pk_bf16_fp4 v100, v127, 1.0 op_sel:[0,1,0]
	v_cvt_scalef32_pk_bf16_fp4 v124, v127, 1.0 op_sel:[1,1,0]
	s_nop 0
	v_dot2_f32_bf16 v102, v60, v30, v102
	v_dot2_f32_bf16 v58, v62, v28, v58
	s_nop 0
	v_dot2_f32_bf16 v102, v100, v36, v102
	v_dot2_f32_bf16 v58, v124, v34, v58
	s_nop 0
	s_nop 2
	v_add_f32_e32 v135, v102, v58
	v_lshl_add_u64 v[58:59], v[40:41], 0, s[12:13]
	global_load_dwordx4 v[124:127], v[58:59], off
	s_waitcnt vmcnt(15)
; __device__ __forceinline__ float gelu_tanh(float h) {
;     return 0.5f * h * (1.f + tanhf(0.7978845608028654f * (h + 0.044715f * h * h * h)));
; }
	v_cvt_scalef32_pk_bf16_fp4 v58, v128, 1.0
	v_cvt_scalef32_pk_bf16_fp4 v60, v128, 1.0 op_sel:[1,0,0]
	v_cvt_scalef32_pk_bf16_fp4 v62, v128, 1.0 op_sel:[0,1,0]
	v_cvt_scalef32_pk_bf16_fp4 v100, v128, 1.0 op_sel:[1,1,0]
	v_readlane_b32 s12, v46, s28
	v_dot2_f32_bf16 v102, v58, v6, 0
	v_dot2c_f32_bf16_e32 v42, v60, v4
	s_lshr_b32 s12, s12, 7
	v_dot2_f32_bf16 v102, v62, v10, v102
	v_dot2c_f32_bf16_e32 v42, v100, v8
	v_cvt_scalef32_pk_bf16_fp4 v58, v129, 1.0
	v_cvt_scalef32_pk_bf16_fp4 v60, v129, 1.0 op_sel:[1,0,0]
	v_cvt_scalef32_pk_bf16_fp4 v62, v129, 1.0 op_sel:[0,1,0]
	v_cvt_scalef32_pk_bf16_fp4 v100, v129, 1.0 op_sel:[1,1,0]
	s_mov_b32 s13, s86
	v_dot2_f32_bf16 v102, v58, v14, v102
	v_dot2c_f32_bf16_e32 v42, v60, v12
	s_lshl_b64 s[12:13], s[12:13], 10
	v_dot2_f32_bf16 v102, v62, v18, v102
	v_dot2c_f32_bf16_e32 v42, v100, v16
	v_cvt_scalef32_pk_bf16_fp4 v58, v130, 1.0
	v_cvt_scalef32_pk_bf16_fp4 v60, v130, 1.0 op_sel:[1,0,0]
	v_cvt_scalef32_pk_bf16_fp4 v62, v130, 1.0 op_sel:[0,1,0]
	v_cvt_scalef32_pk_bf16_fp4 v100, v130, 1.0 op_sel:[1,1,0]
	v_cndmask_b32_e64 v46, v48, v56, s[48:49]
	v_dot2_f32_bf16 v102, v58, v22, v102
	v_dot2c_f32_bf16_e32 v42, v60, v20
	ds_swizzle_b32 v46, v46 offset:swizzle(SWAP,8)
	v_dot2_f32_bf16 v102, v62, v26, v102
	v_dot2c_f32_bf16_e32 v42, v100, v24
	v_cvt_scalef32_pk_bf16_fp4 v58, v131, 1.0
	v_cvt_scalef32_pk_bf16_fp4 v60, v131, 1.0 op_sel:[1,0,0]
	v_cvt_scalef32_pk_bf16_fp4 v62, v131, 1.0 op_sel:[0,1,0]
	v_cvt_scalef32_pk_bf16_fp4 v100, v131, 1.0 op_sel:[1,1,0]
	s_nop 0
	v_dot2_f32_bf16 v102, v58, v30, v102
	v_dot2c_f32_bf16_e32 v42, v60, v28
	s_nop 0
	v_dot2_f32_bf16 v102, v62, v36, v102
	v_dot2c_f32_bf16_e32 v42, v100, v34
	s_nop 0
	s_nop 2
	v_add_f32_e32 v58, v102, v42
	v_lshl_add_u64 v[42:43], v[40:41], 0, s[12:13]
	global_load_dwordx4 v[128:131], v[42:43], off
	v_cndmask_b32_e64 v43, v47, v55, s[48:49]
	ds_swizzle_b32 v43, v43 offset:swizzle(SWAP,8)
	v_cndmask_b32_e64 v42, v55, v47, s[48:49]
	v_cndmask_b32_e64 v47, v49, v57, s[48:49]
	ds_swizzle_b32 v47, v47 offset:swizzle(SWAP,8)
	s_waitcnt lgkmcnt(1)
	v_add_f32_e32 v42, v42, v43
	v_cndmask_b32_e64 v43, v56, v48, s[48:49]
	v_cndmask_b32_e64 v48, v50, v132, s[48:49]
	v_add_f32_e32 v43, v43, v46
	v_cndmask_b32_e64 v46, v57, v49, s[48:49]
	ds_swizzle_b32 v48, v48 offset:swizzle(SWAP,8)
	v_cndmask_b32_e64 v49, v51, v133, s[48:49]
	ds_swizzle_b32 v49, v49 offset:swizzle(SWAP,8)
	s_waitcnt lgkmcnt(2)
	v_add_f32_e32 v46, v46, v47
	v_cndmask_b32_e64 v47, v132, v50, s[48:49]
	v_cndmask_b32_e64 v50, v52, v134, s[48:49]
	ds_swizzle_b32 v50, v50 offset:swizzle(SWAP,8)
	s_waitcnt lgkmcnt(2)
	v_add_f32_e32 v47, v47, v48
	v_cndmask_b32_e64 v48, v133, v51, s[48:49]
	v_cndmask_b32_e64 v51, v53, v135, s[48:49]
	s_waitcnt lgkmcnt(1)
	v_add_f32_e32 v48, v48, v49
	v_cndmask_b32_e64 v49, v134, v52, s[48:49]
	ds_swizzle_b32 v51, v51 offset:swizzle(SWAP,8)
	v_cndmask_b32_e64 v52, v54, v58, s[48:49]
	ds_swizzle_b32 v52, v52 offset:swizzle(SWAP,8)
	s_waitcnt lgkmcnt(2)
	v_add_f32_e32 v49, v49, v50
	v_cndmask_b32_e64 v50, v135, v53, s[48:49]
	s_waitcnt lgkmcnt(1)
	v_add_f32_e32 v50, v50, v51
	v_cndmask_b32_e64 v51, v58, v54, s[48:49]
	s_waitcnt lgkmcnt(0)
	v_add_f32_e32 v51, v51, v52
	v_cndmask_b32_e64 v53, v42, v48, s[46:47]
	v_cndmask_b32_e64 v42, v48, v42, s[46:47]
	v_cndmask_b32_e64 v48, v49, v43, s[46:47]
	v_cndmask_b32_e64 v43, v43, v49, s[46:47]
	v_cndmask_b32_e64 v49, v46, v50, s[46:47]
	v_cndmask_b32_e64 v52, v47, v51, s[46:47]
	ds_swizzle_b32 v53, v53 offset:swizzle(SWAP,4)
	ds_swizzle_b32 v43, v43 offset:swizzle(SWAP,4)
	ds_swizzle_b32 v49, v49 offset:swizzle(SWAP,4)
	ds_swizzle_b32 v52, v52 offset:swizzle(SWAP,4)
	v_cndmask_b32_e64 v46, v50, v46, s[46:47]
	v_cndmask_b32_e64 v47, v51, v47, s[46:47]
	s_waitcnt lgkmcnt(3)
	v_add_f32_e32 v42, v42, v53
	s_waitcnt lgkmcnt(2)
	v_add_f32_e32 v43, v48, v43
	s_waitcnt lgkmcnt(1)
	v_add_f32_e32 v46, v46, v49
	s_waitcnt lgkmcnt(0)
	v_add_f32_e32 v47, v47, v52
	v_cndmask_b32_e64 v48, v42, v46, s[44:45]
	v_cndmask_b32_e64 v49, v43, v47, s[44:45]
	ds_swizzle_b32 v48, v48 offset:swizzle(SWAP,2)
	ds_swizzle_b32 v49, v49 offset:swizzle(SWAP,2)
	v_cndmask_b32_e64 v42, v46, v42, s[44:45]
	v_cndmask_b32_e64 v43, v47, v43, s[44:45]
	s_waitcnt lgkmcnt(1)
	v_add_f32_e32 v42, v42, v48
	s_waitcnt lgkmcnt(0)
	v_add_f32_e32 v43, v43, v49
	v_cndmask_b32_e64 v46, v42, v43, s[42:43]
	ds_swizzle_b32 v46, v46 offset:swizzle(SWAP,1)
	v_cndmask_b32_e64 v42, v43, v42, s[42:43]
	s_waitcnt lgkmcnt(0)
	v_add_f32_e32 v42, v42, v46
	ds_swizzle_b32 v43, v42 offset:swizzle(SWAP,16)
	s_waitcnt lgkmcnt(0)
	v_add_f32_e32 v46, v42, v43
	ds_read2st64_b32 v[42:43], v45 offset1:8
	v_mov_b32_e32 v47, v46
	s_nop 1
	v_permlane32_swap_b32_e32 v46, v47
	v_add_f32_e32 v46, v46, v47
	s_waitcnt lgkmcnt(0)
	v_mul_f32_e32 v42, v42, v46
	v_mul_f32_e32 v46, 0x3d372713, v42
	v_mul_f32_e32 v46, v42, v46
	v_fma_f32 v46, v42, v46, v42
	v_mul_f32_e32 v46, 0x3f4c422a, v46
	v_cmp_nlt_f32_e64 s[12:13], |v46|, s25
	s_and_saveexec_b64 s[40:41], s[12:13]
	s_xor_b64 s[12:13], exec, s[40:41]
	s_cbranch_execz .LBB0_536
	v_add_f32_e64 v47, |v46|, |v46|
	v_mul_f32_e32 v48, 0x3fb8aa3b, v47
	v_rndne_f32_e32 v49, v48
	v_sub_f32_e32 v50, v48, v49
	v_fma_f32 v48, v47, s70, -v48
	v_fmac_f32_e32 v48, 0x32a5705f, v47
	v_add_f32_e32 v48, v50, v48
	v_cvt_i32_f32_e32 v49, v49
	v_exp_f32_e32 v48, v48
	v_cmp_ngt_f32_e64 s[50:51], s67, v47
	v_ldexp_f32 v48, v48, v49
	s_nop 0
	v_cndmask_b32_e64 v48, 0, v48, s[50:51]
	v_cmp_nlt_f32_e64 s[50:51], s68, v47
	s_nop 1
	v_cndmask_b32_e64 v47, v205, v48, s[50:51]
	v_add_f32_e32 v47, 1.0, v47
	v_rcp_f32_e32 v47, v47
	s_nop 0
	v_fma_f32 v47, v47, -2.0, 1.0
	s_andn2_saveexec_b64 s[12:13], s[12:13]
	s_cbranch_execnz .LBB0_537

; #define GAS __attribute__((address_space(1)))
; #define P4_FOR16(M) M(0) M(1) M(2) M(3) M(4) M(5) M(6) M(7) M(8) M(9) M(10) M(11) M(12) M(13) M(14) M(15)
; #define P4_U(i) { P4_DOT(b##i, part[i]); const int nk_ = __builtin_amdgcn_readlane(ksel, nb + i); P4_LOAD(b##i, Ug, nk_); }
; #define P4_U(i) { P4_DOT(b##i, part[i]); const int nk_ = __builtin_amdgcn_readlane(kn, i); P4_LOAD(b##i, nbase, nk_); }
; __device__ __forceinline__ void peer_gather_f4p(const float* X, const int* __restrict__ IDX, const float* __restrict__ G, ...
;     ...
;         const int k0 = keys[kt * 128 + lane], k1 = keys[kt * 128 + 64 + lane];
;         const int kn = keys[((kt + 1) & 3) * 128 + lane];
;         const GAS unsigned char* nbase = (kt < 3) ? Ug : Vg;
;         float part[16];
;     ...
; #pragma unroll 1
;         for (int bt = 0; bt < 7; ++bt) {
;             const int ksel = (bt + 1 < 4) ? k0 : k1;
;             const int nb = (16 * (bt + 1)) & 63;
;     ...
;             P4_FOR16(P4_U)
;     ...
;             P4_RED(bt);
;         }
;         {
;     ...
;             P4_FOR16(P4_U)
.LBB0_539:
	s_mov_b32 s87, s86
	s_waitcnt vmcnt(15)
	v_cvt_scalef32_pk_bf16_fp4 v42, v64, 1.0
	v_or_b32_e32 v40, s27, v44
	v_cvt_scalef32_pk_bf16_fp4 v44, v64, 1.0 op_sel:[1,0,0]
	v_cvt_scalef32_pk_bf16_fp4 v46, v64, 1.0 op_sel:[0,1,0]
	v_cvt_scalef32_pk_bf16_fp4 v48, v64, 1.0 op_sel:[1,1,0]
	v_dot2_f32_bf16 v50, v42, v6, 0
	v_dot2_f32_bf16 v42, v44, v4, 0
	v_dot2_f32_bf16 v50, v46, v10, v50
	s_cmp_eq_u32 s26, 3
	v_dot2_f32_bf16 v42, v48, v8, v42
	v_cvt_scalef32_pk_bf16_fp4 v44, v65, 1.0
	v_cvt_scalef32_pk_bf16_fp4 v46, v65, 1.0 op_sel:[1,0,0]
	v_cvt_scalef32_pk_bf16_fp4 v48, v65, 1.0 op_sel:[0,1,0]
	v_cvt_scalef32_pk_bf16_fp4 v52, v65, 1.0 op_sel:[1,1,0]
	v_readlane_b32 s26, v2, 0
	v_dot2_f32_bf16 v50, v44, v14, v50
	v_dot2_f32_bf16 v42, v46, v12, v42
	s_cselect_b32 s12, s53, s55
	v_dot2_f32_bf16 v50, v48, v18, v50
	v_dot2_f32_bf16 v42, v52, v16, v42
	v_cvt_scalef32_pk_bf16_fp4 v44, v66, 1.0
	v_cvt_scalef32_pk_bf16_fp4 v46, v66, 1.0 op_sel:[1,0,0]
	v_cvt_scalef32_pk_bf16_fp4 v48, v66, 1.0 op_sel:[0,1,0]
	v_cvt_scalef32_pk_bf16_fp4 v52, v66, 1.0 op_sel:[1,1,0]
	s_cselect_b32 s13, s52, s54
	v_dot2_f32_bf16 v50, v44, v22, v50
	v_dot2_f32_bf16 v42, v46, v20, v42
	s_lshr_b32 s26, s26, 7
	v_dot2_f32_bf16 v50, v48, v26, v50
	v_dot2_f32_bf16 v42, v52, v24, v42
	s_mov_b32 s27, s86
	v_cvt_scalef32_pk_bf16_fp4 v44, v67, 1.0
	v_cvt_scalef32_pk_bf16_fp4 v46, v67, 1.0 op_sel:[1,0,0]
	v_cvt_scalef32_pk_bf16_fp4 v48, v67, 1.0 op_sel:[0,1,0]
	v_cvt_scalef32_pk_bf16_fp4 v52, v67, 1.0 op_sel:[1,1,0]
	s_lshl_b64 s[26:27], s[26:27], 10
	v_dot2_f32_bf16 v50, v44, v30, v50
	v_dot2_f32_bf16 v42, v46, v28, v42
	s_add_u32 s26, s13, s26
	v_dot2_f32_bf16 v50, v48, v36, v50
	v_dot2_f32_bf16 v42, v52, v34, v42
	s_addc_u32 s27, s12, s27
	s_nop 2
	v_add_f32_e32 v41, v50, v42
	v_lshl_add_u64 v[42:43], s[26:27], 0, v[32:33]
	global_load_dwordx4 v[64:67], v[42:43], off
	s_waitcnt vmcnt(15)
	v_cvt_scalef32_pk_bf16_fp4 v42, v68, 1.0
	v_cvt_scalef32_pk_bf16_fp4 v44, v68, 1.0 op_sel:[1,0,0]
	v_cvt_scalef32_pk_bf16_fp4 v46, v68, 1.0 op_sel:[0,1,0]
	v_cvt_scalef32_pk_bf16_fp4 v48, v68, 1.0 op_sel:[1,1,0]
	v_dot2_f32_bf16 v50, v42, v6, 0
	v_dot2_f32_bf16 v42, v44, v4, 0
	v_dot2_f32_bf16 v50, v46, v10, v50
	v_readlane_b32 s26, v2, 1
	v_dot2_f32_bf16 v42, v48, v8, v42
	v_cvt_scalef32_pk_bf16_fp4 v44, v69, 1.0
	v_cvt_scalef32_pk_bf16_fp4 v46, v69, 1.0 op_sel:[1,0,0]
	v_cvt_scalef32_pk_bf16_fp4 v48, v69, 1.0 op_sel:[0,1,0]
	v_cvt_scalef32_pk_bf16_fp4 v52, v69, 1.0 op_sel:[1,1,0]
	s_lshr_b32 s26, s26, 7
	v_dot2_f32_bf16 v50, v44, v14, v50
	v_dot2_f32_bf16 v42, v46, v12, v42
	s_mov_b32 s27, s86
	v_dot2_f32_bf16 v50, v48, v18, v50
	v_dot2_f32_bf16 v42, v52, v16, v42
	v_cvt_scalef32_pk_bf16_fp4 v44, v70, 1.0
	v_cvt_scalef32_pk_bf16_fp4 v46, v70, 1.0 op_sel:[1,0,0]
	v_cvt_scalef32_pk_bf16_fp4 v48, v70, 1.0 op_sel:[0,1,0]
	v_cvt_scalef32_pk_bf16_fp4 v52, v70, 1.0 op_sel:[1,1,0]
	s_lshl_b64 s[26:27], s[26:27], 10
	v_dot2_f32_bf16 v50, v44, v22, v50
	v_dot2_f32_bf16 v42, v46, v20, v42
	s_add_u32 s26, s13, s26
	v_dot2_f32_bf16 v50, v48, v26, v50
	v_dot2_f32_bf16 v42, v52, v24, v42
	v_cvt_scalef32_pk_bf16_fp4 v44, v71, 1.0
	v_cvt_scalef32_pk_bf16_fp4 v46, v71, 1.0 op_sel:[1,0,0]
	v_cvt_scalef32_pk_bf16_fp4 v48, v71, 1.0 op_sel:[0,1,0]
	v_cvt_scalef32_pk_bf16_fp4 v52, v71, 1.0 op_sel:[1,1,0]
	s_addc_u32 s27, s12, s27
	v_dot2_f32_bf16 v50, v44, v30, v50
	v_dot2_f32_bf16 v42, v46, v28, v42
	v_mov_b32_e32 v38, 0
	v_dot2_f32_bf16 v50, v48, v36, v50
	v_dot2_f32_bf16 v42, v52, v34, v42
	s_nop 2
	v_add_f32_e32 v42, v50, v42
	v_lshl_add_u64 v[44:45], s[26:27], 0, v[32:33]
	global_load_dwordx4 v[68:71], v[44:45], off
	s_waitcnt vmcnt(15)
	v_cvt_scalef32_pk_bf16_fp4 v44, v72, 1.0
	v_cvt_scalef32_pk_bf16_fp4 v46, v72, 1.0 op_sel:[1,0,0]
	v_cvt_scalef32_pk_bf16_fp4 v48, v72, 1.0 op_sel:[0,1,0]
	v_cvt_scalef32_pk_bf16_fp4 v50, v72, 1.0 op_sel:[1,1,0]
	v_readlane_b32 s26, v2, 2
	v_dot2_f32_bf16 v52, v44, v6, 0
	v_dot2_f32_bf16 v44, v46, v4, 0
	v_dot2_f32_bf16 v52, v48, v10, v52
	s_lshr_b32 s26, s26, 7
	v_dot2_f32_bf16 v44, v50, v8, v44
	v_cvt_scalef32_pk_bf16_fp4 v46, v73, 1.0
	v_cvt_scalef32_pk_bf16_fp4 v48, v73, 1.0 op_sel:[1,0,0]
	v_cvt_scalef32_pk_bf16_fp4 v50, v73, 1.0 op_sel:[0,1,0]
	v_cvt_scalef32_pk_bf16_fp4 v54, v73, 1.0 op_sel:[1,1,0]
	s_mov_b32 s27, s86
	v_dot2_f32_bf16 v52, v46, v14, v52
	v_dot2_f32_bf16 v44, v48, v12, v44
	s_lshl_b64 s[26:27], s[26:27], 10
	v_dot2_f32_bf16 v52, v50, v18, v52
	v_dot2_f32_bf16 v44, v54, v16, v44
	v_cvt_scalef32_pk_bf16_fp4 v46, v74, 1.0
	v_cvt_scalef32_pk_bf16_fp4 v48, v74, 1.0 op_sel:[1,0,0]
	v_cvt_scalef32_pk_bf16_fp4 v50, v74, 1.0 op_sel:[0,1,0]
	v_cvt_scalef32_pk_bf16_fp4 v54, v74, 1.0 op_sel:[1,1,0]
	s_add_u32 s26, s13, s26
	v_dot2_f32_bf16 v52, v46, v22, v52
	v_dot2_f32_bf16 v44, v48, v20, v44
	s_addc_u32 s27, s12, s27
	v_dot2_f32_bf16 v52, v50, v26, v52
	v_dot2_f32_bf16 v44, v54, v24, v44
	v_cvt_scalef32_pk_bf16_fp4 v46, v75, 1.0
	v_cvt_scalef32_pk_bf16_fp4 v48, v75, 1.0 op_sel:[1,0,0]
	v_cvt_scalef32_pk_bf16_fp4 v50, v75, 1.0 op_sel:[0,1,0]
	v_cvt_scalef32_pk_bf16_fp4 v54, v75, 1.0 op_sel:[1,1,0]
	s_nop 0
	v_dot2_f32_bf16 v52, v46, v30, v52
	v_dot2_f32_bf16 v44, v48, v28, v44
	s_nop 0
	v_dot2_f32_bf16 v52, v50, v36, v52
	v_dot2_f32_bf16 v44, v54, v34, v44
	s_nop 0
	s_nop 2
	v_add_f32_e32 v43, v52, v44
	v_lshl_add_u64 v[44:45], s[26:27], 0, v[32:33]
	global_load_dwordx4 v[72:75], v[44:45], off
	s_waitcnt vmcnt(15)
; #define P4_FOR16(M) M(0) M(1) M(2) M(3) M(4) M(5) M(6) M(7) M(8) M(9) M(10) M(11) M(12) M(13) M(14) M(15)
; #define P4_U(i) { P4_DOT(b##i, part[i]); const int nk_ = __builtin_amdgcn_readlane(ksel, nb + i); P4_LOAD(b##i, Ug, nk_); }
; #define P4_U(i) { P4_DOT(b##i, part[i]); const int nk_ = __builtin_amdgcn_readlane(kn, i); P4_LOAD(b##i, nbase, nk_); }
; __device__ __forceinline__ void peer_gather_f4p(const float* X, const int* __restrict__ IDX, const float* __restrict__ G, ...
;     ...
;         {
;     ...
;             P4_FOR16(P4_U)
	v_cvt_scalef32_pk_bf16_fp4 v44, v76, 1.0
	v_cvt_scalef32_pk_bf16_fp4 v46, v76, 1.0 op_sel:[1,0,0]
	v_cvt_scalef32_pk_bf16_fp4 v48, v76, 1.0 op_sel:[0,1,0]
	v_cvt_scalef32_pk_bf16_fp4 v50, v76, 1.0 op_sel:[1,1,0]
	v_dot2_f32_bf16 v52, v44, v6, 0
	v_dot2_f32_bf16 v44, v46, v4, 0
	v_dot2_f32_bf16 v52, v48, v10, v52
	v_readlane_b32 s26, v2, 3
	v_dot2_f32_bf16 v44, v50, v8, v44
	v_cvt_scalef32_pk_bf16_fp4 v46, v77, 1.0
	v_cvt_scalef32_pk_bf16_fp4 v48, v77, 1.0 op_sel:[1,0,0]
	v_cvt_scalef32_pk_bf16_fp4 v50, v77, 1.0 op_sel:[0,1,0]
	v_cvt_scalef32_pk_bf16_fp4 v54, v77, 1.0 op_sel:[1,1,0]
	s_lshr_b32 s26, s26, 7
	v_dot2_f32_bf16 v52, v46, v14, v52
	v_dot2_f32_bf16 v44, v48, v12, v44
	s_mov_b32 s27, s86
	v_dot2_f32_bf16 v52, v50, v18, v52
	v_dot2_f32_bf16 v44, v54, v16, v44
	v_cvt_scalef32_pk_bf16_fp4 v46, v78, 1.0
	v_cvt_scalef32_pk_bf16_fp4 v48, v78, 1.0 op_sel:[1,0,0]
	v_cvt_scalef32_pk_bf16_fp4 v50, v78, 1.0 op_sel:[0,1,0]
	v_cvt_scalef32_pk_bf16_fp4 v54, v78, 1.0 op_sel:[1,1,0]
	s_lshl_b64 s[26:27], s[26:27], 10
	v_dot2_f32_bf16 v52, v46, v22, v52
	v_dot2_f32_bf16 v44, v48, v20, v44
	s_add_u32 s26, s13, s26
	v_dot2_f32_bf16 v52, v50, v26, v52
	v_dot2_f32_bf16 v44, v54, v24, v44
	v_cvt_scalef32_pk_bf16_fp4 v46, v79, 1.0
	v_cvt_scalef32_pk_bf16_fp4 v48, v79, 1.0 op_sel:[1,0,0]
	v_cvt_scalef32_pk_bf16_fp4 v50, v79, 1.0 op_sel:[0,1,0]
	v_cvt_scalef32_pk_bf16_fp4 v54, v79, 1.0 op_sel:[1,1,0]
	s_addc_u32 s27, s12, s27
	v_dot2_f32_bf16 v52, v46, v30, v52
	v_dot2_f32_bf16 v44, v48, v28, v44
	s_nop 0
	v_dot2_f32_bf16 v52, v50, v36, v52
	v_dot2_f32_bf16 v44, v54, v34, v44
	s_nop 2
	v_add_f32_e32 v44, v52, v44
	v_lshl_add_u64 v[46:47], s[26:27], 0, v[32:33]
	global_load_dwordx4 v[76:79], v[46:47], off
	s_waitcnt vmcnt(15)
	v_cvt_scalef32_pk_bf16_fp4 v46, v80, 1.0
	v_cvt_scalef32_pk_bf16_fp4 v48, v80, 1.0 op_sel:[1,0,0]
	v_cvt_scalef32_pk_bf16_fp4 v50, v80, 1.0 op_sel:[0,1,0]
	v_cvt_scalef32_pk_bf16_fp4 v52, v80, 1.0 op_sel:[1,1,0]
	v_readlane_b32 s26, v2, 4
	v_dot2_f32_bf16 v54, v46, v6, 0
	v_dot2_f32_bf16 v46, v48, v4, 0
	v_dot2_f32_bf16 v54, v50, v10, v54
	s_lshr_b32 s26, s26, 7
	v_dot2_f32_bf16 v46, v52, v8, v46
	v_cvt_scalef32_pk_bf16_fp4 v48, v81, 1.0
	v_cvt_scalef32_pk_bf16_fp4 v50, v81, 1.0 op_sel:[1,0,0]
	v_cvt_scalef32_pk_bf16_fp4 v52, v81, 1.0 op_sel:[0,1,0]
	v_cvt_scalef32_pk_bf16_fp4 v56, v81, 1.0 op_sel:[1,1,0]
	s_mov_b32 s27, s86
	v_dot2_f32_bf16 v54, v48, v14, v54
	v_dot2_f32_bf16 v46, v50, v12, v46
	s_lshl_b64 s[26:27], s[26:27], 10
	v_dot2_f32_bf16 v54, v52, v18, v54
	v_dot2_f32_bf16 v46, v56, v16, v46
	v_cvt_scalef32_pk_bf16_fp4 v48, v82, 1.0
	v_cvt_scalef32_pk_bf16_fp4 v50, v82, 1.0 op_sel:[1,0,0]
	v_cvt_scalef32_pk_bf16_fp4 v52, v82, 1.0 op_sel:[0,1,0]
	v_cvt_scalef32_pk_bf16_fp4 v56, v82, 1.0 op_sel:[1,1,0]
	s_add_u32 s26, s13, s26
	v_dot2_f32_bf16 v54, v48, v22, v54
	v_dot2_f32_bf16 v46, v50, v20, v46
	s_addc_u32 s27, s12, s27
	v_dot2_f32_bf16 v54, v52, v26, v54
	v_dot2_f32_bf16 v46, v56, v24, v46
	v_cvt_scalef32_pk_bf16_fp4 v48, v83, 1.0
	v_cvt_scalef32_pk_bf16_fp4 v50, v83, 1.0 op_sel:[1,0,0]
	v_cvt_scalef32_pk_bf16_fp4 v52, v83, 1.0 op_sel:[0,1,0]
	v_cvt_scalef32_pk_bf16_fp4 v56, v83, 1.0 op_sel:[1,1,0]
	s_nop 0
	v_dot2_f32_bf16 v54, v48, v30, v54
	v_dot2_f32_bf16 v46, v50, v28, v46
	s_nop 0
	v_dot2_f32_bf16 v54, v52, v36, v54
	v_dot2_f32_bf16 v46, v56, v34, v46
	s_nop 0
	s_nop 2
	v_add_f32_e32 v45, v54, v46
	v_lshl_add_u64 v[46:47], s[26:27], 0, v[32:33]
	global_load_dwordx4 v[80:83], v[46:47], off
	s_waitcnt vmcnt(15)
	v_cvt_scalef32_pk_bf16_fp4 v46, v84, 1.0
	v_cvt_scalef32_pk_bf16_fp4 v48, v84, 1.0 op_sel:[1,0,0]
	v_cvt_scalef32_pk_bf16_fp4 v50, v84, 1.0 op_sel:[0,1,0]
	v_cvt_scalef32_pk_bf16_fp4 v52, v84, 1.0 op_sel:[1,1,0]
	v_dot2_f32_bf16 v54, v46, v6, 0
	v_dot2_f32_bf16 v46, v48, v4, 0
	v_dot2_f32_bf16 v54, v50, v10, v54
	v_readlane_b32 s26, v2, 5
	v_dot2_f32_bf16 v46, v52, v8, v46
	v_cvt_scalef32_pk_bf16_fp4 v48, v85, 1.0
	v_cvt_scalef32_pk_bf16_fp4 v50, v85, 1.0 op_sel:[1,0,0]
	v_cvt_scalef32_pk_bf16_fp4 v52, v85, 1.0 op_sel:[0,1,0]
	v_cvt_scalef32_pk_bf16_fp4 v56, v85, 1.0 op_sel:[1,1,0]
	s_lshr_b32 s26, s26, 7
	v_dot2_f32_bf16 v54, v48, v14, v54
	v_dot2_f32_bf16 v46, v50, v12, v46
	s_mov_b32 s27, s86
	v_dot2_f32_bf16 v54, v52, v18, v54
	v_dot2_f32_bf16 v46, v56, v16, v46
	v_cvt_scalef32_pk_bf16_fp4 v48, v86, 1.0
	v_cvt_scalef32_pk_bf16_fp4 v50, v86, 1.0 op_sel:[1,0,0]
	v_cvt_scalef32_pk_bf16_fp4 v52, v86, 1.0 op_sel:[0,1,0]
	v_cvt_scalef32_pk_bf16_fp4 v56, v86, 1.0 op_sel:[1,1,0]
	s_lshl_b64 s[26:27], s[26:27], 10
	v_dot2_f32_bf16 v54, v48, v22, v54
	v_dot2_f32_bf16 v46, v50, v20, v46
	s_add_u32 s26, s13, s26
	v_dot2_f32_bf16 v54, v52, v26, v54
	v_dot2_f32_bf16 v46, v56, v24, v46
	v_cvt_scalef32_pk_bf16_fp4 v48, v87, 1.0
	v_cvt_scalef32_pk_bf16_fp4 v50, v87, 1.0 op_sel:[1,0,0]
	v_cvt_scalef32_pk_bf16_fp4 v52, v87, 1.0 op_sel:[0,1,0]
	v_cvt_scalef32_pk_bf16_fp4 v56, v87, 1.0 op_sel:[1,1,0]
	s_addc_u32 s27, s12, s27
	v_dot2_f32_bf16 v54, v48, v30, v54
	v_dot2_f32_bf16 v46, v50, v28, v46
	s_nop 0
	v_dot2_f32_bf16 v54, v52, v36, v54
	v_dot2_f32_bf16 v46, v56, v34, v46
	s_nop 2
	v_add_f32_e32 v46, v54, v46
	v_lshl_add_u64 v[48:49], s[26:27], 0, v[32:33]
	global_load_dwordx4 v[84:87], v[48:49], off
	s_waitcnt vmcnt(15)
; #define P4_FOR16(M) M(0) M(1) M(2) M(3) M(4) M(5) M(6) M(7) M(8) M(9) M(10) M(11) M(12) M(13) M(14) M(15)
; #define P4_U(i) { P4_DOT(b##i, part[i]); const int nk_ = __builtin_amdgcn_readlane(ksel, nb + i); P4_LOAD(b##i, Ug, nk_); }
; #define P4_U(i) { P4_DOT(b##i, part[i]); const int nk_ = __builtin_amdgcn_readlane(kn, i); P4_LOAD(b##i, nbase, nk_); }
; __device__ __forceinline__ void peer_gather_f4p(const float* X, const int* __restrict__ IDX, const float* __restrict__ G, ...
;     ...
;         {
;     ...
;             P4_FOR16(P4_U)
	v_cvt_scalef32_pk_bf16_fp4 v48, v88, 1.0
	v_cvt_scalef32_pk_bf16_fp4 v50, v88, 1.0 op_sel:[1,0,0]
	v_cvt_scalef32_pk_bf16_fp4 v52, v88, 1.0 op_sel:[0,1,0]
	v_cvt_scalef32_pk_bf16_fp4 v54, v88, 1.0 op_sel:[1,1,0]
	v_readlane_b32 s26, v2, 6
	v_dot2_f32_bf16 v56, v48, v6, 0
	v_dot2_f32_bf16 v48, v50, v4, 0
	v_dot2_f32_bf16 v56, v52, v10, v56
	s_lshr_b32 s26, s26, 7
	v_dot2_f32_bf16 v48, v54, v8, v48
	v_cvt_scalef32_pk_bf16_fp4 v50, v89, 1.0
	v_cvt_scalef32_pk_bf16_fp4 v52, v89, 1.0 op_sel:[1,0,0]
	v_cvt_scalef32_pk_bf16_fp4 v54, v89, 1.0 op_sel:[0,1,0]
	v_cvt_scalef32_pk_bf16_fp4 v58, v89, 1.0 op_sel:[1,1,0]
	s_mov_b32 s27, s86
	v_dot2_f32_bf16 v56, v50, v14, v56
	v_dot2_f32_bf16 v48, v52, v12, v48
	s_lshl_b64 s[26:27], s[26:27], 10
	v_dot2_f32_bf16 v56, v54, v18, v56
	v_dot2_f32_bf16 v48, v58, v16, v48
	v_cvt_scalef32_pk_bf16_fp4 v50, v90, 1.0
	v_cvt_scalef32_pk_bf16_fp4 v52, v90, 1.0 op_sel:[1,0,0]
	v_cvt_scalef32_pk_bf16_fp4 v54, v90, 1.0 op_sel:[0,1,0]
	v_cvt_scalef32_pk_bf16_fp4 v58, v90, 1.0 op_sel:[1,1,0]
	s_add_u32 s26, s13, s26
	v_dot2_f32_bf16 v56, v50, v22, v56
	v_dot2_f32_bf16 v48, v52, v20, v48
	s_addc_u32 s27, s12, s27
	v_dot2_f32_bf16 v56, v54, v26, v56
	v_dot2_f32_bf16 v48, v58, v24, v48
	v_cvt_scalef32_pk_bf16_fp4 v50, v91, 1.0
	v_cvt_scalef32_pk_bf16_fp4 v52, v91, 1.0 op_sel:[1,0,0]
	v_cvt_scalef32_pk_bf16_fp4 v54, v91, 1.0 op_sel:[0,1,0]
	v_cvt_scalef32_pk_bf16_fp4 v58, v91, 1.0 op_sel:[1,1,0]
	s_nop 0
	v_dot2_f32_bf16 v56, v50, v30, v56
	v_dot2_f32_bf16 v48, v52, v28, v48
	s_nop 0
	v_dot2_f32_bf16 v56, v54, v36, v56
	v_dot2_f32_bf16 v48, v58, v34, v48
	s_nop 0
	s_nop 2
	v_add_f32_e32 v47, v56, v48
	v_lshl_add_u64 v[48:49], s[26:27], 0, v[32:33]
	global_load_dwordx4 v[88:91], v[48:49], off
	s_waitcnt vmcnt(15)
	v_cvt_scalef32_pk_bf16_fp4 v48, v92, 1.0
	v_cvt_scalef32_pk_bf16_fp4 v50, v92, 1.0 op_sel:[1,0,0]
	v_cvt_scalef32_pk_bf16_fp4 v52, v92, 1.0 op_sel:[0,1,0]
	v_cvt_scalef32_pk_bf16_fp4 v54, v92, 1.0 op_sel:[1,1,0]
	v_dot2_f32_bf16 v56, v48, v6, 0
	v_dot2_f32_bf16 v48, v50, v4, 0
	v_dot2_f32_bf16 v56, v52, v10, v56
	v_readlane_b32 s26, v2, 7
	v_dot2_f32_bf16 v48, v54, v8, v48
	v_cvt_scalef32_pk_bf16_fp4 v50, v93, 1.0
	v_cvt_scalef32_pk_bf16_fp4 v52, v93, 1.0 op_sel:[1,0,0]
	v_cvt_scalef32_pk_bf16_fp4 v54, v93, 1.0 op_sel:[0,1,0]
	v_cvt_scalef32_pk_bf16_fp4 v58, v93, 1.0 op_sel:[1,1,0]
	s_lshr_b32 s26, s26, 7
	v_dot2_f32_bf16 v56, v50, v14, v56
	v_dot2_f32_bf16 v48, v52, v12, v48
	s_mov_b32 s27, s86
	v_dot2_f32_bf16 v56, v54, v18, v56
	v_dot2_f32_bf16 v48, v58, v16, v48
	v_cvt_scalef32_pk_bf16_fp4 v50, v94, 1.0
	v_cvt_scalef32_pk_bf16_fp4 v52, v94, 1.0 op_sel:[1,0,0]
	v_cvt_scalef32_pk_bf16_fp4 v54, v94, 1.0 op_sel:[0,1,0]
	v_cvt_scalef32_pk_bf16_fp4 v58, v94, 1.0 op_sel:[1,1,0]
	s_lshl_b64 s[26:27], s[26:27], 10
	v_dot2_f32_bf16 v56, v50, v22, v56
	v_dot2_f32_bf16 v48, v52, v20, v48
	s_add_u32 s26, s13, s26
	v_dot2_f32_bf16 v56, v54, v26, v56
	v_dot2_f32_bf16 v48, v58, v24, v48
	v_cvt_scalef32_pk_bf16_fp4 v50, v95, 1.0
	v_cvt_scalef32_pk_bf16_fp4 v52, v95, 1.0 op_sel:[1,0,0]
	v_cvt_scalef32_pk_bf16_fp4 v54, v95, 1.0 op_sel:[0,1,0]
	v_cvt_scalef32_pk_bf16_fp4 v58, v95, 1.0 op_sel:[1,1,0]
	s_addc_u32 s27, s12, s27
	v_dot2_f32_bf16 v56, v50, v30, v56
	v_dot2_f32_bf16 v48, v52, v28, v48
	s_nop 0
	v_dot2_f32_bf16 v56, v54, v36, v56
	v_dot2_f32_bf16 v48, v58, v34, v48
	s_nop 2
	v_add_f32_e32 v48, v56, v48
	v_lshl_add_u64 v[50:51], s[26:27], 0, v[32:33]
	global_load_dwordx4 v[92:95], v[50:51], off
	s_waitcnt vmcnt(15)
	v_cvt_scalef32_pk_bf16_fp4 v50, v96, 1.0
	v_cvt_scalef32_pk_bf16_fp4 v52, v96, 1.0 op_sel:[1,0,0]
	v_cvt_scalef32_pk_bf16_fp4 v54, v96, 1.0 op_sel:[0,1,0]
	v_cvt_scalef32_pk_bf16_fp4 v56, v96, 1.0 op_sel:[1,1,0]
	v_readlane_b32 s26, v2, 8
	v_dot2_f32_bf16 v58, v50, v6, 0
	v_dot2_f32_bf16 v50, v52, v4, 0
	v_dot2_f32_bf16 v58, v54, v10, v58
	s_lshr_b32 s26, s26, 7
	v_dot2_f32_bf16 v50, v56, v8, v50
	v_cvt_scalef32_pk_bf16_fp4 v52, v97, 1.0
	v_cvt_scalef32_pk_bf16_fp4 v54, v97, 1.0 op_sel:[1,0,0]
	v_cvt_scalef32_pk_bf16_fp4 v56, v97, 1.0 op_sel:[0,1,0]
	v_cvt_scalef32_pk_bf16_fp4 v60, v97, 1.0 op_sel:[1,1,0]
	s_mov_b32 s27, s86
	v_dot2_f32_bf16 v58, v52, v14, v58
	v_dot2_f32_bf16 v50, v54, v12, v50
	s_lshl_b64 s[26:27], s[26:27], 10
	v_dot2_f32_bf16 v58, v56, v18, v58
	v_dot2_f32_bf16 v50, v60, v16, v50
	v_cvt_scalef32_pk_bf16_fp4 v52, v98, 1.0
	v_cvt_scalef32_pk_bf16_fp4 v54, v98, 1.0 op_sel:[1,0,0]
	v_cvt_scalef32_pk_bf16_fp4 v56, v98, 1.0 op_sel:[0,1,0]
	v_cvt_scalef32_pk_bf16_fp4 v60, v98, 1.0 op_sel:[1,1,0]
	s_add_u32 s26, s13, s26
	v_dot2_f32_bf16 v58, v52, v22, v58
	v_dot2_f32_bf16 v50, v54, v20, v50
	s_addc_u32 s27, s12, s27
	v_dot2_f32_bf16 v58, v56, v26, v58
	v_dot2_f32_bf16 v50, v60, v24, v50
	v_cvt_scalef32_pk_bf16_fp4 v52, v99, 1.0
	v_cvt_scalef32_pk_bf16_fp4 v54, v99, 1.0 op_sel:[1,0,0]
	v_cvt_scalef32_pk_bf16_fp4 v56, v99, 1.0 op_sel:[0,1,0]
	v_cvt_scalef32_pk_bf16_fp4 v60, v99, 1.0 op_sel:[1,1,0]
	s_nop 0
	v_dot2_f32_bf16 v58, v52, v30, v58
	v_dot2_f32_bf16 v50, v54, v28, v50
	s_nop 0
	v_dot2_f32_bf16 v58, v56, v36, v58
	v_dot2_f32_bf16 v50, v60, v34, v50
	s_nop 0
	s_nop 2
	v_add_f32_e32 v49, v58, v50
	v_lshl_add_u64 v[50:51], s[26:27], 0, v[32:33]
	global_load_dwordx4 v[96:99], v[50:51], off
	s_waitcnt vmcnt(15)
; #define P4_FOR16(M) M(0) M(1) M(2) M(3) M(4) M(5) M(6) M(7) M(8) M(9) M(10) M(11) M(12) M(13) M(14) M(15)
; #define P4_U(i) { P4_DOT(b##i, part[i]); const int nk_ = __builtin_amdgcn_readlane(ksel, nb + i); P4_LOAD(b##i, Ug, nk_); }
; #define P4_U(i) { P4_DOT(b##i, part[i]); const int nk_ = __builtin_amdgcn_readlane(kn, i); P4_LOAD(b##i, nbase, nk_); }
; __device__ __forceinline__ void peer_gather_f4p(const float* X, const int* __restrict__ IDX, const float* __restrict__ G, ...
;     ...
;         {
;     ...
;             P4_FOR16(P4_U)
	v_cvt_scalef32_pk_bf16_fp4 v50, v104, 1.0
	v_cvt_scalef32_pk_bf16_fp4 v52, v104, 1.0 op_sel:[1,0,0]
	v_cvt_scalef32_pk_bf16_fp4 v54, v104, 1.0 op_sel:[0,1,0]
	v_cvt_scalef32_pk_bf16_fp4 v56, v104, 1.0 op_sel:[1,1,0]
	v_dot2_f32_bf16 v58, v50, v6, 0
	v_dot2_f32_bf16 v50, v52, v4, 0
	v_dot2_f32_bf16 v58, v54, v10, v58
	v_readlane_b32 s26, v2, 9
	v_dot2_f32_bf16 v50, v56, v8, v50
	v_cvt_scalef32_pk_bf16_fp4 v52, v105, 1.0
	v_cvt_scalef32_pk_bf16_fp4 v54, v105, 1.0 op_sel:[1,0,0]
	v_cvt_scalef32_pk_bf16_fp4 v56, v105, 1.0 op_sel:[0,1,0]
	v_cvt_scalef32_pk_bf16_fp4 v60, v105, 1.0 op_sel:[1,1,0]
	s_lshr_b32 s26, s26, 7
	v_dot2_f32_bf16 v58, v52, v14, v58
	v_dot2_f32_bf16 v50, v54, v12, v50
	s_mov_b32 s27, s86
	v_dot2_f32_bf16 v58, v56, v18, v58
	v_dot2_f32_bf16 v50, v60, v16, v50
	v_cvt_scalef32_pk_bf16_fp4 v52, v106, 1.0
	v_cvt_scalef32_pk_bf16_fp4 v54, v106, 1.0 op_sel:[1,0,0]
	v_cvt_scalef32_pk_bf16_fp4 v56, v106, 1.0 op_sel:[0,1,0]
	v_cvt_scalef32_pk_bf16_fp4 v60, v106, 1.0 op_sel:[1,1,0]
	s_lshl_b64 s[26:27], s[26:27], 10
	v_dot2_f32_bf16 v58, v52, v22, v58
	v_dot2_f32_bf16 v50, v54, v20, v50
	s_add_u32 s26, s13, s26
	v_dot2_f32_bf16 v58, v56, v26, v58
	v_dot2_f32_bf16 v50, v60, v24, v50
	v_cvt_scalef32_pk_bf16_fp4 v52, v107, 1.0
	v_cvt_scalef32_pk_bf16_fp4 v54, v107, 1.0 op_sel:[1,0,0]
	v_cvt_scalef32_pk_bf16_fp4 v56, v107, 1.0 op_sel:[0,1,0]
	v_cvt_scalef32_pk_bf16_fp4 v60, v107, 1.0 op_sel:[1,1,0]
	s_addc_u32 s27, s12, s27
	v_dot2_f32_bf16 v58, v52, v30, v58
	v_dot2_f32_bf16 v50, v54, v28, v50
	s_nop 0
	v_dot2_f32_bf16 v58, v56, v36, v58
	v_dot2_f32_bf16 v50, v60, v34, v50
	s_nop 2
	v_add_f32_e32 v50, v58, v50
	v_lshl_add_u64 v[52:53], s[26:27], 0, v[32:33]
	global_load_dwordx4 v[104:107], v[52:53], off
	s_waitcnt vmcnt(15)
	v_cvt_scalef32_pk_bf16_fp4 v52, v108, 1.0
	v_cvt_scalef32_pk_bf16_fp4 v54, v108, 1.0 op_sel:[1,0,0]
	v_cvt_scalef32_pk_bf16_fp4 v56, v108, 1.0 op_sel:[0,1,0]
	v_cvt_scalef32_pk_bf16_fp4 v58, v108, 1.0 op_sel:[1,1,0]
	v_readlane_b32 s26, v2, 10
	v_dot2_f32_bf16 v60, v52, v6, 0
	v_dot2_f32_bf16 v52, v54, v4, 0
	v_dot2_f32_bf16 v60, v56, v10, v60
	s_lshr_b32 s26, s26, 7
	v_dot2_f32_bf16 v52, v58, v8, v52
	v_cvt_scalef32_pk_bf16_fp4 v54, v109, 1.0
	v_cvt_scalef32_pk_bf16_fp4 v56, v109, 1.0 op_sel:[1,0,0]
	v_cvt_scalef32_pk_bf16_fp4 v58, v109, 1.0 op_sel:[0,1,0]
	v_cvt_scalef32_pk_bf16_fp4 v62, v109, 1.0 op_sel:[1,1,0]
	s_mov_b32 s27, s86
	v_dot2_f32_bf16 v60, v54, v14, v60
	v_dot2_f32_bf16 v52, v56, v12, v52
	s_lshl_b64 s[26:27], s[26:27], 10
	v_dot2_f32_bf16 v60, v58, v18, v60
	v_dot2_f32_bf16 v52, v62, v16, v52
	v_cvt_scalef32_pk_bf16_fp4 v54, v110, 1.0
	v_cvt_scalef32_pk_bf16_fp4 v56, v110, 1.0 op_sel:[1,0,0]
	v_cvt_scalef32_pk_bf16_fp4 v58, v110, 1.0 op_sel:[0,1,0]
	v_cvt_scalef32_pk_bf16_fp4 v62, v110, 1.0 op_sel:[1,1,0]
	s_add_u32 s26, s13, s26
	v_dot2_f32_bf16 v60, v54, v22, v60
	v_dot2_f32_bf16 v52, v56, v20, v52
	s_addc_u32 s27, s12, s27
	v_dot2_f32_bf16 v60, v58, v26, v60
	v_dot2_f32_bf16 v52, v62, v24, v52
	v_cvt_scalef32_pk_bf16_fp4 v54, v111, 1.0
	v_cvt_scalef32_pk_bf16_fp4 v56, v111, 1.0 op_sel:[1,0,0]
	v_cvt_scalef32_pk_bf16_fp4 v58, v111, 1.0 op_sel:[0,1,0]
	v_cvt_scalef32_pk_bf16_fp4 v62, v111, 1.0 op_sel:[1,1,0]
	s_nop 0
	v_dot2_f32_bf16 v60, v54, v30, v60
	v_dot2_f32_bf16 v52, v56, v28, v52
	s_nop 0
	v_dot2_f32_bf16 v60, v58, v36, v60
	v_dot2_f32_bf16 v52, v62, v34, v52
	s_nop 0
	s_nop 2
	v_add_f32_e32 v51, v60, v52
	v_lshl_add_u64 v[52:53], s[26:27], 0, v[32:33]
	global_load_dwordx4 v[108:111], v[52:53], off
	s_waitcnt vmcnt(15)
	v_cvt_scalef32_pk_bf16_fp4 v52, v112, 1.0
	v_cvt_scalef32_pk_bf16_fp4 v54, v112, 1.0 op_sel:[1,0,0]
	v_cvt_scalef32_pk_bf16_fp4 v56, v112, 1.0 op_sel:[0,1,0]
	v_cvt_scalef32_pk_bf16_fp4 v58, v112, 1.0 op_sel:[1,1,0]
	v_dot2_f32_bf16 v60, v52, v6, 0
	v_dot2_f32_bf16 v52, v54, v4, 0
	v_dot2_f32_bf16 v60, v56, v10, v60
	v_readlane_b32 s26, v2, 11
	v_dot2_f32_bf16 v52, v58, v8, v52
	v_cvt_scalef32_pk_bf16_fp4 v54, v113, 1.0
	v_cvt_scalef32_pk_bf16_fp4 v56, v113, 1.0 op_sel:[1,0,0]
	v_cvt_scalef32_pk_bf16_fp4 v58, v113, 1.0 op_sel:[0,1,0]
	v_cvt_scalef32_pk_bf16_fp4 v62, v113, 1.0 op_sel:[1,1,0]
	s_lshr_b32 s26, s26, 7
	v_dot2_f32_bf16 v60, v54, v14, v60
	v_dot2_f32_bf16 v52, v56, v12, v52
	s_mov_b32 s27, s86
	v_dot2_f32_bf16 v60, v58, v18, v60
	v_dot2_f32_bf16 v52, v62, v16, v52
	v_cvt_scalef32_pk_bf16_fp4 v54, v114, 1.0
	v_cvt_scalef32_pk_bf16_fp4 v56, v114, 1.0 op_sel:[1,0,0]
	v_cvt_scalef32_pk_bf16_fp4 v58, v114, 1.0 op_sel:[0,1,0]
	v_cvt_scalef32_pk_bf16_fp4 v62, v114, 1.0 op_sel:[1,1,0]
	s_lshl_b64 s[26:27], s[26:27], 10
	v_dot2_f32_bf16 v60, v54, v22, v60
	v_dot2_f32_bf16 v52, v56, v20, v52
	s_add_u32 s26, s13, s26
	v_dot2_f32_bf16 v60, v58, v26, v60
	v_dot2_f32_bf16 v52, v62, v24, v52
	v_cvt_scalef32_pk_bf16_fp4 v54, v115, 1.0
	v_cvt_scalef32_pk_bf16_fp4 v56, v115, 1.0 op_sel:[1,0,0]
	v_cvt_scalef32_pk_bf16_fp4 v58, v115, 1.0 op_sel:[0,1,0]
	v_cvt_scalef32_pk_bf16_fp4 v62, v115, 1.0 op_sel:[1,1,0]
	s_addc_u32 s27, s12, s27
	v_dot2_f32_bf16 v60, v54, v30, v60
	v_dot2_f32_bf16 v52, v56, v28, v52
	s_nop 0
	v_dot2_f32_bf16 v60, v58, v36, v60
	v_dot2_f32_bf16 v52, v62, v34, v52
	s_nop 0
	s_nop 2
	v_add_f32_e32 v100, v60, v52
	v_lshl_add_u64 v[52:53], s[26:27], 0, v[32:33]
	global_load_dwordx4 v[112:115], v[52:53], off
	s_waitcnt vmcnt(15)
; #define P4_FOR16(M) M(0) M(1) M(2) M(3) M(4) M(5) M(6) M(7) M(8) M(9) M(10) M(11) M(12) M(13) M(14) M(15)
; #define P4_U(i) { P4_DOT(b##i, part[i]); const int nk_ = __builtin_amdgcn_readlane(ksel, nb + i); P4_LOAD(b##i, Ug, nk_); }
; #define P4_U(i) { P4_DOT(b##i, part[i]); const int nk_ = __builtin_amdgcn_readlane(kn, i); P4_LOAD(b##i, nbase, nk_); }
; __device__ __forceinline__ void peer_gather_f4p(const float* X, const int* __restrict__ IDX, const float* __restrict__ G, ...
;     ...
;         {
;     ...
;             P4_FOR16(P4_U)
	v_cvt_scalef32_pk_bf16_fp4 v52, v116, 1.0
	v_cvt_scalef32_pk_bf16_fp4 v54, v116, 1.0 op_sel:[1,0,0]
	v_cvt_scalef32_pk_bf16_fp4 v56, v116, 1.0 op_sel:[0,1,0]
	v_cvt_scalef32_pk_bf16_fp4 v58, v116, 1.0 op_sel:[1,1,0]
	v_dot2_f32_bf16 v60, v52, v6, 0
	v_dot2_f32_bf16 v52, v54, v4, 0
	v_dot2_f32_bf16 v60, v56, v10, v60
	v_readlane_b32 s26, v2, 12
	v_dot2_f32_bf16 v52, v58, v8, v52
	v_cvt_scalef32_pk_bf16_fp4 v54, v117, 1.0
	v_cvt_scalef32_pk_bf16_fp4 v56, v117, 1.0 op_sel:[1,0,0]
	v_cvt_scalef32_pk_bf16_fp4 v58, v117, 1.0 op_sel:[0,1,0]
	v_cvt_scalef32_pk_bf16_fp4 v62, v117, 1.0 op_sel:[1,1,0]
	s_lshr_b32 s26, s26, 7
	v_dot2_f32_bf16 v60, v54, v14, v60
	v_dot2_f32_bf16 v52, v56, v12, v52
	s_mov_b32 s27, s86
	v_dot2_f32_bf16 v60, v58, v18, v60
	v_dot2_f32_bf16 v52, v62, v16, v52
	v_cvt_scalef32_pk_bf16_fp4 v54, v118, 1.0
	v_cvt_scalef32_pk_bf16_fp4 v56, v118, 1.0 op_sel:[1,0,0]
	v_cvt_scalef32_pk_bf16_fp4 v58, v118, 1.0 op_sel:[0,1,0]
	v_cvt_scalef32_pk_bf16_fp4 v62, v118, 1.0 op_sel:[1,1,0]
	s_lshl_b64 s[26:27], s[26:27], 10
	v_dot2_f32_bf16 v60, v54, v22, v60
	v_dot2_f32_bf16 v52, v56, v20, v52
	s_add_u32 s26, s13, s26
	v_dot2_f32_bf16 v60, v58, v26, v60
	v_dot2_f32_bf16 v52, v62, v24, v52
	v_cvt_scalef32_pk_bf16_fp4 v54, v119, 1.0
	v_cvt_scalef32_pk_bf16_fp4 v56, v119, 1.0 op_sel:[1,0,0]
	v_cvt_scalef32_pk_bf16_fp4 v58, v119, 1.0 op_sel:[0,1,0]
	v_cvt_scalef32_pk_bf16_fp4 v62, v119, 1.0 op_sel:[1,1,0]
	s_addc_u32 s27, s12, s27
	v_dot2_f32_bf16 v60, v54, v30, v60
	v_dot2_f32_bf16 v52, v56, v28, v52
	s_nop 0
	v_dot2_f32_bf16 v60, v58, v36, v60
	v_dot2_f32_bf16 v52, v62, v34, v52
	s_nop 0
	s_nop 2
	v_add_f32_e32 v101, v60, v52
	v_lshl_add_u64 v[52:53], s[26:27], 0, v[32:33]
	global_load_dwordx4 v[116:119], v[52:53], off
	s_waitcnt vmcnt(15)
	v_cvt_scalef32_pk_bf16_fp4 v52, v120, 1.0
	v_cvt_scalef32_pk_bf16_fp4 v54, v120, 1.0 op_sel:[1,0,0]
	v_cvt_scalef32_pk_bf16_fp4 v56, v120, 1.0 op_sel:[0,1,0]
	v_cvt_scalef32_pk_bf16_fp4 v58, v120, 1.0 op_sel:[1,1,0]
	v_dot2_f32_bf16 v60, v52, v6, 0
	v_dot2_f32_bf16 v52, v54, v4, 0
	v_dot2_f32_bf16 v60, v56, v10, v60
	v_readlane_b32 s26, v2, 13
	v_dot2_f32_bf16 v52, v58, v8, v52
	v_cvt_scalef32_pk_bf16_fp4 v54, v121, 1.0
	v_cvt_scalef32_pk_bf16_fp4 v56, v121, 1.0 op_sel:[1,0,0]
	v_cvt_scalef32_pk_bf16_fp4 v58, v121, 1.0 op_sel:[0,1,0]
	v_cvt_scalef32_pk_bf16_fp4 v62, v121, 1.0 op_sel:[1,1,0]
	s_lshr_b32 s26, s26, 7
	v_dot2_f32_bf16 v60, v54, v14, v60
	v_dot2_f32_bf16 v52, v56, v12, v52
	s_mov_b32 s27, s86
	v_dot2_f32_bf16 v60, v58, v18, v60
	v_dot2_f32_bf16 v52, v62, v16, v52
	v_cvt_scalef32_pk_bf16_fp4 v54, v122, 1.0
	v_cvt_scalef32_pk_bf16_fp4 v56, v122, 1.0 op_sel:[1,0,0]
	v_cvt_scalef32_pk_bf16_fp4 v58, v122, 1.0 op_sel:[0,1,0]
	v_cvt_scalef32_pk_bf16_fp4 v62, v122, 1.0 op_sel:[1,1,0]
	s_lshl_b64 s[26:27], s[26:27], 10
	v_dot2_f32_bf16 v60, v54, v22, v60
	v_dot2_f32_bf16 v52, v56, v20, v52
	s_add_u32 s26, s13, s26
	v_dot2_f32_bf16 v60, v58, v26, v60
	v_dot2_f32_bf16 v52, v62, v24, v52
	v_cvt_scalef32_pk_bf16_fp4 v54, v123, 1.0
	v_cvt_scalef32_pk_bf16_fp4 v56, v123, 1.0 op_sel:[1,0,0]
	v_cvt_scalef32_pk_bf16_fp4 v58, v123, 1.0 op_sel:[0,1,0]
	v_cvt_scalef32_pk_bf16_fp4 v62, v123, 1.0 op_sel:[1,1,0]
	s_addc_u32 s27, s12, s27
	v_dot2_f32_bf16 v60, v54, v30, v60
	v_dot2_f32_bf16 v52, v56, v28, v52
	s_nop 0
	v_dot2_f32_bf16 v60, v58, v36, v60
	v_dot2_f32_bf16 v52, v62, v34, v52
	s_nop 0
	s_nop 2
	v_add_f32_e32 v102, v60, v52
	v_lshl_add_u64 v[52:53], s[26:27], 0, v[32:33]
	global_load_dwordx4 v[120:123], v[52:53], off
	s_waitcnt vmcnt(15)
	v_cvt_scalef32_pk_bf16_fp4 v52, v124, 1.0
	v_cvt_scalef32_pk_bf16_fp4 v54, v124, 1.0 op_sel:[1,0,0]
	v_cvt_scalef32_pk_bf16_fp4 v56, v124, 1.0 op_sel:[0,1,0]
	v_cvt_scalef32_pk_bf16_fp4 v58, v124, 1.0 op_sel:[1,1,0]
	v_dot2_f32_bf16 v60, v52, v6, 0
	v_dot2_f32_bf16 v52, v54, v4, 0
	v_dot2_f32_bf16 v60, v56, v10, v60
	v_readlane_b32 s26, v2, 14
	v_dot2_f32_bf16 v52, v58, v8, v52
	v_cvt_scalef32_pk_bf16_fp4 v54, v125, 1.0
	v_cvt_scalef32_pk_bf16_fp4 v56, v125, 1.0 op_sel:[1,0,0]
	v_cvt_scalef32_pk_bf16_fp4 v58, v125, 1.0 op_sel:[0,1,0]
	v_cvt_scalef32_pk_bf16_fp4 v62, v125, 1.0 op_sel:[1,1,0]
	s_lshr_b32 s26, s26, 7
	v_dot2_f32_bf16 v60, v54, v14, v60
	v_dot2_f32_bf16 v52, v56, v12, v52
	s_mov_b32 s27, s86
	v_dot2_f32_bf16 v60, v58, v18, v60
	v_dot2_f32_bf16 v52, v62, v16, v52
	v_cvt_scalef32_pk_bf16_fp4 v54, v126, 1.0
	v_cvt_scalef32_pk_bf16_fp4 v56, v126, 1.0 op_sel:[1,0,0]
	v_cvt_scalef32_pk_bf16_fp4 v58, v126, 1.0 op_sel:[0,1,0]
	v_cvt_scalef32_pk_bf16_fp4 v62, v126, 1.0 op_sel:[1,1,0]
	s_lshl_b64 s[26:27], s[26:27], 10
	v_dot2_f32_bf16 v60, v54, v22, v60
	v_dot2_f32_bf16 v52, v56, v20, v52
	s_add_u32 s26, s13, s26
	v_dot2_f32_bf16 v60, v58, v26, v60
	v_dot2_f32_bf16 v52, v62, v24, v52
	v_cvt_scalef32_pk_bf16_fp4 v54, v127, 1.0
	v_cvt_scalef32_pk_bf16_fp4 v56, v127, 1.0 op_sel:[1,0,0]
	v_cvt_scalef32_pk_bf16_fp4 v58, v127, 1.0 op_sel:[0,1,0]
	v_cvt_scalef32_pk_bf16_fp4 v62, v127, 1.0 op_sel:[1,1,0]
	s_addc_u32 s27, s12, s27
	v_dot2_f32_bf16 v60, v54, v30, v60
	v_dot2_f32_bf16 v52, v56, v28, v52
	s_nop 0
	v_dot2_f32_bf16 v60, v58, v36, v60
	v_dot2_f32_bf16 v52, v62, v34, v52
	s_nop 0
	s_nop 2
	v_add_f32_e32 v62, v60, v52
	v_lshl_add_u64 v[52:53], s[26:27], 0, v[32:33]
	global_load_dwordx4 v[124:127], v[52:53], off
	s_waitcnt vmcnt(15)
; __device__ __forceinline__ float gelu_tanh(float h) {
;     return 0.5f * h * (1.f + tanhf(0.7978845608028654f * (h + 0.044715f * h * h * h)));
; }
	v_cvt_scalef32_pk_bf16_fp4 v52, v128, 1.0
	v_cvt_scalef32_pk_bf16_fp4 v54, v128, 1.0 op_sel:[1,0,0]
	v_cvt_scalef32_pk_bf16_fp4 v56, v128, 1.0 op_sel:[0,1,0]
	v_cvt_scalef32_pk_bf16_fp4 v58, v128, 1.0 op_sel:[1,1,0]
	v_readlane_b32 s26, v2, 15
	v_dot2_f32_bf16 v60, v52, v6, 0
	v_dot2c_f32_bf16_e32 v38, v54, v4
	s_lshr_b32 s26, s26, 7
	v_dot2_f32_bf16 v60, v56, v10, v60
	v_dot2c_f32_bf16_e32 v38, v58, v8
	v_cvt_scalef32_pk_bf16_fp4 v4, v129, 1.0
	v_cvt_scalef32_pk_bf16_fp4 v6, v129, 1.0 op_sel:[1,0,0]
	v_cvt_scalef32_pk_bf16_fp4 v8, v129, 1.0 op_sel:[0,1,0]
	v_cvt_scalef32_pk_bf16_fp4 v10, v129, 1.0 op_sel:[1,1,0]
	s_mov_b32 s27, s86
	v_dot2_f32_bf16 v60, v4, v14, v60
	v_dot2c_f32_bf16_e32 v38, v6, v12
	s_lshl_b64 s[26:27], s[26:27], 10
	v_dot2_f32_bf16 v60, v8, v18, v60
	v_dot2c_f32_bf16_e32 v38, v10, v16
	v_cvt_scalef32_pk_bf16_fp4 v4, v130, 1.0
	v_cvt_scalef32_pk_bf16_fp4 v6, v130, 1.0 op_sel:[1,0,0]
	v_cvt_scalef32_pk_bf16_fp4 v8, v130, 1.0 op_sel:[0,1,0]
	v_cvt_scalef32_pk_bf16_fp4 v10, v130, 1.0 op_sel:[1,1,0]
	s_add_u32 s26, s13, s26
	v_dot2_f32_bf16 v60, v4, v22, v60
	v_dot2c_f32_bf16_e32 v38, v6, v20
	s_addc_u32 s27, s12, s27
	v_dot2_f32_bf16 v60, v8, v26, v60
	v_dot2c_f32_bf16_e32 v38, v10, v24
	v_cvt_scalef32_pk_bf16_fp4 v4, v131, 1.0
	v_cvt_scalef32_pk_bf16_fp4 v6, v131, 1.0 op_sel:[1,0,0]
	v_cvt_scalef32_pk_bf16_fp4 v8, v131, 1.0 op_sel:[0,1,0]
	v_cvt_scalef32_pk_bf16_fp4 v10, v131, 1.0 op_sel:[1,1,0]
	v_cndmask_b32_e64 v2, v49, v41, s[48:49]
	v_dot2_f32_bf16 v60, v4, v30, v60
	v_dot2c_f32_bf16_e32 v38, v6, v28
	v_cndmask_b32_e64 v7, v43, v51, s[48:49]
	v_dot2_f32_bf16 v60, v8, v36, v60
	v_dot2c_f32_bf16_e32 v38, v10, v34
	ds_swizzle_b32 v7, v7 offset:swizzle(SWAP,8)
	s_nop 2
	v_add_f32_e32 v6, v60, v38
	v_lshl_add_u64 v[4:5], s[26:27], 0, v[32:33]
	global_load_dwordx4 v[128:131], v[4:5], off
	v_cndmask_b32_e64 v4, v41, v49, s[48:49]
	ds_swizzle_b32 v4, v4 offset:swizzle(SWAP,8)
	v_cndmask_b32_e64 v5, v42, v50, s[48:49]
	ds_swizzle_b32 v5, v5 offset:swizzle(SWAP,8)
	v_cndmask_b32_e64 v8, v44, v100, s[48:49]
	ds_swizzle_b32 v8, v8 offset:swizzle(SWAP,8)
	v_cndmask_b32_e64 v9, v45, v101, s[48:49]
	ds_swizzle_b32 v9, v9 offset:swizzle(SWAP,8)
	v_cndmask_b32_e64 v10, v46, v102, s[48:49]
	s_waitcnt lgkmcnt(3)
	v_add_f32_e32 v2, v2, v4
	v_cndmask_b32_e64 v4, v50, v42, s[48:49]
	ds_swizzle_b32 v10, v10 offset:swizzle(SWAP,8)
	v_cndmask_b32_e64 v11, v47, v62, s[48:49]
	s_waitcnt lgkmcnt(3)
	v_add_f32_e32 v4, v4, v5
	v_cndmask_b32_e64 v5, v51, v43, s[48:49]
	ds_swizzle_b32 v11, v11 offset:swizzle(SWAP,8)
	v_add_f32_e32 v5, v5, v7
	v_cndmask_b32_e64 v7, v100, v44, s[48:49]
	s_waitcnt lgkmcnt(3)
	v_add_f32_e32 v7, v7, v8
	v_cndmask_b32_e64 v8, v101, v45, s[48:49]
	s_waitcnt lgkmcnt(2)
	v_add_f32_e32 v8, v8, v9
	v_cndmask_b32_e64 v9, v102, v46, s[48:49]
	s_waitcnt lgkmcnt(1)
	v_add_f32_e32 v9, v9, v10
	v_cndmask_b32_e64 v10, v62, v47, s[48:49]
	s_waitcnt lgkmcnt(0)
	v_add_f32_e32 v10, v10, v11
	v_cndmask_b32_e64 v11, v6, v48, s[48:49]
	v_cndmask_b32_e64 v6, v48, v6, s[48:49]
	ds_swizzle_b32 v6, v6 offset:swizzle(SWAP,8)
	s_waitcnt lgkmcnt(0)
	v_add_f32_e32 v6, v11, v6
	v_cndmask_b32_e64 v11, v8, v2, s[46:47]
	v_cndmask_b32_e64 v2, v2, v8, s[46:47]
	v_cndmask_b32_e64 v8, v9, v4, s[46:47]
	v_cndmask_b32_e64 v4, v4, v9, s[46:47]
	ds_swizzle_b32 v4, v4 offset:swizzle(SWAP,4)
	ds_swizzle_b32 v2, v2 offset:swizzle(SWAP,4)
	s_waitcnt lgkmcnt(1)
	v_add_f32_e32 v4, v8, v4
	v_cndmask_b32_e64 v8, v10, v5, s[46:47]
	v_cndmask_b32_e64 v5, v5, v10, s[46:47]
	ds_swizzle_b32 v5, v5 offset:swizzle(SWAP,4)
	s_waitcnt lgkmcnt(1)
	v_add_f32_e32 v2, v11, v2
	s_waitcnt lgkmcnt(0)
	v_add_f32_e32 v5, v8, v5
	v_cndmask_b32_e64 v8, v6, v7, s[46:47]
	v_cndmask_b32_e64 v6, v7, v6, s[46:47]
	ds_swizzle_b32 v6, v6 offset:swizzle(SWAP,4)
	v_cndmask_b32_e64 v7, v5, v2, s[44:45]
	v_cndmask_b32_e64 v2, v2, v5, s[44:45]
	ds_swizzle_b32 v2, v2 offset:swizzle(SWAP,2)
	s_waitcnt lgkmcnt(1)
	v_add_f32_e32 v6, v8, v6
	v_cndmask_b32_e64 v5, v6, v4, s[44:45]
	v_cndmask_b32_e64 v4, v4, v6, s[44:45]
	ds_swizzle_b32 v4, v4 offset:swizzle(SWAP,2)
	s_waitcnt lgkmcnt(1)
	v_add_f32_e32 v2, v7, v2
	s_waitcnt lgkmcnt(0)
	v_add_f32_e32 v4, v5, v4
	v_cndmask_b32_e64 v5, v4, v2, s[42:43]
	v_cndmask_b32_e64 v2, v2, v4, s[42:43]
	ds_swizzle_b32 v2, v2 offset:swizzle(SWAP,1)
	s_waitcnt lgkmcnt(0)
	v_add_f32_e32 v2, v5, v2
	ds_swizzle_b32 v4, v2 offset:swizzle(SWAP,16)
	s_waitcnt lgkmcnt(0)
	v_add_f32_e32 v2, v2, v4
	v_mov_b32_e32 v4, v2
	s_nop 1
	v_permlane32_swap_b32_e32 v2, v4
	v_add_f32_e32 v6, v2, v4
	v_lshl_add_u32 v2, v40, 2, s14
	v_add_u32_e32 v4, 0xc0, v2
	ds_read2st64_b32 v[4:5], v4 offset0:9 offset1:17
	s_waitcnt lgkmcnt(0)
	v_mul_f32_e32 v4, v4, v6
	v_mul_f32_e32 v6, 0x3d372713, v4
	v_mul_f32_e32 v6, v4, v6
	v_fma_f32 v6, v4, v6, v4
	v_mul_f32_e32 v6, 0x3f4c422a, v6
	v_cmp_nlt_f32_e64 s[12:13], |v6|, s25
	s_and_saveexec_b64 s[26:27], s[12:13]
	s_xor_b64 s[12:13], exec, s[26:27]
	s_cbranch_execz .LBB0_543
	v_add_f32_e64 v7, |v6|, |v6|
	v_mul_f32_e32 v8, 0x3fb8aa3b, v7
	v_rndne_f32_e32 v9, v8
	v_sub_f32_e32 v10, v8, v9
	v_fma_f32 v8, v7, s70, -v8
	v_fmac_f32_e32 v8, 0x32a5705f, v7
	v_add_f32_e32 v8, v10, v8
	v_cvt_i32_f32_e32 v9, v9
	v_exp_f32_e32 v8, v8
	v_cmp_ngt_f32_e64 s[42:43], s67, v7
	v_ldexp_f32 v8, v8, v9
	s_nop 0
	v_cndmask_b32_e64 v8, 0, v8, s[42:43]
	v_cmp_nlt_f32_e64 s[42:43], s68, v7
	s_nop 1
	v_cndmask_b32_e64 v7, v205, v8, s[42:43]
	v_add_f32_e32 v7, 1.0, v7
	v_rcp_f32_e32 v7, v7
	s_nop 0
	v_fma_f32 v7, v7, -2.0, 1.0
	s_andn2_saveexec_b64 s[12:13], s[12:13]
	s_cbranch_execnz .LBB0_544

; #define P4_FOR16(M) M(0) M(1) M(2) M(3) M(4) M(5) M(6) M(7) M(8) M(9) M(10) M(11) M(12) M(13) M(14) M(15)
; #define P4_U(i) { P4_DOT(b##i, part[i]); const int nk_ = __builtin_amdgcn_readlane(ksel, nb + i); P4_LOAD(b##i, Ug, nk_); }
; #define P4_U(i) { P4_DOT(b##i, part[i]); const int nk_ = __builtin_amdgcn_readlane(kn, i); P4_LOAD(b##i, nbase, nk_); }
; __device__ __forceinline__ void peer_gather_f4p(const float* X, const int* __restrict__ IDX, const float* __restrict__ G, ...
;     ...
; #pragma unroll 1
;         for (int bt = 0; bt < 7; ++bt) {
;             const int ksel = (bt + 1 < 4) ? k0 : k1;
;             const int nb = (16 * (bt + 1)) & 63;
;     ...
;             P4_FOR16(P4_U)
;     ...
;             P4_RED(bt);
.LBB0_1230:
	s_mov_b32 s87, s86
	s_waitcnt vmcnt(15)
	v_cvt_scalef32_pk_bf16_fp4 v48, v64, 1.0
	v_cvt_scalef32_pk_bf16_fp4 v50, v64, 1.0 op_sel:[1,0,0]
	v_cvt_scalef32_pk_bf16_fp4 v52, v64, 1.0 op_sel:[0,1,0]
	v_cvt_scalef32_pk_bf16_fp4 v54, v64, 1.0 op_sel:[1,1,0]
	v_dot2_f32_bf16 v56, v48, v6, 0
	v_dot2_f32_bf16 v48, v50, v4, 0
	v_dot2_f32_bf16 v56, v52, v10, v56
	s_cmp_lt_u32 s29, 3
	v_dot2_f32_bf16 v48, v54, v8, v48
	v_cvt_scalef32_pk_bf16_fp4 v50, v65, 1.0
	v_cvt_scalef32_pk_bf16_fp4 v52, v65, 1.0 op_sel:[1,0,0]
	v_cvt_scalef32_pk_bf16_fp4 v54, v65, 1.0 op_sel:[0,1,0]
	v_cvt_scalef32_pk_bf16_fp4 v58, v65, 1.0 op_sel:[1,1,0]
	s_cselect_b64 s[48:49], -1, 0
	v_dot2_f32_bf16 v56, v50, v14, v56
	v_dot2_f32_bf16 v48, v52, v12, v48
	s_waitcnt lgkmcnt(1)
	v_cndmask_b32_e64 v46, v39, v38, s[48:49]
	v_dot2_f32_bf16 v56, v54, v18, v56
	v_dot2_f32_bf16 v48, v58, v16, v48
	v_cvt_scalef32_pk_bf16_fp4 v50, v66, 1.0
	v_cvt_scalef32_pk_bf16_fp4 v52, v66, 1.0 op_sel:[1,0,0]
	v_cvt_scalef32_pk_bf16_fp4 v54, v66, 1.0 op_sel:[0,1,0]
	v_cvt_scalef32_pk_bf16_fp4 v58, v66, 1.0 op_sel:[1,1,0]
	s_add_i32 s12, s28, -15
	v_dot2_f32_bf16 v56, v50, v22, v56
	v_dot2_f32_bf16 v48, v52, v20, v48
	v_readlane_b32 s12, v46, s12
	v_dot2_f32_bf16 v56, v54, v26, v56
	v_dot2_f32_bf16 v48, v58, v24, v48
	v_cvt_scalef32_pk_bf16_fp4 v50, v67, 1.0
	v_cvt_scalef32_pk_bf16_fp4 v52, v67, 1.0 op_sel:[1,0,0]
	v_cvt_scalef32_pk_bf16_fp4 v54, v67, 1.0 op_sel:[0,1,0]
	v_cvt_scalef32_pk_bf16_fp4 v58, v67, 1.0 op_sel:[1,1,0]
	s_lshr_b32 s12, s12, 7
	v_dot2_f32_bf16 v56, v50, v30, v56
	v_dot2_f32_bf16 v48, v52, v28, v48
	s_mov_b32 s13, s86
	v_dot2_f32_bf16 v56, v54, v36, v56
	v_dot2_f32_bf16 v48, v58, v34, v48
	s_lshl_b64 s[12:13], s[12:13], 10
	s_nop 2
	v_add_f32_e32 v47, v56, v48
	v_lshl_add_u64 v[48:49], v[40:41], 0, s[12:13]
	global_load_dwordx4 v[64:67], v[48:49], off
	s_waitcnt vmcnt(15)
	v_cvt_scalef32_pk_bf16_fp4 v48, v68, 1.0
	v_cvt_scalef32_pk_bf16_fp4 v50, v68, 1.0 op_sel:[1,0,0]
	v_cvt_scalef32_pk_bf16_fp4 v52, v68, 1.0 op_sel:[0,1,0]
	v_cvt_scalef32_pk_bf16_fp4 v54, v68, 1.0 op_sel:[1,1,0]
	v_dot2_f32_bf16 v56, v48, v6, 0
	v_dot2_f32_bf16 v48, v50, v4, 0
	v_dot2_f32_bf16 v56, v52, v10, v56
	s_add_i32 s12, s28, -14
	v_dot2_f32_bf16 v48, v54, v8, v48
	v_cvt_scalef32_pk_bf16_fp4 v50, v69, 1.0
	v_cvt_scalef32_pk_bf16_fp4 v52, v69, 1.0 op_sel:[1,0,0]
	v_cvt_scalef32_pk_bf16_fp4 v54, v69, 1.0 op_sel:[0,1,0]
	v_cvt_scalef32_pk_bf16_fp4 v58, v69, 1.0 op_sel:[1,1,0]
	v_readlane_b32 s12, v46, s12
	v_dot2_f32_bf16 v56, v50, v14, v56
	v_dot2_f32_bf16 v48, v52, v12, v48
	s_lshr_b32 s12, s12, 7
	v_dot2_f32_bf16 v56, v54, v18, v56
	v_dot2_f32_bf16 v48, v58, v16, v48
	v_cvt_scalef32_pk_bf16_fp4 v50, v70, 1.0
	v_cvt_scalef32_pk_bf16_fp4 v52, v70, 1.0 op_sel:[1,0,0]
	v_cvt_scalef32_pk_bf16_fp4 v54, v70, 1.0 op_sel:[0,1,0]
	v_cvt_scalef32_pk_bf16_fp4 v58, v70, 1.0 op_sel:[1,1,0]
	s_mov_b32 s13, s86
	v_dot2_f32_bf16 v56, v50, v22, v56
	v_dot2_f32_bf16 v48, v52, v20, v48
	s_lshl_b64 s[12:13], s[12:13], 10
	v_dot2_f32_bf16 v56, v54, v26, v56
	v_dot2_f32_bf16 v48, v58, v24, v48
	v_cvt_scalef32_pk_bf16_fp4 v50, v71, 1.0
	v_cvt_scalef32_pk_bf16_fp4 v52, v71, 1.0 op_sel:[1,0,0]
	v_cvt_scalef32_pk_bf16_fp4 v54, v71, 1.0 op_sel:[0,1,0]
	v_cvt_scalef32_pk_bf16_fp4 v58, v71, 1.0 op_sel:[1,1,0]
	v_mov_b32_e32 v42, 0
	v_dot2_f32_bf16 v56, v50, v30, v56
	v_dot2_f32_bf16 v48, v52, v28, v48
	s_nop 0
	v_dot2_f32_bf16 v56, v54, v36, v56
	v_dot2_f32_bf16 v48, v58, v34, v48
	s_nop 2
	v_add_f32_e32 v48, v56, v48
	v_lshl_add_u64 v[50:51], v[40:41], 0, s[12:13]
	global_load_dwordx4 v[68:71], v[50:51], off
	s_waitcnt vmcnt(15)
	v_cvt_scalef32_pk_bf16_fp4 v50, v72, 1.0
	v_cvt_scalef32_pk_bf16_fp4 v52, v72, 1.0 op_sel:[1,0,0]
	v_cvt_scalef32_pk_bf16_fp4 v54, v72, 1.0 op_sel:[0,1,0]
	v_cvt_scalef32_pk_bf16_fp4 v56, v72, 1.0 op_sel:[1,1,0]
	s_add_i32 s12, s28, -13
	v_dot2_f32_bf16 v58, v50, v6, 0
	v_dot2_f32_bf16 v50, v52, v4, 0
	v_dot2_f32_bf16 v58, v54, v10, v58
	v_readlane_b32 s12, v46, s12
	v_dot2_f32_bf16 v50, v56, v8, v50
	v_cvt_scalef32_pk_bf16_fp4 v52, v73, 1.0
	v_cvt_scalef32_pk_bf16_fp4 v54, v73, 1.0 op_sel:[1,0,0]
	v_cvt_scalef32_pk_bf16_fp4 v56, v73, 1.0 op_sel:[0,1,0]
	v_cvt_scalef32_pk_bf16_fp4 v60, v73, 1.0 op_sel:[1,1,0]
	s_lshr_b32 s12, s12, 7
	v_dot2_f32_bf16 v58, v52, v14, v58
	v_dot2_f32_bf16 v50, v54, v12, v50
	s_mov_b32 s13, s86
	v_dot2_f32_bf16 v58, v56, v18, v58
	v_dot2_f32_bf16 v50, v60, v16, v50
	v_cvt_scalef32_pk_bf16_fp4 v52, v74, 1.0
	v_cvt_scalef32_pk_bf16_fp4 v54, v74, 1.0 op_sel:[1,0,0]
	v_cvt_scalef32_pk_bf16_fp4 v56, v74, 1.0 op_sel:[0,1,0]
	v_cvt_scalef32_pk_bf16_fp4 v60, v74, 1.0 op_sel:[1,1,0]
	s_lshl_b64 s[12:13], s[12:13], 10
	v_dot2_f32_bf16 v58, v52, v22, v58
	v_dot2_f32_bf16 v50, v54, v20, v50
	s_nop 0
	v_dot2_f32_bf16 v58, v56, v26, v58
	v_dot2_f32_bf16 v50, v60, v24, v50
	v_cvt_scalef32_pk_bf16_fp4 v52, v75, 1.0
	v_cvt_scalef32_pk_bf16_fp4 v54, v75, 1.0 op_sel:[1,0,0]
	v_cvt_scalef32_pk_bf16_fp4 v56, v75, 1.0 op_sel:[0,1,0]
	v_cvt_scalef32_pk_bf16_fp4 v60, v75, 1.0 op_sel:[1,1,0]
	s_nop 0
	v_dot2_f32_bf16 v58, v52, v30, v58
	v_dot2_f32_bf16 v50, v54, v28, v50
	s_nop 0
	v_dot2_f32_bf16 v58, v56, v36, v58
	v_dot2_f32_bf16 v50, v60, v34, v50
	s_nop 0
	s_nop 2
	v_add_f32_e32 v49, v58, v50
	v_lshl_add_u64 v[50:51], v[40:41], 0, s[12:13]
	global_load_dwordx4 v[72:75], v[50:51], off
	s_waitcnt vmcnt(15)
; #define P4_FOR16(M) M(0) M(1) M(2) M(3) M(4) M(5) M(6) M(7) M(8) M(9) M(10) M(11) M(12) M(13) M(14) M(15)
; #define P4_U(i) { P4_DOT(b##i, part[i]); const int nk_ = __builtin_amdgcn_readlane(ksel, nb + i); P4_LOAD(b##i, Ug, nk_); }
; #define P4_U(i) { P4_DOT(b##i, part[i]); const int nk_ = __builtin_amdgcn_readlane(kn, i); P4_LOAD(b##i, nbase, nk_); }
; __device__ __forceinline__ void peer_gather_f4p(const float* X, const int* __restrict__ IDX, const float* __restrict__ G, ...
;     ...
; #pragma unroll 1
;         for (int bt = 0; bt < 7; ++bt) {
;             const int ksel = (bt + 1 < 4) ? k0 : k1;
;             const int nb = (16 * (bt + 1)) & 63;
;     ...
;             P4_FOR16(P4_U)
;     ...
;             P4_RED(bt);
	v_cvt_scalef32_pk_bf16_fp4 v50, v76, 1.0
	v_cvt_scalef32_pk_bf16_fp4 v52, v76, 1.0 op_sel:[1,0,0]
	v_cvt_scalef32_pk_bf16_fp4 v54, v76, 1.0 op_sel:[0,1,0]
	v_cvt_scalef32_pk_bf16_fp4 v56, v76, 1.0 op_sel:[1,1,0]
	v_dot2_f32_bf16 v58, v50, v6, 0
	v_dot2_f32_bf16 v50, v52, v4, 0
	v_dot2_f32_bf16 v58, v54, v10, v58
	s_add_i32 s12, s28, -12
	v_dot2_f32_bf16 v50, v56, v8, v50
	v_cvt_scalef32_pk_bf16_fp4 v52, v77, 1.0
	v_cvt_scalef32_pk_bf16_fp4 v54, v77, 1.0 op_sel:[1,0,0]
	v_cvt_scalef32_pk_bf16_fp4 v56, v77, 1.0 op_sel:[0,1,0]
	v_cvt_scalef32_pk_bf16_fp4 v60, v77, 1.0 op_sel:[1,1,0]
	v_readlane_b32 s12, v46, s12
	v_dot2_f32_bf16 v58, v52, v14, v58
	v_dot2_f32_bf16 v50, v54, v12, v50
	s_lshr_b32 s12, s12, 7
	v_dot2_f32_bf16 v58, v56, v18, v58
	v_dot2_f32_bf16 v50, v60, v16, v50
	v_cvt_scalef32_pk_bf16_fp4 v52, v78, 1.0
	v_cvt_scalef32_pk_bf16_fp4 v54, v78, 1.0 op_sel:[1,0,0]
	v_cvt_scalef32_pk_bf16_fp4 v56, v78, 1.0 op_sel:[0,1,0]
	v_cvt_scalef32_pk_bf16_fp4 v60, v78, 1.0 op_sel:[1,1,0]
	s_mov_b32 s13, s86
	v_dot2_f32_bf16 v58, v52, v22, v58
	v_dot2_f32_bf16 v50, v54, v20, v50
	s_lshl_b64 s[12:13], s[12:13], 10
	v_dot2_f32_bf16 v58, v56, v26, v58
	v_dot2_f32_bf16 v50, v60, v24, v50
	v_cvt_scalef32_pk_bf16_fp4 v52, v79, 1.0
	v_cvt_scalef32_pk_bf16_fp4 v54, v79, 1.0 op_sel:[1,0,0]
	v_cvt_scalef32_pk_bf16_fp4 v56, v79, 1.0 op_sel:[0,1,0]
	v_cvt_scalef32_pk_bf16_fp4 v60, v79, 1.0 op_sel:[1,1,0]
	s_nop 0
	v_dot2_f32_bf16 v58, v52, v30, v58
	v_dot2_f32_bf16 v50, v54, v28, v50
	s_nop 0
	v_dot2_f32_bf16 v58, v56, v36, v58
	v_dot2_f32_bf16 v50, v60, v34, v50
	s_nop 2
	v_add_f32_e32 v50, v58, v50
	v_lshl_add_u64 v[52:53], v[40:41], 0, s[12:13]
	global_load_dwordx4 v[76:79], v[52:53], off
	s_waitcnt vmcnt(15)
	v_cvt_scalef32_pk_bf16_fp4 v52, v84, 1.0
	v_cvt_scalef32_pk_bf16_fp4 v54, v84, 1.0 op_sel:[1,0,0]
	v_cvt_scalef32_pk_bf16_fp4 v56, v84, 1.0 op_sel:[0,1,0]
	v_cvt_scalef32_pk_bf16_fp4 v58, v84, 1.0 op_sel:[1,1,0]
	s_add_i32 s12, s28, -11
	v_dot2_f32_bf16 v60, v52, v6, 0
	v_dot2_f32_bf16 v52, v54, v4, 0
	v_dot2_f32_bf16 v60, v56, v10, v60
	v_readlane_b32 s12, v46, s12
	v_dot2_f32_bf16 v52, v58, v8, v52
	v_cvt_scalef32_pk_bf16_fp4 v54, v85, 1.0
	v_cvt_scalef32_pk_bf16_fp4 v56, v85, 1.0 op_sel:[1,0,0]
	v_cvt_scalef32_pk_bf16_fp4 v58, v85, 1.0 op_sel:[0,1,0]
	v_cvt_scalef32_pk_bf16_fp4 v62, v85, 1.0 op_sel:[1,1,0]
	s_lshr_b32 s12, s12, 7
	v_dot2_f32_bf16 v60, v54, v14, v60
	v_dot2_f32_bf16 v52, v56, v12, v52
	s_mov_b32 s13, s86
	v_dot2_f32_bf16 v60, v58, v18, v60
	v_dot2_f32_bf16 v52, v62, v16, v52
	v_cvt_scalef32_pk_bf16_fp4 v54, v86, 1.0
	v_cvt_scalef32_pk_bf16_fp4 v56, v86, 1.0 op_sel:[1,0,0]
	v_cvt_scalef32_pk_bf16_fp4 v58, v86, 1.0 op_sel:[0,1,0]
	v_cvt_scalef32_pk_bf16_fp4 v62, v86, 1.0 op_sel:[1,1,0]
	s_lshl_b64 s[12:13], s[12:13], 10
	v_dot2_f32_bf16 v60, v54, v22, v60
	v_dot2_f32_bf16 v52, v56, v20, v52
	s_nop 0
	v_dot2_f32_bf16 v60, v58, v26, v60
	v_dot2_f32_bf16 v52, v62, v24, v52
	v_cvt_scalef32_pk_bf16_fp4 v54, v87, 1.0
	v_cvt_scalef32_pk_bf16_fp4 v56, v87, 1.0 op_sel:[1,0,0]
	v_cvt_scalef32_pk_bf16_fp4 v58, v87, 1.0 op_sel:[0,1,0]
	v_cvt_scalef32_pk_bf16_fp4 v62, v87, 1.0 op_sel:[1,1,0]
	s_nop 0
	v_dot2_f32_bf16 v60, v54, v30, v60
	v_dot2_f32_bf16 v52, v56, v28, v52
	s_nop 0
	v_dot2_f32_bf16 v60, v58, v36, v60
	v_dot2_f32_bf16 v52, v62, v34, v52
	s_nop 0
	s_nop 2
	v_add_f32_e32 v51, v60, v52
	v_lshl_add_u64 v[52:53], v[40:41], 0, s[12:13]
	global_load_dwordx4 v[84:87], v[52:53], off
	s_waitcnt vmcnt(15)
	v_cvt_scalef32_pk_bf16_fp4 v52, v88, 1.0
	v_cvt_scalef32_pk_bf16_fp4 v54, v88, 1.0 op_sel:[1,0,0]
	v_cvt_scalef32_pk_bf16_fp4 v56, v88, 1.0 op_sel:[0,1,0]
	v_cvt_scalef32_pk_bf16_fp4 v58, v88, 1.0 op_sel:[1,1,0]
	v_dot2_f32_bf16 v60, v52, v6, 0
	v_dot2_f32_bf16 v52, v54, v4, 0
	v_dot2_f32_bf16 v60, v56, v10, v60
	s_add_i32 s12, s28, -10
	v_dot2_f32_bf16 v52, v58, v8, v52
	v_cvt_scalef32_pk_bf16_fp4 v54, v89, 1.0
	v_cvt_scalef32_pk_bf16_fp4 v56, v89, 1.0 op_sel:[1,0,0]
	v_cvt_scalef32_pk_bf16_fp4 v58, v89, 1.0 op_sel:[0,1,0]
	v_cvt_scalef32_pk_bf16_fp4 v62, v89, 1.0 op_sel:[1,1,0]
	v_readlane_b32 s12, v46, s12
	v_dot2_f32_bf16 v60, v54, v14, v60
	v_dot2_f32_bf16 v52, v56, v12, v52
	s_lshr_b32 s12, s12, 7
	v_dot2_f32_bf16 v60, v58, v18, v60
	v_dot2_f32_bf16 v52, v62, v16, v52
	v_cvt_scalef32_pk_bf16_fp4 v54, v90, 1.0
	v_cvt_scalef32_pk_bf16_fp4 v56, v90, 1.0 op_sel:[1,0,0]
	v_cvt_scalef32_pk_bf16_fp4 v58, v90, 1.0 op_sel:[0,1,0]
	v_cvt_scalef32_pk_bf16_fp4 v62, v90, 1.0 op_sel:[1,1,0]
	s_mov_b32 s13, s86
	v_dot2_f32_bf16 v60, v54, v22, v60
	v_dot2_f32_bf16 v52, v56, v20, v52
	s_lshl_b64 s[12:13], s[12:13], 10
	v_dot2_f32_bf16 v60, v58, v26, v60
	v_dot2_f32_bf16 v52, v62, v24, v52
	v_cvt_scalef32_pk_bf16_fp4 v54, v91, 1.0
	v_cvt_scalef32_pk_bf16_fp4 v56, v91, 1.0 op_sel:[1,0,0]
	v_cvt_scalef32_pk_bf16_fp4 v58, v91, 1.0 op_sel:[0,1,0]
	v_cvt_scalef32_pk_bf16_fp4 v62, v91, 1.0 op_sel:[1,1,0]
	s_nop 0
	v_dot2_f32_bf16 v60, v54, v30, v60
	v_dot2_f32_bf16 v52, v56, v28, v52
	s_nop 0
	v_dot2_f32_bf16 v60, v58, v36, v60
	v_dot2_f32_bf16 v52, v62, v34, v52
	s_nop 2
	v_add_f32_e32 v52, v60, v52
	v_lshl_add_u64 v[54:55], v[40:41], 0, s[12:13]
	global_load_dwordx4 v[88:91], v[54:55], off
	s_waitcnt vmcnt(15)
; #define P4_FOR16(M) M(0) M(1) M(2) M(3) M(4) M(5) M(6) M(7) M(8) M(9) M(10) M(11) M(12) M(13) M(14) M(15)
; #define P4_U(i) { P4_DOT(b##i, part[i]); const int nk_ = __builtin_amdgcn_readlane(ksel, nb + i); P4_LOAD(b##i, Ug, nk_); }
; #define P4_U(i) { P4_DOT(b##i, part[i]); const int nk_ = __builtin_amdgcn_readlane(kn, i); P4_LOAD(b##i, nbase, nk_); }
; __device__ __forceinline__ void peer_gather_f4p(const float* X, const int* __restrict__ IDX, const float* __restrict__ G, ...
;     ...
; #pragma unroll 1
;         for (int bt = 0; bt < 7; ++bt) {
;             const int ksel = (bt + 1 < 4) ? k0 : k1;
;             const int nb = (16 * (bt + 1)) & 63;
;     ...
;             P4_FOR16(P4_U)
;     ...
;             P4_RED(bt);
	v_cvt_scalef32_pk_bf16_fp4 v54, v92, 1.0
	v_cvt_scalef32_pk_bf16_fp4 v56, v92, 1.0 op_sel:[1,0,0]
	v_cvt_scalef32_pk_bf16_fp4 v58, v92, 1.0 op_sel:[0,1,0]
	v_cvt_scalef32_pk_bf16_fp4 v60, v92, 1.0 op_sel:[1,1,0]
	s_add_i32 s12, s28, -9
	v_dot2_f32_bf16 v62, v54, v6, 0
	v_dot2_f32_bf16 v54, v56, v4, 0
	v_dot2_f32_bf16 v62, v58, v10, v62
	v_readlane_b32 s12, v46, s12
	v_dot2_f32_bf16 v54, v60, v8, v54
	v_cvt_scalef32_pk_bf16_fp4 v56, v93, 1.0
	v_cvt_scalef32_pk_bf16_fp4 v58, v93, 1.0 op_sel:[1,0,0]
	v_cvt_scalef32_pk_bf16_fp4 v60, v93, 1.0 op_sel:[0,1,0]
	v_cvt_scalef32_pk_bf16_fp4 v80, v93, 1.0 op_sel:[1,1,0]
	s_lshr_b32 s12, s12, 7
	v_dot2_f32_bf16 v62, v56, v14, v62
	v_dot2_f32_bf16 v54, v58, v12, v54
	s_mov_b32 s13, s86
	v_dot2_f32_bf16 v62, v60, v18, v62
	v_dot2_f32_bf16 v54, v80, v16, v54
	v_cvt_scalef32_pk_bf16_fp4 v56, v94, 1.0
	v_cvt_scalef32_pk_bf16_fp4 v58, v94, 1.0 op_sel:[1,0,0]
	v_cvt_scalef32_pk_bf16_fp4 v60, v94, 1.0 op_sel:[0,1,0]
	v_cvt_scalef32_pk_bf16_fp4 v80, v94, 1.0 op_sel:[1,1,0]
	s_lshl_b64 s[12:13], s[12:13], 10
	v_dot2_f32_bf16 v62, v56, v22, v62
	v_dot2_f32_bf16 v54, v58, v20, v54
	s_nop 0
	v_dot2_f32_bf16 v62, v60, v26, v62
	v_dot2_f32_bf16 v54, v80, v24, v54
	v_cvt_scalef32_pk_bf16_fp4 v56, v95, 1.0
	v_cvt_scalef32_pk_bf16_fp4 v58, v95, 1.0 op_sel:[1,0,0]
	v_cvt_scalef32_pk_bf16_fp4 v60, v95, 1.0 op_sel:[0,1,0]
	v_cvt_scalef32_pk_bf16_fp4 v80, v95, 1.0 op_sel:[1,1,0]
	s_nop 0
	v_dot2_f32_bf16 v62, v56, v30, v62
	v_dot2_f32_bf16 v54, v58, v28, v54
	s_nop 0
	v_dot2_f32_bf16 v62, v60, v36, v62
	v_dot2_f32_bf16 v54, v80, v34, v54
	s_nop 0
	s_nop 2
	v_add_f32_e32 v53, v62, v54
	v_lshl_add_u64 v[54:55], v[40:41], 0, s[12:13]
	global_load_dwordx4 v[92:95], v[54:55], off
	s_waitcnt vmcnt(15)
	v_cvt_scalef32_pk_bf16_fp4 v54, v96, 1.0
	v_cvt_scalef32_pk_bf16_fp4 v56, v96, 1.0 op_sel:[1,0,0]
	v_cvt_scalef32_pk_bf16_fp4 v58, v96, 1.0 op_sel:[0,1,0]
	v_cvt_scalef32_pk_bf16_fp4 v60, v96, 1.0 op_sel:[1,1,0]
	v_dot2_f32_bf16 v62, v54, v6, 0
	v_dot2_f32_bf16 v54, v56, v4, 0
	v_dot2_f32_bf16 v62, v58, v10, v62
	s_add_i32 s12, s28, -8
	v_dot2_f32_bf16 v54, v60, v8, v54
	v_cvt_scalef32_pk_bf16_fp4 v56, v97, 1.0
	v_cvt_scalef32_pk_bf16_fp4 v58, v97, 1.0 op_sel:[1,0,0]
	v_cvt_scalef32_pk_bf16_fp4 v60, v97, 1.0 op_sel:[0,1,0]
	v_cvt_scalef32_pk_bf16_fp4 v80, v97, 1.0 op_sel:[1,1,0]
	v_readlane_b32 s12, v46, s12
	v_dot2_f32_bf16 v62, v56, v14, v62
	v_dot2_f32_bf16 v54, v58, v12, v54
	s_lshr_b32 s12, s12, 7
	v_dot2_f32_bf16 v62, v60, v18, v62
	v_dot2_f32_bf16 v54, v80, v16, v54
	v_cvt_scalef32_pk_bf16_fp4 v56, v98, 1.0
	v_cvt_scalef32_pk_bf16_fp4 v58, v98, 1.0 op_sel:[1,0,0]
	v_cvt_scalef32_pk_bf16_fp4 v60, v98, 1.0 op_sel:[0,1,0]
	v_cvt_scalef32_pk_bf16_fp4 v80, v98, 1.0 op_sel:[1,1,0]
	s_mov_b32 s13, s86
	v_dot2_f32_bf16 v62, v56, v22, v62
	v_dot2_f32_bf16 v54, v58, v20, v54
	s_lshl_b64 s[12:13], s[12:13], 10
	v_dot2_f32_bf16 v62, v60, v26, v62
	v_dot2_f32_bf16 v54, v80, v24, v54
	v_cvt_scalef32_pk_bf16_fp4 v56, v99, 1.0
	v_cvt_scalef32_pk_bf16_fp4 v58, v99, 1.0 op_sel:[1,0,0]
	v_cvt_scalef32_pk_bf16_fp4 v60, v99, 1.0 op_sel:[0,1,0]
	v_cvt_scalef32_pk_bf16_fp4 v80, v99, 1.0 op_sel:[1,1,0]
	s_nop 0
	v_dot2_f32_bf16 v62, v56, v30, v62
	v_dot2_f32_bf16 v54, v58, v28, v54
	s_nop 0
	v_dot2_f32_bf16 v62, v60, v36, v62
	v_dot2_f32_bf16 v54, v80, v34, v54
	s_nop 2
	v_add_f32_e32 v54, v62, v54
	v_lshl_add_u64 v[56:57], v[40:41], 0, s[12:13]
	global_load_dwordx4 v[96:99], v[56:57], off
	s_waitcnt vmcnt(15)
	v_cvt_scalef32_pk_bf16_fp4 v56, v100, 1.0
	v_cvt_scalef32_pk_bf16_fp4 v58, v100, 1.0 op_sel:[1,0,0]
	v_cvt_scalef32_pk_bf16_fp4 v60, v100, 1.0 op_sel:[0,1,0]
	v_cvt_scalef32_pk_bf16_fp4 v62, v100, 1.0 op_sel:[1,1,0]
	s_add_i32 s12, s28, -7
	v_dot2_f32_bf16 v80, v56, v6, 0
	v_dot2_f32_bf16 v56, v58, v4, 0
	v_dot2_f32_bf16 v80, v60, v10, v80
	v_readlane_b32 s12, v46, s12
	v_dot2_f32_bf16 v56, v62, v8, v56
	v_cvt_scalef32_pk_bf16_fp4 v58, v101, 1.0
	v_cvt_scalef32_pk_bf16_fp4 v60, v101, 1.0 op_sel:[1,0,0]
	v_cvt_scalef32_pk_bf16_fp4 v62, v101, 1.0 op_sel:[0,1,0]
	v_cvt_scalef32_pk_bf16_fp4 v82, v101, 1.0 op_sel:[1,1,0]
	s_lshr_b32 s12, s12, 7
	v_dot2_f32_bf16 v80, v58, v14, v80
	v_dot2_f32_bf16 v56, v60, v12, v56
	s_mov_b32 s13, s86
	v_dot2_f32_bf16 v80, v62, v18, v80
	v_dot2_f32_bf16 v56, v82, v16, v56
	v_cvt_scalef32_pk_bf16_fp4 v58, v102, 1.0
	v_cvt_scalef32_pk_bf16_fp4 v60, v102, 1.0 op_sel:[1,0,0]
	v_cvt_scalef32_pk_bf16_fp4 v62, v102, 1.0 op_sel:[0,1,0]
	v_cvt_scalef32_pk_bf16_fp4 v82, v102, 1.0 op_sel:[1,1,0]
	s_lshl_b64 s[12:13], s[12:13], 10
	v_dot2_f32_bf16 v80, v58, v22, v80
	v_dot2_f32_bf16 v56, v60, v20, v56
	s_nop 0
	v_dot2_f32_bf16 v80, v62, v26, v80
	v_dot2_f32_bf16 v56, v82, v24, v56
	v_cvt_scalef32_pk_bf16_fp4 v58, v103, 1.0
	v_cvt_scalef32_pk_bf16_fp4 v60, v103, 1.0 op_sel:[1,0,0]
	v_cvt_scalef32_pk_bf16_fp4 v62, v103, 1.0 op_sel:[0,1,0]
	v_cvt_scalef32_pk_bf16_fp4 v82, v103, 1.0 op_sel:[1,1,0]
	s_nop 0
	v_dot2_f32_bf16 v80, v58, v30, v80
	v_dot2_f32_bf16 v56, v60, v28, v56
	s_nop 0
	v_dot2_f32_bf16 v80, v62, v36, v80
	v_dot2_f32_bf16 v56, v82, v34, v56
	s_nop 0
	s_nop 2
	v_add_f32_e32 v55, v80, v56
	v_lshl_add_u64 v[56:57], v[40:41], 0, s[12:13]
	global_load_dwordx4 v[100:103], v[56:57], off
	s_waitcnt vmcnt(15)
; #define P4_FOR16(M) M(0) M(1) M(2) M(3) M(4) M(5) M(6) M(7) M(8) M(9) M(10) M(11) M(12) M(13) M(14) M(15)
; #define P4_U(i) { P4_DOT(b##i, part[i]); const int nk_ = __builtin_amdgcn_readlane(ksel, nb + i); P4_LOAD(b##i, Ug, nk_); }
; #define P4_U(i) { P4_DOT(b##i, part[i]); const int nk_ = __builtin_amdgcn_readlane(kn, i); P4_LOAD(b##i, nbase, nk_); }
; __device__ __forceinline__ void peer_gather_f4p(const float* X, const int* __restrict__ IDX, const float* __restrict__ G, ...
;     ...
; #pragma unroll 1
;         for (int bt = 0; bt < 7; ++bt) {
;             const int ksel = (bt + 1 < 4) ? k0 : k1;
;             const int nb = (16 * (bt + 1)) & 63;
;     ...
;             P4_FOR16(P4_U)
;     ...
;             P4_RED(bt);
	v_cvt_scalef32_pk_bf16_fp4 v56, v104, 1.0
	v_cvt_scalef32_pk_bf16_fp4 v58, v104, 1.0 op_sel:[1,0,0]
	v_cvt_scalef32_pk_bf16_fp4 v60, v104, 1.0 op_sel:[0,1,0]
	v_cvt_scalef32_pk_bf16_fp4 v62, v104, 1.0 op_sel:[1,1,0]
	v_dot2_f32_bf16 v80, v56, v6, 0
	v_dot2_f32_bf16 v56, v58, v4, 0
	v_dot2_f32_bf16 v80, v60, v10, v80
	s_add_i32 s12, s28, -6
	v_dot2_f32_bf16 v56, v62, v8, v56
	v_cvt_scalef32_pk_bf16_fp4 v58, v105, 1.0
	v_cvt_scalef32_pk_bf16_fp4 v60, v105, 1.0 op_sel:[1,0,0]
	v_cvt_scalef32_pk_bf16_fp4 v62, v105, 1.0 op_sel:[0,1,0]
	v_cvt_scalef32_pk_bf16_fp4 v82, v105, 1.0 op_sel:[1,1,0]
	v_readlane_b32 s12, v46, s12
	v_dot2_f32_bf16 v80, v58, v14, v80
	v_dot2_f32_bf16 v56, v60, v12, v56
	s_lshr_b32 s12, s12, 7
	v_dot2_f32_bf16 v80, v62, v18, v80
	v_dot2_f32_bf16 v56, v82, v16, v56
	v_cvt_scalef32_pk_bf16_fp4 v58, v106, 1.0
	v_cvt_scalef32_pk_bf16_fp4 v60, v106, 1.0 op_sel:[1,0,0]
	v_cvt_scalef32_pk_bf16_fp4 v62, v106, 1.0 op_sel:[0,1,0]
	v_cvt_scalef32_pk_bf16_fp4 v82, v106, 1.0 op_sel:[1,1,0]
	s_mov_b32 s13, s86
	v_dot2_f32_bf16 v80, v58, v22, v80
	v_dot2_f32_bf16 v56, v60, v20, v56
	s_lshl_b64 s[12:13], s[12:13], 10
	v_dot2_f32_bf16 v80, v62, v26, v80
	v_dot2_f32_bf16 v56, v82, v24, v56
	v_cvt_scalef32_pk_bf16_fp4 v58, v107, 1.0
	v_cvt_scalef32_pk_bf16_fp4 v60, v107, 1.0 op_sel:[1,0,0]
	v_cvt_scalef32_pk_bf16_fp4 v62, v107, 1.0 op_sel:[0,1,0]
	v_cvt_scalef32_pk_bf16_fp4 v82, v107, 1.0 op_sel:[1,1,0]
	s_nop 0
	v_dot2_f32_bf16 v80, v58, v30, v80
	v_dot2_f32_bf16 v56, v60, v28, v56
	s_nop 0
	v_dot2_f32_bf16 v80, v62, v36, v80
	v_dot2_f32_bf16 v56, v82, v34, v56
	s_nop 2
	v_add_f32_e32 v56, v80, v56
	v_lshl_add_u64 v[58:59], v[40:41], 0, s[12:13]
	global_load_dwordx4 v[104:107], v[58:59], off
	s_waitcnt vmcnt(15)
	v_cvt_scalef32_pk_bf16_fp4 v58, v108, 1.0
	v_cvt_scalef32_pk_bf16_fp4 v60, v108, 1.0 op_sel:[1,0,0]
	v_cvt_scalef32_pk_bf16_fp4 v62, v108, 1.0 op_sel:[0,1,0]
	v_cvt_scalef32_pk_bf16_fp4 v80, v108, 1.0 op_sel:[1,1,0]
	s_add_i32 s12, s28, -5
	v_dot2_f32_bf16 v82, v58, v6, 0
	v_dot2_f32_bf16 v58, v60, v4, 0
	v_dot2_f32_bf16 v82, v62, v10, v82
	v_readlane_b32 s12, v46, s12
	v_dot2_f32_bf16 v58, v80, v8, v58
	v_cvt_scalef32_pk_bf16_fp4 v60, v109, 1.0
	v_cvt_scalef32_pk_bf16_fp4 v62, v109, 1.0 op_sel:[1,0,0]
	v_cvt_scalef32_pk_bf16_fp4 v80, v109, 1.0 op_sel:[0,1,0]
	v_cvt_scalef32_pk_bf16_fp4 v108, v109, 1.0 op_sel:[1,1,0]
	s_lshr_b32 s12, s12, 7
	v_dot2_f32_bf16 v82, v60, v14, v82
	v_dot2_f32_bf16 v58, v62, v12, v58
	s_mov_b32 s13, s86
	v_dot2_f32_bf16 v82, v80, v18, v82
	v_dot2_f32_bf16 v58, v108, v16, v58
	v_cvt_scalef32_pk_bf16_fp4 v60, v110, 1.0
	v_cvt_scalef32_pk_bf16_fp4 v62, v110, 1.0 op_sel:[1,0,0]
	v_cvt_scalef32_pk_bf16_fp4 v80, v110, 1.0 op_sel:[0,1,0]
	v_cvt_scalef32_pk_bf16_fp4 v108, v110, 1.0 op_sel:[1,1,0]
	s_lshl_b64 s[12:13], s[12:13], 10
	v_dot2_f32_bf16 v82, v60, v22, v82
	v_dot2_f32_bf16 v58, v62, v20, v58
	s_nop 0
	v_dot2_f32_bf16 v82, v80, v26, v82
	v_dot2_f32_bf16 v58, v108, v24, v58
	v_cvt_scalef32_pk_bf16_fp4 v60, v111, 1.0
	v_cvt_scalef32_pk_bf16_fp4 v62, v111, 1.0 op_sel:[1,0,0]
	v_cvt_scalef32_pk_bf16_fp4 v80, v111, 1.0 op_sel:[0,1,0]
	v_cvt_scalef32_pk_bf16_fp4 v108, v111, 1.0 op_sel:[1,1,0]
	s_nop 0
	v_dot2_f32_bf16 v82, v60, v30, v82
	v_dot2_f32_bf16 v58, v62, v28, v58
	s_nop 0
	v_dot2_f32_bf16 v82, v80, v36, v82
	v_dot2_f32_bf16 v58, v108, v34, v58
	s_nop 0
	s_nop 2
	v_add_f32_e32 v57, v82, v58
	v_lshl_add_u64 v[58:59], v[40:41], 0, s[12:13]
	global_load_dwordx4 v[108:111], v[58:59], off
	s_waitcnt vmcnt(15)
	v_cvt_scalef32_pk_bf16_fp4 v58, v112, 1.0
	v_cvt_scalef32_pk_bf16_fp4 v60, v112, 1.0 op_sel:[1,0,0]
	v_cvt_scalef32_pk_bf16_fp4 v62, v112, 1.0 op_sel:[0,1,0]
	v_cvt_scalef32_pk_bf16_fp4 v80, v112, 1.0 op_sel:[1,1,0]
	v_dot2_f32_bf16 v82, v58, v6, 0
	v_dot2_f32_bf16 v58, v60, v4, 0
	v_dot2_f32_bf16 v82, v62, v10, v82
	s_add_i32 s12, s28, -4
	v_dot2_f32_bf16 v58, v80, v8, v58
	v_cvt_scalef32_pk_bf16_fp4 v60, v113, 1.0
	v_cvt_scalef32_pk_bf16_fp4 v62, v113, 1.0 op_sel:[1,0,0]
	v_cvt_scalef32_pk_bf16_fp4 v80, v113, 1.0 op_sel:[0,1,0]
	v_cvt_scalef32_pk_bf16_fp4 v112, v113, 1.0 op_sel:[1,1,0]
	v_readlane_b32 s12, v46, s12
	v_dot2_f32_bf16 v82, v60, v14, v82
	v_dot2_f32_bf16 v58, v62, v12, v58
	s_lshr_b32 s12, s12, 7
	v_dot2_f32_bf16 v82, v80, v18, v82
	v_dot2_f32_bf16 v58, v112, v16, v58
	v_cvt_scalef32_pk_bf16_fp4 v60, v114, 1.0
	v_cvt_scalef32_pk_bf16_fp4 v62, v114, 1.0 op_sel:[1,0,0]
	v_cvt_scalef32_pk_bf16_fp4 v80, v114, 1.0 op_sel:[0,1,0]
	v_cvt_scalef32_pk_bf16_fp4 v112, v114, 1.0 op_sel:[1,1,0]
	s_mov_b32 s13, s86
	v_dot2_f32_bf16 v82, v60, v22, v82
	v_dot2_f32_bf16 v58, v62, v20, v58
	s_lshl_b64 s[12:13], s[12:13], 10
	v_dot2_f32_bf16 v82, v80, v26, v82
	v_dot2_f32_bf16 v58, v112, v24, v58
	v_cvt_scalef32_pk_bf16_fp4 v60, v115, 1.0
	v_cvt_scalef32_pk_bf16_fp4 v62, v115, 1.0 op_sel:[1,0,0]
	v_cvt_scalef32_pk_bf16_fp4 v80, v115, 1.0 op_sel:[0,1,0]
	v_cvt_scalef32_pk_bf16_fp4 v112, v115, 1.0 op_sel:[1,1,0]
	s_nop 0
	v_dot2_f32_bf16 v82, v60, v30, v82
	v_dot2_f32_bf16 v58, v62, v28, v58
	s_nop 0
	v_dot2_f32_bf16 v82, v80, v36, v82
	v_dot2_f32_bf16 v58, v112, v34, v58
	s_nop 0
	s_nop 2
	v_add_f32_e32 v132, v82, v58
	v_lshl_add_u64 v[58:59], v[40:41], 0, s[12:13]
	global_load_dwordx4 v[112:115], v[58:59], off
	s_waitcnt vmcnt(15)
; #define P4_FOR16(M) M(0) M(1) M(2) M(3) M(4) M(5) M(6) M(7) M(8) M(9) M(10) M(11) M(12) M(13) M(14) M(15)
; #define P4_U(i) { P4_DOT(b##i, part[i]); const int nk_ = __builtin_amdgcn_readlane(ksel, nb + i); P4_LOAD(b##i, Ug, nk_); }
; #define P4_U(i) { P4_DOT(b##i, part[i]); const int nk_ = __builtin_amdgcn_readlane(kn, i); P4_LOAD(b##i, nbase, nk_); }
; __device__ __forceinline__ void peer_gather_f4p(const float* X, const int* __restrict__ IDX, const float* __restrict__ G, ...
;     ...
; #pragma unroll 1
;         for (int bt = 0; bt < 7; ++bt) {
;             const int ksel = (bt + 1 < 4) ? k0 : k1;
;             const int nb = (16 * (bt + 1)) & 63;
;     ...
;             P4_FOR16(P4_U)
;     ...
;             P4_RED(bt);
	v_cvt_scalef32_pk_bf16_fp4 v58, v116, 1.0
	v_cvt_scalef32_pk_bf16_fp4 v60, v116, 1.0 op_sel:[1,0,0]
	v_cvt_scalef32_pk_bf16_fp4 v62, v116, 1.0 op_sel:[0,1,0]
	v_cvt_scalef32_pk_bf16_fp4 v80, v116, 1.0 op_sel:[1,1,0]
	v_dot2_f32_bf16 v82, v58, v6, 0
	v_dot2_f32_bf16 v58, v60, v4, 0
	v_dot2_f32_bf16 v82, v62, v10, v82
	s_add_i32 s12, s28, -3
	v_dot2_f32_bf16 v58, v80, v8, v58
	v_cvt_scalef32_pk_bf16_fp4 v60, v117, 1.0
	v_cvt_scalef32_pk_bf16_fp4 v62, v117, 1.0 op_sel:[1,0,0]
	v_cvt_scalef32_pk_bf16_fp4 v80, v117, 1.0 op_sel:[0,1,0]
	v_cvt_scalef32_pk_bf16_fp4 v116, v117, 1.0 op_sel:[1,1,0]
	v_readlane_b32 s12, v46, s12
	v_dot2_f32_bf16 v82, v60, v14, v82
	v_dot2_f32_bf16 v58, v62, v12, v58
	s_lshr_b32 s12, s12, 7
	v_dot2_f32_bf16 v82, v80, v18, v82
	v_dot2_f32_bf16 v58, v116, v16, v58
	v_cvt_scalef32_pk_bf16_fp4 v60, v118, 1.0
	v_cvt_scalef32_pk_bf16_fp4 v62, v118, 1.0 op_sel:[1,0,0]
	v_cvt_scalef32_pk_bf16_fp4 v80, v118, 1.0 op_sel:[0,1,0]
	v_cvt_scalef32_pk_bf16_fp4 v116, v118, 1.0 op_sel:[1,1,0]
	s_mov_b32 s13, s86
	v_dot2_f32_bf16 v82, v60, v22, v82
	v_dot2_f32_bf16 v58, v62, v20, v58
	s_lshl_b64 s[12:13], s[12:13], 10
	v_dot2_f32_bf16 v82, v80, v26, v82
	v_dot2_f32_bf16 v58, v116, v24, v58
	v_cvt_scalef32_pk_bf16_fp4 v60, v119, 1.0
	v_cvt_scalef32_pk_bf16_fp4 v62, v119, 1.0 op_sel:[1,0,0]
	v_cvt_scalef32_pk_bf16_fp4 v80, v119, 1.0 op_sel:[0,1,0]
	v_cvt_scalef32_pk_bf16_fp4 v116, v119, 1.0 op_sel:[1,1,0]
	s_nop 0
	v_dot2_f32_bf16 v82, v60, v30, v82
	v_dot2_f32_bf16 v58, v62, v28, v58
	s_nop 0
	v_dot2_f32_bf16 v82, v80, v36, v82
	v_dot2_f32_bf16 v58, v116, v34, v58
	s_nop 0
	s_nop 2
	v_add_f32_e32 v133, v82, v58
	v_lshl_add_u64 v[58:59], v[40:41], 0, s[12:13]
	global_load_dwordx4 v[116:119], v[58:59], off
	s_waitcnt vmcnt(15)
	v_cvt_scalef32_pk_bf16_fp4 v58, v120, 1.0
	v_cvt_scalef32_pk_bf16_fp4 v60, v120, 1.0 op_sel:[1,0,0]
	v_cvt_scalef32_pk_bf16_fp4 v62, v120, 1.0 op_sel:[0,1,0]
	v_cvt_scalef32_pk_bf16_fp4 v80, v120, 1.0 op_sel:[1,1,0]
	v_dot2_f32_bf16 v82, v58, v6, 0
	v_dot2_f32_bf16 v58, v60, v4, 0
	v_dot2_f32_bf16 v82, v62, v10, v82
	s_add_i32 s12, s28, -2
	v_dot2_f32_bf16 v58, v80, v8, v58
	v_cvt_scalef32_pk_bf16_fp4 v60, v121, 1.0
	v_cvt_scalef32_pk_bf16_fp4 v62, v121, 1.0 op_sel:[1,0,0]
	v_cvt_scalef32_pk_bf16_fp4 v80, v121, 1.0 op_sel:[0,1,0]
	v_cvt_scalef32_pk_bf16_fp4 v120, v121, 1.0 op_sel:[1,1,0]
	v_readlane_b32 s12, v46, s12
	v_dot2_f32_bf16 v82, v60, v14, v82
	v_dot2_f32_bf16 v58, v62, v12, v58
	s_lshr_b32 s12, s12, 7
	v_dot2_f32_bf16 v82, v80, v18, v82
	v_dot2_f32_bf16 v58, v120, v16, v58
	v_cvt_scalef32_pk_bf16_fp4 v60, v122, 1.0
	v_cvt_scalef32_pk_bf16_fp4 v62, v122, 1.0 op_sel:[1,0,0]
	v_cvt_scalef32_pk_bf16_fp4 v80, v122, 1.0 op_sel:[0,1,0]
	v_cvt_scalef32_pk_bf16_fp4 v120, v122, 1.0 op_sel:[1,1,0]
	s_mov_b32 s13, s86
	v_dot2_f32_bf16 v82, v60, v22, v82
	v_dot2_f32_bf16 v58, v62, v20, v58
	s_lshl_b64 s[12:13], s[12:13], 10
	v_dot2_f32_bf16 v82, v80, v26, v82
	v_dot2_f32_bf16 v58, v120, v24, v58
	v_cvt_scalef32_pk_bf16_fp4 v60, v123, 1.0
	v_cvt_scalef32_pk_bf16_fp4 v62, v123, 1.0 op_sel:[1,0,0]
	v_cvt_scalef32_pk_bf16_fp4 v80, v123, 1.0 op_sel:[0,1,0]
	v_cvt_scalef32_pk_bf16_fp4 v120, v123, 1.0 op_sel:[1,1,0]
	s_nop 0
	v_dot2_f32_bf16 v82, v60, v30, v82
	v_dot2_f32_bf16 v58, v62, v28, v58
	s_nop 0
	v_dot2_f32_bf16 v82, v80, v36, v82
	v_dot2_f32_bf16 v58, v120, v34, v58
	s_nop 0
	s_nop 2
	v_add_f32_e32 v134, v82, v58
	v_lshl_add_u64 v[58:59], v[40:41], 0, s[12:13]
	global_load_dwordx4 v[120:123], v[58:59], off
	s_waitcnt vmcnt(15)
	v_cvt_scalef32_pk_bf16_fp4 v58, v124, 1.0
	v_cvt_scalef32_pk_bf16_fp4 v60, v124, 1.0 op_sel:[1,0,0]
	v_cvt_scalef32_pk_bf16_fp4 v62, v124, 1.0 op_sel:[0,1,0]
	v_cvt_scalef32_pk_bf16_fp4 v80, v124, 1.0 op_sel:[1,1,0]
	v_dot2_f32_bf16 v82, v58, v6, 0
	v_dot2_f32_bf16 v58, v60, v4, 0
	v_dot2_f32_bf16 v82, v62, v10, v82
	s_add_i32 s12, s28, -1
	v_dot2_f32_bf16 v58, v80, v8, v58
	v_cvt_scalef32_pk_bf16_fp4 v60, v125, 1.0
	v_cvt_scalef32_pk_bf16_fp4 v62, v125, 1.0 op_sel:[1,0,0]
	v_cvt_scalef32_pk_bf16_fp4 v80, v125, 1.0 op_sel:[0,1,0]
	v_cvt_scalef32_pk_bf16_fp4 v124, v125, 1.0 op_sel:[1,1,0]
	v_readlane_b32 s12, v46, s12
	v_dot2_f32_bf16 v82, v60, v14, v82
	v_dot2_f32_bf16 v58, v62, v12, v58
	s_lshr_b32 s12, s12, 7
	v_dot2_f32_bf16 v82, v80, v18, v82
	v_dot2_f32_bf16 v58, v124, v16, v58
	v_cvt_scalef32_pk_bf16_fp4 v60, v126, 1.0
	v_cvt_scalef32_pk_bf16_fp4 v62, v126, 1.0 op_sel:[1,0,0]
	v_cvt_scalef32_pk_bf16_fp4 v80, v126, 1.0 op_sel:[0,1,0]
	v_cvt_scalef32_pk_bf16_fp4 v124, v126, 1.0 op_sel:[1,1,0]
	s_mov_b32 s13, s86
	v_dot2_f32_bf16 v82, v60, v22, v82
	v_dot2_f32_bf16 v58, v62, v20, v58
	s_lshl_b64 s[12:13], s[12:13], 10
	v_dot2_f32_bf16 v82, v80, v26, v82
	v_dot2_f32_bf16 v58, v124, v24, v58
	v_cvt_scalef32_pk_bf16_fp4 v60, v127, 1.0
	v_cvt_scalef32_pk_bf16_fp4 v62, v127, 1.0 op_sel:[1,0,0]
	v_cvt_scalef32_pk_bf16_fp4 v80, v127, 1.0 op_sel:[0,1,0]
	v_cvt_scalef32_pk_bf16_fp4 v124, v127, 1.0 op_sel:[1,1,0]
	s_nop 0
	v_dot2_f32_bf16 v82, v60, v30, v82
	v_dot2_f32_bf16 v58, v62, v28, v58
	s_nop 0
	v_dot2_f32_bf16 v82, v80, v36, v82
	v_dot2_f32_bf16 v58, v124, v34, v58
	s_nop 0
	s_nop 2
	v_add_f32_e32 v135, v82, v58
	v_lshl_add_u64 v[58:59], v[40:41], 0, s[12:13]
	global_load_dwordx4 v[124:127], v[58:59], off
	s_waitcnt vmcnt(15)
; __device__ __forceinline__ float gelu_tanh(float h) {
;     return 0.5f * h * (1.f + tanhf(0.7978845608028654f * (h + 0.044715f * h * h * h)));
; }
	v_cvt_scalef32_pk_bf16_fp4 v58, v128, 1.0
	v_cvt_scalef32_pk_bf16_fp4 v60, v128, 1.0 op_sel:[1,0,0]
	v_cvt_scalef32_pk_bf16_fp4 v62, v128, 1.0 op_sel:[0,1,0]
	v_cvt_scalef32_pk_bf16_fp4 v80, v128, 1.0 op_sel:[1,1,0]
	v_readlane_b32 s12, v46, s28
	v_dot2_f32_bf16 v82, v58, v6, 0
	v_dot2c_f32_bf16_e32 v42, v60, v4
	s_lshr_b32 s12, s12, 7
	v_dot2_f32_bf16 v82, v62, v10, v82
	v_dot2c_f32_bf16_e32 v42, v80, v8
	v_cvt_scalef32_pk_bf16_fp4 v58, v129, 1.0
	v_cvt_scalef32_pk_bf16_fp4 v60, v129, 1.0 op_sel:[1,0,0]
	v_cvt_scalef32_pk_bf16_fp4 v62, v129, 1.0 op_sel:[0,1,0]
	v_cvt_scalef32_pk_bf16_fp4 v80, v129, 1.0 op_sel:[1,1,0]
	s_mov_b32 s13, s86
	v_dot2_f32_bf16 v82, v58, v14, v82
	v_dot2c_f32_bf16_e32 v42, v60, v12
	s_lshl_b64 s[12:13], s[12:13], 10
	v_dot2_f32_bf16 v82, v62, v18, v82
	v_dot2c_f32_bf16_e32 v42, v80, v16
	v_cvt_scalef32_pk_bf16_fp4 v58, v130, 1.0
	v_cvt_scalef32_pk_bf16_fp4 v60, v130, 1.0 op_sel:[1,0,0]
	v_cvt_scalef32_pk_bf16_fp4 v62, v130, 1.0 op_sel:[0,1,0]
	v_cvt_scalef32_pk_bf16_fp4 v80, v130, 1.0 op_sel:[1,1,0]
	v_cndmask_b32_e64 v46, v48, v56, s[46:47]
	v_dot2_f32_bf16 v82, v58, v22, v82
	v_dot2c_f32_bf16_e32 v42, v60, v20
	ds_swizzle_b32 v46, v46 offset:swizzle(SWAP,8)
	v_dot2_f32_bf16 v82, v62, v26, v82
	v_dot2c_f32_bf16_e32 v42, v80, v24
	v_cvt_scalef32_pk_bf16_fp4 v58, v131, 1.0
	v_cvt_scalef32_pk_bf16_fp4 v60, v131, 1.0 op_sel:[1,0,0]
	v_cvt_scalef32_pk_bf16_fp4 v62, v131, 1.0 op_sel:[0,1,0]
	v_cvt_scalef32_pk_bf16_fp4 v80, v131, 1.0 op_sel:[1,1,0]
	s_nop 0
	v_dot2_f32_bf16 v82, v58, v30, v82
	v_dot2c_f32_bf16_e32 v42, v60, v28
	s_nop 0
	v_dot2_f32_bf16 v82, v62, v36, v82
	v_dot2c_f32_bf16_e32 v42, v80, v34
	s_nop 0
	s_nop 2
	v_add_f32_e32 v58, v82, v42
	v_lshl_add_u64 v[42:43], v[40:41], 0, s[12:13]
	global_load_dwordx4 v[128:131], v[42:43], off
	v_cndmask_b32_e64 v43, v47, v55, s[46:47]
	ds_swizzle_b32 v43, v43 offset:swizzle(SWAP,8)
	v_cndmask_b32_e64 v42, v55, v47, s[46:47]
	v_cndmask_b32_e64 v47, v49, v57, s[46:47]
	ds_swizzle_b32 v47, v47 offset:swizzle(SWAP,8)
	s_waitcnt lgkmcnt(1)
	v_add_f32_e32 v42, v42, v43
	v_cndmask_b32_e64 v43, v56, v48, s[46:47]
	v_cndmask_b32_e64 v48, v50, v132, s[46:47]
	v_add_f32_e32 v43, v43, v46
	v_cndmask_b32_e64 v46, v57, v49, s[46:47]
	ds_swizzle_b32 v48, v48 offset:swizzle(SWAP,8)
	v_cndmask_b32_e64 v49, v51, v133, s[46:47]
	ds_swizzle_b32 v49, v49 offset:swizzle(SWAP,8)
	s_waitcnt lgkmcnt(2)
	v_add_f32_e32 v46, v46, v47
	v_cndmask_b32_e64 v47, v132, v50, s[46:47]
	v_cndmask_b32_e64 v50, v52, v134, s[46:47]
	ds_swizzle_b32 v50, v50 offset:swizzle(SWAP,8)
	s_waitcnt lgkmcnt(2)
	v_add_f32_e32 v47, v47, v48
	v_cndmask_b32_e64 v48, v133, v51, s[46:47]
	v_cndmask_b32_e64 v51, v53, v135, s[46:47]
	s_waitcnt lgkmcnt(1)
	v_add_f32_e32 v48, v48, v49
	v_cndmask_b32_e64 v49, v134, v52, s[46:47]
	ds_swizzle_b32 v51, v51 offset:swizzle(SWAP,8)
	v_cndmask_b32_e64 v52, v54, v58, s[46:47]
	ds_swizzle_b32 v52, v52 offset:swizzle(SWAP,8)
	s_waitcnt lgkmcnt(2)
	v_add_f32_e32 v49, v49, v50
	v_cndmask_b32_e64 v50, v135, v53, s[46:47]
	s_waitcnt lgkmcnt(1)
	v_add_f32_e32 v50, v50, v51
	v_cndmask_b32_e64 v51, v58, v54, s[46:47]
	s_waitcnt lgkmcnt(0)
	v_add_f32_e32 v51, v51, v52
	v_cndmask_b32_e64 v53, v42, v48, s[44:45]
	v_cndmask_b32_e64 v42, v48, v42, s[44:45]
	v_cndmask_b32_e64 v48, v49, v43, s[44:45]
	v_cndmask_b32_e64 v43, v43, v49, s[44:45]
	v_cndmask_b32_e64 v49, v46, v50, s[44:45]
	v_cndmask_b32_e64 v52, v47, v51, s[44:45]
	ds_swizzle_b32 v53, v53 offset:swizzle(SWAP,4)
	ds_swizzle_b32 v43, v43 offset:swizzle(SWAP,4)
	ds_swizzle_b32 v49, v49 offset:swizzle(SWAP,4)
	ds_swizzle_b32 v52, v52 offset:swizzle(SWAP,4)
	v_cndmask_b32_e64 v46, v50, v46, s[44:45]
	v_cndmask_b32_e64 v47, v51, v47, s[44:45]
	s_waitcnt lgkmcnt(3)
	v_add_f32_e32 v42, v42, v53
	s_waitcnt lgkmcnt(2)
	v_add_f32_e32 v43, v48, v43
	s_waitcnt lgkmcnt(1)
	v_add_f32_e32 v46, v46, v49
	s_waitcnt lgkmcnt(0)
	v_add_f32_e32 v47, v47, v52
	v_cndmask_b32_e64 v48, v42, v46, s[42:43]
	v_cndmask_b32_e64 v49, v43, v47, s[42:43]
	ds_swizzle_b32 v48, v48 offset:swizzle(SWAP,2)
	ds_swizzle_b32 v49, v49 offset:swizzle(SWAP,2)
	v_cndmask_b32_e64 v42, v46, v42, s[42:43]
	v_cndmask_b32_e64 v43, v47, v43, s[42:43]
	s_waitcnt lgkmcnt(1)
	v_add_f32_e32 v42, v42, v48
	s_waitcnt lgkmcnt(0)
	v_add_f32_e32 v43, v43, v49
	v_cndmask_b32_e64 v46, v42, v43, s[40:41]
	ds_swizzle_b32 v46, v46 offset:swizzle(SWAP,1)
	v_cndmask_b32_e64 v42, v43, v42, s[40:41]
	s_waitcnt lgkmcnt(0)
	v_add_f32_e32 v42, v42, v46
	ds_swizzle_b32 v43, v42 offset:swizzle(SWAP,16)
	s_waitcnt lgkmcnt(0)
	v_add_f32_e32 v46, v42, v43
	ds_read2st64_b32 v[42:43], v45 offset1:8
	v_mov_b32_e32 v47, v46
	s_nop 1
	v_permlane32_swap_b32_e32 v46, v47
	v_add_f32_e32 v46, v46, v47
	s_waitcnt lgkmcnt(0)
	v_mul_f32_e32 v42, v42, v46
	v_mul_f32_e32 v46, 0x3d372713, v42
	v_mul_f32_e32 v46, v42, v46
	v_fma_f32 v46, v42, v46, v42
	v_mul_f32_e32 v46, 0x3f4c422a, v46
	v_cmp_nlt_f32_e64 s[12:13], |v46|, s25
	s_and_saveexec_b64 s[48:49], s[12:13]
	s_xor_b64 s[12:13], exec, s[48:49]
	s_cbranch_execz .LBB0_1233
	v_add_f32_e64 v47, |v46|, |v46|
	v_mul_f32_e32 v48, 0x3fb8aa3b, v47
	v_rndne_f32_e32 v49, v48
	v_sub_f32_e32 v50, v48, v49
	v_fma_f32 v48, v47, s70, -v48
	v_fmac_f32_e32 v48, 0x32a5705f, v47
	v_add_f32_e32 v48, v50, v48
	v_cvt_i32_f32_e32 v49, v49
	v_exp_f32_e32 v48, v48
	v_cmp_ngt_f32_e64 s[48:49], s67, v47
	v_ldexp_f32 v48, v48, v49
	s_nop 0
	v_cndmask_b32_e64 v48, 0, v48, s[48:49]
	v_cmp_nlt_f32_e64 s[48:49], s68, v47
	s_nop 1
	v_cndmask_b32_e64 v47, v205, v48, s[48:49]
	v_add_f32_e32 v47, 1.0, v47
	v_rcp_f32_e32 v47, v47
	s_nop 0
	v_fma_f32 v47, v47, -2.0, 1.0
	s_andn2_saveexec_b64 s[12:13], s[12:13]
	s_cbranch_execnz .LBB0_1234

; #define GAS __attribute__((address_space(1)))
; #define P4_FOR16(M) M(0) M(1) M(2) M(3) M(4) M(5) M(6) M(7) M(8) M(9) M(10) M(11) M(12) M(13) M(14) M(15)
; #define P4_U(i) { P4_DOT(b##i, part[i]); const int nk_ = __builtin_amdgcn_readlane(ksel, nb + i); P4_LOAD(b##i, Ug, nk_); }
; #define P4_U(i) { P4_DOT(b##i, part[i]); const int nk_ = __builtin_amdgcn_readlane(kn, i); P4_LOAD(b##i, nbase, nk_); }
; __device__ __forceinline__ void peer_gather_f4p(const float* X, const int* __restrict__ IDX, const float* __restrict__ G, ...
;     ...
;         const int k0 = keys[kt * 128 + lane], k1 = keys[kt * 128 + 64 + lane];
;         const int kn = keys[((kt + 1) & 3) * 128 + lane];
;         const GAS unsigned char* nbase = (kt < 3) ? Ug : Vg;
;         float part[16];
;     ...
; #pragma unroll 1
;         for (int bt = 0; bt < 7; ++bt) {
;             const int ksel = (bt + 1 < 4) ? k0 : k1;
;             const int nb = (16 * (bt + 1)) & 63;
;     ...
;             P4_FOR16(P4_U)
;     ...
;             P4_RED(bt);
;         }
;         {
;     ...
;             P4_FOR16(P4_U)
.LBB0_1236:
	s_mov_b32 s87, s86
	s_waitcnt vmcnt(15)
	v_cvt_scalef32_pk_bf16_fp4 v42, v64, 1.0
	v_or_b32_e32 v40, s27, v44
	v_cvt_scalef32_pk_bf16_fp4 v44, v64, 1.0 op_sel:[1,0,0]
	v_cvt_scalef32_pk_bf16_fp4 v46, v64, 1.0 op_sel:[0,1,0]
	v_cvt_scalef32_pk_bf16_fp4 v48, v64, 1.0 op_sel:[1,1,0]
	v_dot2_f32_bf16 v50, v42, v6, 0
	v_dot2_f32_bf16 v42, v44, v4, 0
	v_dot2_f32_bf16 v50, v46, v10, v50
	s_cmp_eq_u32 s26, 3
	v_dot2_f32_bf16 v42, v48, v8, v42
	v_cvt_scalef32_pk_bf16_fp4 v44, v65, 1.0
	v_cvt_scalef32_pk_bf16_fp4 v46, v65, 1.0 op_sel:[1,0,0]
	v_cvt_scalef32_pk_bf16_fp4 v48, v65, 1.0 op_sel:[0,1,0]
	v_cvt_scalef32_pk_bf16_fp4 v52, v65, 1.0 op_sel:[1,1,0]
	v_readlane_b32 s26, v2, 0
	v_dot2_f32_bf16 v50, v44, v14, v50
	v_dot2_f32_bf16 v42, v46, v12, v42
	s_cselect_b32 s12, s53, s51
	v_dot2_f32_bf16 v50, v48, v18, v50
	v_dot2_f32_bf16 v42, v52, v16, v42
	v_cvt_scalef32_pk_bf16_fp4 v44, v66, 1.0
	v_cvt_scalef32_pk_bf16_fp4 v46, v66, 1.0 op_sel:[1,0,0]
	v_cvt_scalef32_pk_bf16_fp4 v48, v66, 1.0 op_sel:[0,1,0]
	v_cvt_scalef32_pk_bf16_fp4 v52, v66, 1.0 op_sel:[1,1,0]
	s_cselect_b32 s13, s52, s50
	v_dot2_f32_bf16 v50, v44, v22, v50
	v_dot2_f32_bf16 v42, v46, v20, v42
	s_lshr_b32 s26, s26, 7
	v_dot2_f32_bf16 v50, v48, v26, v50
	v_dot2_f32_bf16 v42, v52, v24, v42
	s_mov_b32 s27, s86
	v_cvt_scalef32_pk_bf16_fp4 v44, v67, 1.0
	v_cvt_scalef32_pk_bf16_fp4 v46, v67, 1.0 op_sel:[1,0,0]
	v_cvt_scalef32_pk_bf16_fp4 v48, v67, 1.0 op_sel:[0,1,0]
	v_cvt_scalef32_pk_bf16_fp4 v52, v67, 1.0 op_sel:[1,1,0]
	s_lshl_b64 s[26:27], s[26:27], 10
	v_dot2_f32_bf16 v50, v44, v30, v50
	v_dot2_f32_bf16 v42, v46, v28, v42
	s_add_u32 s26, s13, s26
	v_dot2_f32_bf16 v50, v48, v36, v50
	v_dot2_f32_bf16 v42, v52, v34, v42
	s_addc_u32 s27, s12, s27
	s_nop 2
	v_add_f32_e32 v41, v50, v42
	v_lshl_add_u64 v[42:43], s[26:27], 0, v[32:33]
	global_load_dwordx4 v[64:67], v[42:43], off
	s_waitcnt vmcnt(15)
	v_cvt_scalef32_pk_bf16_fp4 v42, v68, 1.0
	v_cvt_scalef32_pk_bf16_fp4 v44, v68, 1.0 op_sel:[1,0,0]
	v_cvt_scalef32_pk_bf16_fp4 v46, v68, 1.0 op_sel:[0,1,0]
	v_cvt_scalef32_pk_bf16_fp4 v48, v68, 1.0 op_sel:[1,1,0]
	v_dot2_f32_bf16 v50, v42, v6, 0
	v_dot2_f32_bf16 v42, v44, v4, 0
	v_dot2_f32_bf16 v50, v46, v10, v50
	v_readlane_b32 s26, v2, 1
	v_dot2_f32_bf16 v42, v48, v8, v42
	v_cvt_scalef32_pk_bf16_fp4 v44, v69, 1.0
	v_cvt_scalef32_pk_bf16_fp4 v46, v69, 1.0 op_sel:[1,0,0]
	v_cvt_scalef32_pk_bf16_fp4 v48, v69, 1.0 op_sel:[0,1,0]
	v_cvt_scalef32_pk_bf16_fp4 v52, v69, 1.0 op_sel:[1,1,0]
	s_lshr_b32 s26, s26, 7
	v_dot2_f32_bf16 v50, v44, v14, v50
	v_dot2_f32_bf16 v42, v46, v12, v42
	s_mov_b32 s27, s86
	v_dot2_f32_bf16 v50, v48, v18, v50
	v_dot2_f32_bf16 v42, v52, v16, v42
	v_cvt_scalef32_pk_bf16_fp4 v44, v70, 1.0
	v_cvt_scalef32_pk_bf16_fp4 v46, v70, 1.0 op_sel:[1,0,0]
	v_cvt_scalef32_pk_bf16_fp4 v48, v70, 1.0 op_sel:[0,1,0]
	v_cvt_scalef32_pk_bf16_fp4 v52, v70, 1.0 op_sel:[1,1,0]
	s_lshl_b64 s[26:27], s[26:27], 10
	v_dot2_f32_bf16 v50, v44, v22, v50
	v_dot2_f32_bf16 v42, v46, v20, v42
	s_add_u32 s26, s13, s26
	v_dot2_f32_bf16 v50, v48, v26, v50
	v_dot2_f32_bf16 v42, v52, v24, v42
	v_cvt_scalef32_pk_bf16_fp4 v44, v71, 1.0
	v_cvt_scalef32_pk_bf16_fp4 v46, v71, 1.0 op_sel:[1,0,0]
	v_cvt_scalef32_pk_bf16_fp4 v48, v71, 1.0 op_sel:[0,1,0]
	v_cvt_scalef32_pk_bf16_fp4 v52, v71, 1.0 op_sel:[1,1,0]
	s_addc_u32 s27, s12, s27
	v_dot2_f32_bf16 v50, v44, v30, v50
	v_dot2_f32_bf16 v42, v46, v28, v42
	v_mov_b32_e32 v38, 0
	v_dot2_f32_bf16 v50, v48, v36, v50
	v_dot2_f32_bf16 v42, v52, v34, v42
	s_nop 2
	v_add_f32_e32 v42, v50, v42
	v_lshl_add_u64 v[44:45], s[26:27], 0, v[32:33]
	global_load_dwordx4 v[68:71], v[44:45], off
	s_waitcnt vmcnt(15)
	v_cvt_scalef32_pk_bf16_fp4 v44, v72, 1.0
	v_cvt_scalef32_pk_bf16_fp4 v46, v72, 1.0 op_sel:[1,0,0]
	v_cvt_scalef32_pk_bf16_fp4 v48, v72, 1.0 op_sel:[0,1,0]
	v_cvt_scalef32_pk_bf16_fp4 v50, v72, 1.0 op_sel:[1,1,0]
	v_readlane_b32 s26, v2, 2
	v_dot2_f32_bf16 v52, v44, v6, 0
	v_dot2_f32_bf16 v44, v46, v4, 0
	v_dot2_f32_bf16 v52, v48, v10, v52
	s_lshr_b32 s26, s26, 7
	v_dot2_f32_bf16 v44, v50, v8, v44
	v_cvt_scalef32_pk_bf16_fp4 v46, v73, 1.0
	v_cvt_scalef32_pk_bf16_fp4 v48, v73, 1.0 op_sel:[1,0,0]
	v_cvt_scalef32_pk_bf16_fp4 v50, v73, 1.0 op_sel:[0,1,0]
	v_cvt_scalef32_pk_bf16_fp4 v54, v73, 1.0 op_sel:[1,1,0]
	s_mov_b32 s27, s86
	v_dot2_f32_bf16 v52, v46, v14, v52
	v_dot2_f32_bf16 v44, v48, v12, v44
	s_lshl_b64 s[26:27], s[26:27], 10
	v_dot2_f32_bf16 v52, v50, v18, v52
	v_dot2_f32_bf16 v44, v54, v16, v44
	v_cvt_scalef32_pk_bf16_fp4 v46, v74, 1.0
	v_cvt_scalef32_pk_bf16_fp4 v48, v74, 1.0 op_sel:[1,0,0]
	v_cvt_scalef32_pk_bf16_fp4 v50, v74, 1.0 op_sel:[0,1,0]
	v_cvt_scalef32_pk_bf16_fp4 v54, v74, 1.0 op_sel:[1,1,0]
	s_add_u32 s26, s13, s26
	v_dot2_f32_bf16 v52, v46, v22, v52
	v_dot2_f32_bf16 v44, v48, v20, v44
	s_addc_u32 s27, s12, s27
	v_dot2_f32_bf16 v52, v50, v26, v52
	v_dot2_f32_bf16 v44, v54, v24, v44
	v_cvt_scalef32_pk_bf16_fp4 v46, v75, 1.0
	v_cvt_scalef32_pk_bf16_fp4 v48, v75, 1.0 op_sel:[1,0,0]
	v_cvt_scalef32_pk_bf16_fp4 v50, v75, 1.0 op_sel:[0,1,0]
	v_cvt_scalef32_pk_bf16_fp4 v54, v75, 1.0 op_sel:[1,1,0]
	s_nop 0
	v_dot2_f32_bf16 v52, v46, v30, v52
	v_dot2_f32_bf16 v44, v48, v28, v44
	s_nop 0
	v_dot2_f32_bf16 v52, v50, v36, v52
	v_dot2_f32_bf16 v44, v54, v34, v44
	s_nop 0
	s_nop 2
	v_add_f32_e32 v43, v52, v44
	v_lshl_add_u64 v[44:45], s[26:27], 0, v[32:33]
	global_load_dwordx4 v[72:75], v[44:45], off
	s_waitcnt vmcnt(15)
; #define P4_FOR16(M) M(0) M(1) M(2) M(3) M(4) M(5) M(6) M(7) M(8) M(9) M(10) M(11) M(12) M(13) M(14) M(15)
; #define P4_U(i) { P4_DOT(b##i, part[i]); const int nk_ = __builtin_amdgcn_readlane(ksel, nb + i); P4_LOAD(b##i, Ug, nk_); }
; #define P4_U(i) { P4_DOT(b##i, part[i]); const int nk_ = __builtin_amdgcn_readlane(kn, i); P4_LOAD(b##i, nbase, nk_); }
; __device__ __forceinline__ void peer_gather_f4p(const float* X, const int* __restrict__ IDX, const float* __restrict__ G, ...
;     ...
;         {
;     ...
;             P4_FOR16(P4_U)
	v_cvt_scalef32_pk_bf16_fp4 v44, v76, 1.0
	v_cvt_scalef32_pk_bf16_fp4 v46, v76, 1.0 op_sel:[1,0,0]
	v_cvt_scalef32_pk_bf16_fp4 v48, v76, 1.0 op_sel:[0,1,0]
	v_cvt_scalef32_pk_bf16_fp4 v50, v76, 1.0 op_sel:[1,1,0]
	v_dot2_f32_bf16 v52, v44, v6, 0
	v_dot2_f32_bf16 v44, v46, v4, 0
	v_dot2_f32_bf16 v52, v48, v10, v52
	v_readlane_b32 s26, v2, 3
	v_dot2_f32_bf16 v44, v50, v8, v44
	v_cvt_scalef32_pk_bf16_fp4 v46, v77, 1.0
	v_cvt_scalef32_pk_bf16_fp4 v48, v77, 1.0 op_sel:[1,0,0]
	v_cvt_scalef32_pk_bf16_fp4 v50, v77, 1.0 op_sel:[0,1,0]
	v_cvt_scalef32_pk_bf16_fp4 v54, v77, 1.0 op_sel:[1,1,0]
	s_lshr_b32 s26, s26, 7
	v_dot2_f32_bf16 v52, v46, v14, v52
	v_dot2_f32_bf16 v44, v48, v12, v44
	s_mov_b32 s27, s86
	v_dot2_f32_bf16 v52, v50, v18, v52
	v_dot2_f32_bf16 v44, v54, v16, v44
	v_cvt_scalef32_pk_bf16_fp4 v46, v78, 1.0
	v_cvt_scalef32_pk_bf16_fp4 v48, v78, 1.0 op_sel:[1,0,0]
	v_cvt_scalef32_pk_bf16_fp4 v50, v78, 1.0 op_sel:[0,1,0]
	v_cvt_scalef32_pk_bf16_fp4 v54, v78, 1.0 op_sel:[1,1,0]
	s_lshl_b64 s[26:27], s[26:27], 10
	v_dot2_f32_bf16 v52, v46, v22, v52
	v_dot2_f32_bf16 v44, v48, v20, v44
	s_add_u32 s26, s13, s26
	v_dot2_f32_bf16 v52, v50, v26, v52
	v_dot2_f32_bf16 v44, v54, v24, v44
	v_cvt_scalef32_pk_bf16_fp4 v46, v79, 1.0
	v_cvt_scalef32_pk_bf16_fp4 v48, v79, 1.0 op_sel:[1,0,0]
	v_cvt_scalef32_pk_bf16_fp4 v50, v79, 1.0 op_sel:[0,1,0]
	v_cvt_scalef32_pk_bf16_fp4 v54, v79, 1.0 op_sel:[1,1,0]
	s_addc_u32 s27, s12, s27
	v_dot2_f32_bf16 v52, v46, v30, v52
	v_dot2_f32_bf16 v44, v48, v28, v44
	s_nop 0
	v_dot2_f32_bf16 v52, v50, v36, v52
	v_dot2_f32_bf16 v44, v54, v34, v44
	s_nop 2
	v_add_f32_e32 v44, v52, v44
	v_lshl_add_u64 v[46:47], s[26:27], 0, v[32:33]
	global_load_dwordx4 v[76:79], v[46:47], off
	s_waitcnt vmcnt(15)
	v_cvt_scalef32_pk_bf16_fp4 v46, v84, 1.0
	v_cvt_scalef32_pk_bf16_fp4 v48, v84, 1.0 op_sel:[1,0,0]
	v_cvt_scalef32_pk_bf16_fp4 v50, v84, 1.0 op_sel:[0,1,0]
	v_cvt_scalef32_pk_bf16_fp4 v52, v84, 1.0 op_sel:[1,1,0]
	v_readlane_b32 s26, v2, 4
	v_dot2_f32_bf16 v54, v46, v6, 0
	v_dot2_f32_bf16 v46, v48, v4, 0
	v_dot2_f32_bf16 v54, v50, v10, v54
	s_lshr_b32 s26, s26, 7
	v_dot2_f32_bf16 v46, v52, v8, v46
	v_cvt_scalef32_pk_bf16_fp4 v48, v85, 1.0
	v_cvt_scalef32_pk_bf16_fp4 v50, v85, 1.0 op_sel:[1,0,0]
	v_cvt_scalef32_pk_bf16_fp4 v52, v85, 1.0 op_sel:[0,1,0]
	v_cvt_scalef32_pk_bf16_fp4 v56, v85, 1.0 op_sel:[1,1,0]
	s_mov_b32 s27, s86
	v_dot2_f32_bf16 v54, v48, v14, v54
	v_dot2_f32_bf16 v46, v50, v12, v46
	s_lshl_b64 s[26:27], s[26:27], 10
	v_dot2_f32_bf16 v54, v52, v18, v54
	v_dot2_f32_bf16 v46, v56, v16, v46
	v_cvt_scalef32_pk_bf16_fp4 v48, v86, 1.0
	v_cvt_scalef32_pk_bf16_fp4 v50, v86, 1.0 op_sel:[1,0,0]
	v_cvt_scalef32_pk_bf16_fp4 v52, v86, 1.0 op_sel:[0,1,0]
	v_cvt_scalef32_pk_bf16_fp4 v56, v86, 1.0 op_sel:[1,1,0]
	s_add_u32 s26, s13, s26
	v_dot2_f32_bf16 v54, v48, v22, v54
	v_dot2_f32_bf16 v46, v50, v20, v46
	s_addc_u32 s27, s12, s27
	v_dot2_f32_bf16 v54, v52, v26, v54
	v_dot2_f32_bf16 v46, v56, v24, v46
	v_cvt_scalef32_pk_bf16_fp4 v48, v87, 1.0
	v_cvt_scalef32_pk_bf16_fp4 v50, v87, 1.0 op_sel:[1,0,0]
	v_cvt_scalef32_pk_bf16_fp4 v52, v87, 1.0 op_sel:[0,1,0]
	v_cvt_scalef32_pk_bf16_fp4 v56, v87, 1.0 op_sel:[1,1,0]
	s_nop 0
	v_dot2_f32_bf16 v54, v48, v30, v54
	v_dot2_f32_bf16 v46, v50, v28, v46
	s_nop 0
	v_dot2_f32_bf16 v54, v52, v36, v54
	v_dot2_f32_bf16 v46, v56, v34, v46
	s_nop 0
	s_nop 2
	v_add_f32_e32 v45, v54, v46
	v_lshl_add_u64 v[46:47], s[26:27], 0, v[32:33]
	global_load_dwordx4 v[84:87], v[46:47], off
	s_waitcnt vmcnt(15)
	v_cvt_scalef32_pk_bf16_fp4 v46, v88, 1.0
	v_cvt_scalef32_pk_bf16_fp4 v48, v88, 1.0 op_sel:[1,0,0]
	v_cvt_scalef32_pk_bf16_fp4 v50, v88, 1.0 op_sel:[0,1,0]
	v_cvt_scalef32_pk_bf16_fp4 v52, v88, 1.0 op_sel:[1,1,0]
	v_dot2_f32_bf16 v54, v46, v6, 0
	v_dot2_f32_bf16 v46, v48, v4, 0
	v_dot2_f32_bf16 v54, v50, v10, v54
	v_readlane_b32 s26, v2, 5
	v_dot2_f32_bf16 v46, v52, v8, v46
	v_cvt_scalef32_pk_bf16_fp4 v48, v89, 1.0
	v_cvt_scalef32_pk_bf16_fp4 v50, v89, 1.0 op_sel:[1,0,0]
	v_cvt_scalef32_pk_bf16_fp4 v52, v89, 1.0 op_sel:[0,1,0]
	v_cvt_scalef32_pk_bf16_fp4 v56, v89, 1.0 op_sel:[1,1,0]
	s_lshr_b32 s26, s26, 7
	v_dot2_f32_bf16 v54, v48, v14, v54
	v_dot2_f32_bf16 v46, v50, v12, v46
	s_mov_b32 s27, s86
	v_dot2_f32_bf16 v54, v52, v18, v54
	v_dot2_f32_bf16 v46, v56, v16, v46
	v_cvt_scalef32_pk_bf16_fp4 v48, v90, 1.0
	v_cvt_scalef32_pk_bf16_fp4 v50, v90, 1.0 op_sel:[1,0,0]
	v_cvt_scalef32_pk_bf16_fp4 v52, v90, 1.0 op_sel:[0,1,0]
	v_cvt_scalef32_pk_bf16_fp4 v56, v90, 1.0 op_sel:[1,1,0]
	s_lshl_b64 s[26:27], s[26:27], 10
	v_dot2_f32_bf16 v54, v48, v22, v54
	v_dot2_f32_bf16 v46, v50, v20, v46
	s_add_u32 s26, s13, s26
	v_dot2_f32_bf16 v54, v52, v26, v54
	v_dot2_f32_bf16 v46, v56, v24, v46
	v_cvt_scalef32_pk_bf16_fp4 v48, v91, 1.0
	v_cvt_scalef32_pk_bf16_fp4 v50, v91, 1.0 op_sel:[1,0,0]
	v_cvt_scalef32_pk_bf16_fp4 v52, v91, 1.0 op_sel:[0,1,0]
	v_cvt_scalef32_pk_bf16_fp4 v56, v91, 1.0 op_sel:[1,1,0]
	s_addc_u32 s27, s12, s27
	v_dot2_f32_bf16 v54, v48, v30, v54
	v_dot2_f32_bf16 v46, v50, v28, v46
	s_nop 0
	v_dot2_f32_bf16 v54, v52, v36, v54
	v_dot2_f32_bf16 v46, v56, v34, v46
	s_nop 2
	v_add_f32_e32 v46, v54, v46
	v_lshl_add_u64 v[48:49], s[26:27], 0, v[32:33]
	global_load_dwordx4 v[88:91], v[48:49], off
	s_waitcnt vmcnt(15)
; #define P4_FOR16(M) M(0) M(1) M(2) M(3) M(4) M(5) M(6) M(7) M(8) M(9) M(10) M(11) M(12) M(13) M(14) M(15)
; #define P4_U(i) { P4_DOT(b##i, part[i]); const int nk_ = __builtin_amdgcn_readlane(ksel, nb + i); P4_LOAD(b##i, Ug, nk_); }
; #define P4_U(i) { P4_DOT(b##i, part[i]); const int nk_ = __builtin_amdgcn_readlane(kn, i); P4_LOAD(b##i, nbase, nk_); }
; __device__ __forceinline__ void peer_gather_f4p(const float* X, const int* __restrict__ IDX, const float* __restrict__ G, ...
;     ...
;         for (int bt = 0; bt < 7; ++bt) {
;             const int ksel = (bt + 1 < 4) ? k0 : k1;
;             const int nb = (16 * (bt + 1)) & 63;
;     ...
;             P4_FOR16(P4_U)
	v_cvt_scalef32_pk_bf16_fp4 v48, v92, 1.0
	v_cvt_scalef32_pk_bf16_fp4 v50, v92, 1.0 op_sel:[1,0,0]
	v_cvt_scalef32_pk_bf16_fp4 v52, v92, 1.0 op_sel:[0,1,0]
	v_cvt_scalef32_pk_bf16_fp4 v54, v92, 1.0 op_sel:[1,1,0]
	v_readlane_b32 s26, v2, 6
	v_dot2_f32_bf16 v56, v48, v6, 0
	v_dot2_f32_bf16 v48, v50, v4, 0
	v_dot2_f32_bf16 v56, v52, v10, v56
	s_lshr_b32 s26, s26, 7
	v_dot2_f32_bf16 v48, v54, v8, v48
	v_cvt_scalef32_pk_bf16_fp4 v50, v93, 1.0
	v_cvt_scalef32_pk_bf16_fp4 v52, v93, 1.0 op_sel:[1,0,0]
	v_cvt_scalef32_pk_bf16_fp4 v54, v93, 1.0 op_sel:[0,1,0]
	v_cvt_scalef32_pk_bf16_fp4 v58, v93, 1.0 op_sel:[1,1,0]
	s_mov_b32 s27, s86
	v_dot2_f32_bf16 v56, v50, v14, v56
	v_dot2_f32_bf16 v48, v52, v12, v48
	s_lshl_b64 s[26:27], s[26:27], 10
	v_dot2_f32_bf16 v56, v54, v18, v56
	v_dot2_f32_bf16 v48, v58, v16, v48
	v_cvt_scalef32_pk_bf16_fp4 v50, v94, 1.0
	v_cvt_scalef32_pk_bf16_fp4 v52, v94, 1.0 op_sel:[1,0,0]
	v_cvt_scalef32_pk_bf16_fp4 v54, v94, 1.0 op_sel:[0,1,0]
	v_cvt_scalef32_pk_bf16_fp4 v58, v94, 1.0 op_sel:[1,1,0]
	s_add_u32 s26, s13, s26
	v_dot2_f32_bf16 v56, v50, v22, v56
	v_dot2_f32_bf16 v48, v52, v20, v48
	s_addc_u32 s27, s12, s27
	v_dot2_f32_bf16 v56, v54, v26, v56
	v_dot2_f32_bf16 v48, v58, v24, v48
	v_cvt_scalef32_pk_bf16_fp4 v50, v95, 1.0
	v_cvt_scalef32_pk_bf16_fp4 v52, v95, 1.0 op_sel:[1,0,0]
	v_cvt_scalef32_pk_bf16_fp4 v54, v95, 1.0 op_sel:[0,1,0]
	v_cvt_scalef32_pk_bf16_fp4 v58, v95, 1.0 op_sel:[1,1,0]
	s_nop 0
	v_dot2_f32_bf16 v56, v50, v30, v56
	v_dot2_f32_bf16 v48, v52, v28, v48
	s_nop 0
	v_dot2_f32_bf16 v56, v54, v36, v56
	v_dot2_f32_bf16 v48, v58, v34, v48
	s_nop 0
	s_nop 2
	v_add_f32_e32 v47, v56, v48
	v_lshl_add_u64 v[48:49], s[26:27], 0, v[32:33]
	global_load_dwordx4 v[92:95], v[48:49], off
	s_waitcnt vmcnt(15)
	v_cvt_scalef32_pk_bf16_fp4 v48, v96, 1.0
	v_cvt_scalef32_pk_bf16_fp4 v50, v96, 1.0 op_sel:[1,0,0]
	v_cvt_scalef32_pk_bf16_fp4 v52, v96, 1.0 op_sel:[0,1,0]
	v_cvt_scalef32_pk_bf16_fp4 v54, v96, 1.0 op_sel:[1,1,0]
	v_dot2_f32_bf16 v56, v48, v6, 0
	v_dot2_f32_bf16 v48, v50, v4, 0
	v_dot2_f32_bf16 v56, v52, v10, v56
	v_readlane_b32 s26, v2, 7
	v_dot2_f32_bf16 v48, v54, v8, v48
	v_cvt_scalef32_pk_bf16_fp4 v50, v97, 1.0
	v_cvt_scalef32_pk_bf16_fp4 v52, v97, 1.0 op_sel:[1,0,0]
	v_cvt_scalef32_pk_bf16_fp4 v54, v97, 1.0 op_sel:[0,1,0]
	v_cvt_scalef32_pk_bf16_fp4 v58, v97, 1.0 op_sel:[1,1,0]
	s_lshr_b32 s26, s26, 7
	v_dot2_f32_bf16 v56, v50, v14, v56
	v_dot2_f32_bf16 v48, v52, v12, v48
	s_mov_b32 s27, s86
	v_dot2_f32_bf16 v56, v54, v18, v56
	v_dot2_f32_bf16 v48, v58, v16, v48
	v_cvt_scalef32_pk_bf16_fp4 v50, v98, 1.0
	v_cvt_scalef32_pk_bf16_fp4 v52, v98, 1.0 op_sel:[1,0,0]
	v_cvt_scalef32_pk_bf16_fp4 v54, v98, 1.0 op_sel:[0,1,0]
	v_cvt_scalef32_pk_bf16_fp4 v58, v98, 1.0 op_sel:[1,1,0]
	s_lshl_b64 s[26:27], s[26:27], 10
	v_dot2_f32_bf16 v56, v50, v22, v56
	v_dot2_f32_bf16 v48, v52, v20, v48
	s_add_u32 s26, s13, s26
	v_dot2_f32_bf16 v56, v54, v26, v56
	v_dot2_f32_bf16 v48, v58, v24, v48
	v_cvt_scalef32_pk_bf16_fp4 v50, v99, 1.0
	v_cvt_scalef32_pk_bf16_fp4 v52, v99, 1.0 op_sel:[1,0,0]
	v_cvt_scalef32_pk_bf16_fp4 v54, v99, 1.0 op_sel:[0,1,0]
	v_cvt_scalef32_pk_bf16_fp4 v58, v99, 1.0 op_sel:[1,1,0]
	s_addc_u32 s27, s12, s27
	v_dot2_f32_bf16 v56, v50, v30, v56
	v_dot2_f32_bf16 v48, v52, v28, v48
	s_nop 0
	v_dot2_f32_bf16 v56, v54, v36, v56
	v_dot2_f32_bf16 v48, v58, v34, v48
	s_nop 2
	v_add_f32_e32 v48, v56, v48
	v_lshl_add_u64 v[50:51], s[26:27], 0, v[32:33]
	global_load_dwordx4 v[96:99], v[50:51], off
	s_waitcnt vmcnt(15)
	v_cvt_scalef32_pk_bf16_fp4 v50, v100, 1.0
	v_cvt_scalef32_pk_bf16_fp4 v52, v100, 1.0 op_sel:[1,0,0]
	v_cvt_scalef32_pk_bf16_fp4 v54, v100, 1.0 op_sel:[0,1,0]
	v_cvt_scalef32_pk_bf16_fp4 v56, v100, 1.0 op_sel:[1,1,0]
	v_readlane_b32 s26, v2, 8
	v_dot2_f32_bf16 v58, v50, v6, 0
	v_dot2_f32_bf16 v50, v52, v4, 0
	v_dot2_f32_bf16 v58, v54, v10, v58
	s_lshr_b32 s26, s26, 7
	v_dot2_f32_bf16 v50, v56, v8, v50
	v_cvt_scalef32_pk_bf16_fp4 v52, v101, 1.0
	v_cvt_scalef32_pk_bf16_fp4 v54, v101, 1.0 op_sel:[1,0,0]
	v_cvt_scalef32_pk_bf16_fp4 v56, v101, 1.0 op_sel:[0,1,0]
	v_cvt_scalef32_pk_bf16_fp4 v60, v101, 1.0 op_sel:[1,1,0]
	s_mov_b32 s27, s86
	v_dot2_f32_bf16 v58, v52, v14, v58
	v_dot2_f32_bf16 v50, v54, v12, v50
	s_lshl_b64 s[26:27], s[26:27], 10
	v_dot2_f32_bf16 v58, v56, v18, v58
	v_dot2_f32_bf16 v50, v60, v16, v50
	v_cvt_scalef32_pk_bf16_fp4 v52, v102, 1.0
	v_cvt_scalef32_pk_bf16_fp4 v54, v102, 1.0 op_sel:[1,0,0]
	v_cvt_scalef32_pk_bf16_fp4 v56, v102, 1.0 op_sel:[0,1,0]
	v_cvt_scalef32_pk_bf16_fp4 v60, v102, 1.0 op_sel:[1,1,0]
	s_add_u32 s26, s13, s26
	v_dot2_f32_bf16 v58, v52, v22, v58
	v_dot2_f32_bf16 v50, v54, v20, v50
	s_addc_u32 s27, s12, s27
	v_dot2_f32_bf16 v58, v56, v26, v58
	v_dot2_f32_bf16 v50, v60, v24, v50
	v_cvt_scalef32_pk_bf16_fp4 v52, v103, 1.0
	v_cvt_scalef32_pk_bf16_fp4 v54, v103, 1.0 op_sel:[1,0,0]
	v_cvt_scalef32_pk_bf16_fp4 v56, v103, 1.0 op_sel:[0,1,0]
	v_cvt_scalef32_pk_bf16_fp4 v60, v103, 1.0 op_sel:[1,1,0]
	s_nop 0
	v_dot2_f32_bf16 v58, v52, v30, v58
	v_dot2_f32_bf16 v50, v54, v28, v50
	s_nop 0
	v_dot2_f32_bf16 v58, v56, v36, v58
	v_dot2_f32_bf16 v50, v60, v34, v50
	s_nop 0
	s_nop 2
	v_add_f32_e32 v49, v58, v50
	v_lshl_add_u64 v[50:51], s[26:27], 0, v[32:33]
	global_load_dwordx4 v[100:103], v[50:51], off
	s_waitcnt vmcnt(15)
; #define P4_FOR16(M) M(0) M(1) M(2) M(3) M(4) M(5) M(6) M(7) M(8) M(9) M(10) M(11) M(12) M(13) M(14) M(15)
; #define P4_U(i) { P4_DOT(b##i, part[i]); const int nk_ = __builtin_amdgcn_readlane(ksel, nb + i); P4_LOAD(b##i, Ug, nk_); }
; #define P4_U(i) { P4_DOT(b##i, part[i]); const int nk_ = __builtin_amdgcn_readlane(kn, i); P4_LOAD(b##i, nbase, nk_); }
; __device__ __forceinline__ void peer_gather_f4p(const float* X, const int* __restrict__ IDX, const float* __restrict__ G, ...
;     ...
;         for (int bt = 0; bt < 7; ++bt) {
;             const int ksel = (bt + 1 < 4) ? k0 : k1;
;             const int nb = (16 * (bt + 1)) & 63;
;     ...
;             P4_FOR16(P4_U)
	v_cvt_scalef32_pk_bf16_fp4 v50, v104, 1.0
	v_cvt_scalef32_pk_bf16_fp4 v52, v104, 1.0 op_sel:[1,0,0]
	v_cvt_scalef32_pk_bf16_fp4 v54, v104, 1.0 op_sel:[0,1,0]
	v_cvt_scalef32_pk_bf16_fp4 v56, v104, 1.0 op_sel:[1,1,0]
	v_dot2_f32_bf16 v58, v50, v6, 0
	v_dot2_f32_bf16 v50, v52, v4, 0
	v_dot2_f32_bf16 v58, v54, v10, v58
	v_readlane_b32 s26, v2, 9
	v_dot2_f32_bf16 v50, v56, v8, v50
	v_cvt_scalef32_pk_bf16_fp4 v52, v105, 1.0
	v_cvt_scalef32_pk_bf16_fp4 v54, v105, 1.0 op_sel:[1,0,0]
	v_cvt_scalef32_pk_bf16_fp4 v56, v105, 1.0 op_sel:[0,1,0]
	v_cvt_scalef32_pk_bf16_fp4 v60, v105, 1.0 op_sel:[1,1,0]
	s_lshr_b32 s26, s26, 7
	v_dot2_f32_bf16 v58, v52, v14, v58
	v_dot2_f32_bf16 v50, v54, v12, v50
	s_mov_b32 s27, s86
	v_dot2_f32_bf16 v58, v56, v18, v58
	v_dot2_f32_bf16 v50, v60, v16, v50
	v_cvt_scalef32_pk_bf16_fp4 v52, v106, 1.0
	v_cvt_scalef32_pk_bf16_fp4 v54, v106, 1.0 op_sel:[1,0,0]
	v_cvt_scalef32_pk_bf16_fp4 v56, v106, 1.0 op_sel:[0,1,0]
	v_cvt_scalef32_pk_bf16_fp4 v60, v106, 1.0 op_sel:[1,1,0]
	s_lshl_b64 s[26:27], s[26:27], 10
	v_dot2_f32_bf16 v58, v52, v22, v58
	v_dot2_f32_bf16 v50, v54, v20, v50
	s_add_u32 s26, s13, s26
	v_dot2_f32_bf16 v58, v56, v26, v58
	v_dot2_f32_bf16 v50, v60, v24, v50
	v_cvt_scalef32_pk_bf16_fp4 v52, v107, 1.0
	v_cvt_scalef32_pk_bf16_fp4 v54, v107, 1.0 op_sel:[1,0,0]
	v_cvt_scalef32_pk_bf16_fp4 v56, v107, 1.0 op_sel:[0,1,0]
	v_cvt_scalef32_pk_bf16_fp4 v60, v107, 1.0 op_sel:[1,1,0]
	s_addc_u32 s27, s12, s27
	v_dot2_f32_bf16 v58, v52, v30, v58
	v_dot2_f32_bf16 v50, v54, v28, v50
	s_nop 0
	v_dot2_f32_bf16 v58, v56, v36, v58
	v_dot2_f32_bf16 v50, v60, v34, v50
	s_nop 2
	v_add_f32_e32 v50, v58, v50
	v_lshl_add_u64 v[52:53], s[26:27], 0, v[32:33]
	global_load_dwordx4 v[104:107], v[52:53], off
	s_waitcnt vmcnt(15)
	v_cvt_scalef32_pk_bf16_fp4 v52, v108, 1.0
	v_cvt_scalef32_pk_bf16_fp4 v54, v108, 1.0 op_sel:[1,0,0]
	v_cvt_scalef32_pk_bf16_fp4 v56, v108, 1.0 op_sel:[0,1,0]
	v_cvt_scalef32_pk_bf16_fp4 v58, v108, 1.0 op_sel:[1,1,0]
	v_readlane_b32 s26, v2, 10
	v_dot2_f32_bf16 v60, v52, v6, 0
	v_dot2_f32_bf16 v52, v54, v4, 0
	v_dot2_f32_bf16 v60, v56, v10, v60
	s_lshr_b32 s26, s26, 7
	v_dot2_f32_bf16 v52, v58, v8, v52
	v_cvt_scalef32_pk_bf16_fp4 v54, v109, 1.0
	v_cvt_scalef32_pk_bf16_fp4 v56, v109, 1.0 op_sel:[1,0,0]
	v_cvt_scalef32_pk_bf16_fp4 v58, v109, 1.0 op_sel:[0,1,0]
	v_cvt_scalef32_pk_bf16_fp4 v62, v109, 1.0 op_sel:[1,1,0]
	s_mov_b32 s27, s86
	v_dot2_f32_bf16 v60, v54, v14, v60
	v_dot2_f32_bf16 v52, v56, v12, v52
	s_lshl_b64 s[26:27], s[26:27], 10
	v_dot2_f32_bf16 v60, v58, v18, v60
	v_dot2_f32_bf16 v52, v62, v16, v52
	v_cvt_scalef32_pk_bf16_fp4 v54, v110, 1.0
	v_cvt_scalef32_pk_bf16_fp4 v56, v110, 1.0 op_sel:[1,0,0]
	v_cvt_scalef32_pk_bf16_fp4 v58, v110, 1.0 op_sel:[0,1,0]
	v_cvt_scalef32_pk_bf16_fp4 v62, v110, 1.0 op_sel:[1,1,0]
	s_add_u32 s26, s13, s26
	v_dot2_f32_bf16 v60, v54, v22, v60
	v_dot2_f32_bf16 v52, v56, v20, v52
	s_addc_u32 s27, s12, s27
	v_dot2_f32_bf16 v60, v58, v26, v60
	v_dot2_f32_bf16 v52, v62, v24, v52
	v_cvt_scalef32_pk_bf16_fp4 v54, v111, 1.0
	v_cvt_scalef32_pk_bf16_fp4 v56, v111, 1.0 op_sel:[1,0,0]
	v_cvt_scalef32_pk_bf16_fp4 v58, v111, 1.0 op_sel:[0,1,0]
	v_cvt_scalef32_pk_bf16_fp4 v62, v111, 1.0 op_sel:[1,1,0]
	s_nop 0
	v_dot2_f32_bf16 v60, v54, v30, v60
	v_dot2_f32_bf16 v52, v56, v28, v52
	s_nop 0
	v_dot2_f32_bf16 v60, v58, v36, v60
	v_dot2_f32_bf16 v52, v62, v34, v52
	s_nop 0
	s_nop 2
	v_add_f32_e32 v51, v60, v52
	v_lshl_add_u64 v[52:53], s[26:27], 0, v[32:33]
	global_load_dwordx4 v[108:111], v[52:53], off
	s_waitcnt vmcnt(15)
	v_cvt_scalef32_pk_bf16_fp4 v52, v112, 1.0
	v_cvt_scalef32_pk_bf16_fp4 v54, v112, 1.0 op_sel:[1,0,0]
	v_cvt_scalef32_pk_bf16_fp4 v56, v112, 1.0 op_sel:[0,1,0]
	v_cvt_scalef32_pk_bf16_fp4 v58, v112, 1.0 op_sel:[1,1,0]
	v_dot2_f32_bf16 v60, v52, v6, 0
	v_dot2_f32_bf16 v52, v54, v4, 0
	v_dot2_f32_bf16 v60, v56, v10, v60
	v_readlane_b32 s26, v2, 11
	v_dot2_f32_bf16 v52, v58, v8, v52
	v_cvt_scalef32_pk_bf16_fp4 v54, v113, 1.0
	v_cvt_scalef32_pk_bf16_fp4 v56, v113, 1.0 op_sel:[1,0,0]
	v_cvt_scalef32_pk_bf16_fp4 v58, v113, 1.0 op_sel:[0,1,0]
	v_cvt_scalef32_pk_bf16_fp4 v62, v113, 1.0 op_sel:[1,1,0]
	s_lshr_b32 s26, s26, 7
	v_dot2_f32_bf16 v60, v54, v14, v60
	v_dot2_f32_bf16 v52, v56, v12, v52
	s_mov_b32 s27, s86
	v_dot2_f32_bf16 v60, v58, v18, v60
	v_dot2_f32_bf16 v52, v62, v16, v52
	v_cvt_scalef32_pk_bf16_fp4 v54, v114, 1.0
	v_cvt_scalef32_pk_bf16_fp4 v56, v114, 1.0 op_sel:[1,0,0]
	v_cvt_scalef32_pk_bf16_fp4 v58, v114, 1.0 op_sel:[0,1,0]
	v_cvt_scalef32_pk_bf16_fp4 v62, v114, 1.0 op_sel:[1,1,0]
	s_lshl_b64 s[26:27], s[26:27], 10
	v_dot2_f32_bf16 v60, v54, v22, v60
	v_dot2_f32_bf16 v52, v56, v20, v52
	s_add_u32 s26, s13, s26
	v_dot2_f32_bf16 v60, v58, v26, v60
	v_dot2_f32_bf16 v52, v62, v24, v52
	v_cvt_scalef32_pk_bf16_fp4 v54, v115, 1.0
	v_cvt_scalef32_pk_bf16_fp4 v56, v115, 1.0 op_sel:[1,0,0]
	v_cvt_scalef32_pk_bf16_fp4 v58, v115, 1.0 op_sel:[0,1,0]
	v_cvt_scalef32_pk_bf16_fp4 v62, v115, 1.0 op_sel:[1,1,0]
	s_addc_u32 s27, s12, s27
	v_dot2_f32_bf16 v60, v54, v30, v60
	v_dot2_f32_bf16 v52, v56, v28, v52
	s_nop 0
	v_dot2_f32_bf16 v60, v58, v36, v60
	v_dot2_f32_bf16 v52, v62, v34, v52
	s_nop 0
	s_nop 2
	v_add_f32_e32 v80, v60, v52
	v_lshl_add_u64 v[52:53], s[26:27], 0, v[32:33]
	global_load_dwordx4 v[112:115], v[52:53], off
	s_waitcnt vmcnt(15)
; #define P4_FOR16(M) M(0) M(1) M(2) M(3) M(4) M(5) M(6) M(7) M(8) M(9) M(10) M(11) M(12) M(13) M(14) M(15)
; #define P4_U(i) { P4_DOT(b##i, part[i]); const int nk_ = __builtin_amdgcn_readlane(ksel, nb + i); P4_LOAD(b##i, Ug, nk_); }
; #define P4_U(i) { P4_DOT(b##i, part[i]); const int nk_ = __builtin_amdgcn_readlane(kn, i); P4_LOAD(b##i, nbase, nk_); }
; __device__ __forceinline__ void peer_gather_f4p(const float* X, const int* __restrict__ IDX, const float* __restrict__ G, ...
;     ...
;         for (int bt = 0; bt < 7; ++bt) {
;             const int ksel = (bt + 1 < 4) ? k0 : k1;
;             const int nb = (16 * (bt + 1)) & 63;
;     ...
;             P4_FOR16(P4_U)
	v_cvt_scalef32_pk_bf16_fp4 v52, v116, 1.0
	v_cvt_scalef32_pk_bf16_fp4 v54, v116, 1.0 op_sel:[1,0,0]
	v_cvt_scalef32_pk_bf16_fp4 v56, v116, 1.0 op_sel:[0,1,0]
	v_cvt_scalef32_pk_bf16_fp4 v58, v116, 1.0 op_sel:[1,1,0]
	v_dot2_f32_bf16 v60, v52, v6, 0
	v_dot2_f32_bf16 v52, v54, v4, 0
	v_dot2_f32_bf16 v60, v56, v10, v60
	v_readlane_b32 s26, v2, 12
	v_dot2_f32_bf16 v52, v58, v8, v52
	v_cvt_scalef32_pk_bf16_fp4 v54, v117, 1.0
	v_cvt_scalef32_pk_bf16_fp4 v56, v117, 1.0 op_sel:[1,0,0]
	v_cvt_scalef32_pk_bf16_fp4 v58, v117, 1.0 op_sel:[0,1,0]
	v_cvt_scalef32_pk_bf16_fp4 v62, v117, 1.0 op_sel:[1,1,0]
	s_lshr_b32 s26, s26, 7
	v_dot2_f32_bf16 v60, v54, v14, v60
	v_dot2_f32_bf16 v52, v56, v12, v52
	s_mov_b32 s27, s86
	v_dot2_f32_bf16 v60, v58, v18, v60
	v_dot2_f32_bf16 v52, v62, v16, v52
	v_cvt_scalef32_pk_bf16_fp4 v54, v118, 1.0
	v_cvt_scalef32_pk_bf16_fp4 v56, v118, 1.0 op_sel:[1,0,0]
	v_cvt_scalef32_pk_bf16_fp4 v58, v118, 1.0 op_sel:[0,1,0]
	v_cvt_scalef32_pk_bf16_fp4 v62, v118, 1.0 op_sel:[1,1,0]
	s_lshl_b64 s[26:27], s[26:27], 10
	v_dot2_f32_bf16 v60, v54, v22, v60
	v_dot2_f32_bf16 v52, v56, v20, v52
	s_add_u32 s26, s13, s26
	v_dot2_f32_bf16 v60, v58, v26, v60
	v_dot2_f32_bf16 v52, v62, v24, v52
	v_cvt_scalef32_pk_bf16_fp4 v54, v119, 1.0
	v_cvt_scalef32_pk_bf16_fp4 v56, v119, 1.0 op_sel:[1,0,0]
	v_cvt_scalef32_pk_bf16_fp4 v58, v119, 1.0 op_sel:[0,1,0]
	v_cvt_scalef32_pk_bf16_fp4 v62, v119, 1.0 op_sel:[1,1,0]
	s_addc_u32 s27, s12, s27
	v_dot2_f32_bf16 v60, v54, v30, v60
	v_dot2_f32_bf16 v52, v56, v28, v52
	s_nop 0
	v_dot2_f32_bf16 v60, v58, v36, v60
	v_dot2_f32_bf16 v52, v62, v34, v52
	s_nop 0
	s_nop 2
	v_add_f32_e32 v81, v60, v52
	v_lshl_add_u64 v[52:53], s[26:27], 0, v[32:33]
	global_load_dwordx4 v[116:119], v[52:53], off
	s_waitcnt vmcnt(15)
	v_cvt_scalef32_pk_bf16_fp4 v52, v120, 1.0
	v_cvt_scalef32_pk_bf16_fp4 v54, v120, 1.0 op_sel:[1,0,0]
	v_cvt_scalef32_pk_bf16_fp4 v56, v120, 1.0 op_sel:[0,1,0]
	v_cvt_scalef32_pk_bf16_fp4 v58, v120, 1.0 op_sel:[1,1,0]
	v_dot2_f32_bf16 v60, v52, v6, 0
	v_dot2_f32_bf16 v52, v54, v4, 0
	v_dot2_f32_bf16 v60, v56, v10, v60
	v_readlane_b32 s26, v2, 13
	v_dot2_f32_bf16 v52, v58, v8, v52
	v_cvt_scalef32_pk_bf16_fp4 v54, v121, 1.0
	v_cvt_scalef32_pk_bf16_fp4 v56, v121, 1.0 op_sel:[1,0,0]
	v_cvt_scalef32_pk_bf16_fp4 v58, v121, 1.0 op_sel:[0,1,0]
	v_cvt_scalef32_pk_bf16_fp4 v62, v121, 1.0 op_sel:[1,1,0]
	s_lshr_b32 s26, s26, 7
	v_dot2_f32_bf16 v60, v54, v14, v60
	v_dot2_f32_bf16 v52, v56, v12, v52
	s_mov_b32 s27, s86
	v_dot2_f32_bf16 v60, v58, v18, v60
	v_dot2_f32_bf16 v52, v62, v16, v52
	v_cvt_scalef32_pk_bf16_fp4 v54, v122, 1.0
	v_cvt_scalef32_pk_bf16_fp4 v56, v122, 1.0 op_sel:[1,0,0]
	v_cvt_scalef32_pk_bf16_fp4 v58, v122, 1.0 op_sel:[0,1,0]
	v_cvt_scalef32_pk_bf16_fp4 v62, v122, 1.0 op_sel:[1,1,0]
	s_lshl_b64 s[26:27], s[26:27], 10
	v_dot2_f32_bf16 v60, v54, v22, v60
	v_dot2_f32_bf16 v52, v56, v20, v52
	s_add_u32 s26, s13, s26
	v_dot2_f32_bf16 v60, v58, v26, v60
	v_dot2_f32_bf16 v52, v62, v24, v52
	v_cvt_scalef32_pk_bf16_fp4 v54, v123, 1.0
	v_cvt_scalef32_pk_bf16_fp4 v56, v123, 1.0 op_sel:[1,0,0]
	v_cvt_scalef32_pk_bf16_fp4 v58, v123, 1.0 op_sel:[0,1,0]
	v_cvt_scalef32_pk_bf16_fp4 v62, v123, 1.0 op_sel:[1,1,0]
	s_addc_u32 s27, s12, s27
	v_dot2_f32_bf16 v60, v54, v30, v60
	v_dot2_f32_bf16 v52, v56, v28, v52
	s_nop 0
	v_dot2_f32_bf16 v60, v58, v36, v60
	v_dot2_f32_bf16 v52, v62, v34, v52
	s_nop 0
	s_nop 2
	v_add_f32_e32 v82, v60, v52
	v_lshl_add_u64 v[52:53], s[26:27], 0, v[32:33]
	global_load_dwordx4 v[120:123], v[52:53], off
	s_waitcnt vmcnt(15)
	v_cvt_scalef32_pk_bf16_fp4 v52, v124, 1.0
	v_cvt_scalef32_pk_bf16_fp4 v54, v124, 1.0 op_sel:[1,0,0]
	v_cvt_scalef32_pk_bf16_fp4 v56, v124, 1.0 op_sel:[0,1,0]
	v_cvt_scalef32_pk_bf16_fp4 v58, v124, 1.0 op_sel:[1,1,0]
	v_dot2_f32_bf16 v60, v52, v6, 0
	v_dot2_f32_bf16 v52, v54, v4, 0
	v_dot2_f32_bf16 v60, v56, v10, v60
	v_readlane_b32 s26, v2, 14
	v_dot2_f32_bf16 v52, v58, v8, v52
	v_cvt_scalef32_pk_bf16_fp4 v54, v125, 1.0
	v_cvt_scalef32_pk_bf16_fp4 v56, v125, 1.0 op_sel:[1,0,0]
	v_cvt_scalef32_pk_bf16_fp4 v58, v125, 1.0 op_sel:[0,1,0]
	v_cvt_scalef32_pk_bf16_fp4 v62, v125, 1.0 op_sel:[1,1,0]
	s_lshr_b32 s26, s26, 7
	v_dot2_f32_bf16 v60, v54, v14, v60
	v_dot2_f32_bf16 v52, v56, v12, v52
	s_mov_b32 s27, s86
	v_dot2_f32_bf16 v60, v58, v18, v60
	v_dot2_f32_bf16 v52, v62, v16, v52
	v_cvt_scalef32_pk_bf16_fp4 v54, v126, 1.0
	v_cvt_scalef32_pk_bf16_fp4 v56, v126, 1.0 op_sel:[1,0,0]
	v_cvt_scalef32_pk_bf16_fp4 v58, v126, 1.0 op_sel:[0,1,0]
	v_cvt_scalef32_pk_bf16_fp4 v62, v126, 1.0 op_sel:[1,1,0]
	s_lshl_b64 s[26:27], s[26:27], 10
	v_dot2_f32_bf16 v60, v54, v22, v60
	v_dot2_f32_bf16 v52, v56, v20, v52
	s_add_u32 s26, s13, s26
	v_dot2_f32_bf16 v60, v58, v26, v60
	v_dot2_f32_bf16 v52, v62, v24, v52
	v_cvt_scalef32_pk_bf16_fp4 v54, v127, 1.0
	v_cvt_scalef32_pk_bf16_fp4 v56, v127, 1.0 op_sel:[1,0,0]
	v_cvt_scalef32_pk_bf16_fp4 v58, v127, 1.0 op_sel:[0,1,0]
	v_cvt_scalef32_pk_bf16_fp4 v62, v127, 1.0 op_sel:[1,1,0]
	s_addc_u32 s27, s12, s27
	v_dot2_f32_bf16 v60, v54, v30, v60
	v_dot2_f32_bf16 v52, v56, v28, v52
	s_nop 0
	v_dot2_f32_bf16 v60, v58, v36, v60
	v_dot2_f32_bf16 v52, v62, v34, v52
	s_nop 0
	s_nop 2
	v_add_f32_e32 v62, v60, v52
	v_lshl_add_u64 v[52:53], s[26:27], 0, v[32:33]
	global_load_dwordx4 v[124:127], v[52:53], off
	s_waitcnt vmcnt(15)
; __device__ __forceinline__ float gelu_tanh(float h) {
;     return 0.5f * h * (1.f + tanhf(0.7978845608028654f * (h + 0.044715f * h * h * h)));
; }
	v_cvt_scalef32_pk_bf16_fp4 v52, v128, 1.0
	v_cvt_scalef32_pk_bf16_fp4 v54, v128, 1.0 op_sel:[1,0,0]
	v_cvt_scalef32_pk_bf16_fp4 v56, v128, 1.0 op_sel:[0,1,0]
	v_cvt_scalef32_pk_bf16_fp4 v58, v128, 1.0 op_sel:[1,1,0]
	v_readlane_b32 s26, v2, 15
	v_dot2_f32_bf16 v60, v52, v6, 0
	v_dot2c_f32_bf16_e32 v38, v54, v4
	s_lshr_b32 s26, s26, 7
	v_dot2_f32_bf16 v60, v56, v10, v60
	v_dot2c_f32_bf16_e32 v38, v58, v8
	v_cvt_scalef32_pk_bf16_fp4 v4, v129, 1.0
	v_cvt_scalef32_pk_bf16_fp4 v6, v129, 1.0 op_sel:[1,0,0]
	v_cvt_scalef32_pk_bf16_fp4 v8, v129, 1.0 op_sel:[0,1,0]
	v_cvt_scalef32_pk_bf16_fp4 v10, v129, 1.0 op_sel:[1,1,0]
	s_mov_b32 s27, s86
	v_dot2_f32_bf16 v60, v4, v14, v60
	v_dot2c_f32_bf16_e32 v38, v6, v12
	s_lshl_b64 s[26:27], s[26:27], 10
	v_dot2_f32_bf16 v60, v8, v18, v60
	v_dot2c_f32_bf16_e32 v38, v10, v16
	v_cvt_scalef32_pk_bf16_fp4 v4, v130, 1.0
	v_cvt_scalef32_pk_bf16_fp4 v6, v130, 1.0 op_sel:[1,0,0]
	v_cvt_scalef32_pk_bf16_fp4 v8, v130, 1.0 op_sel:[0,1,0]
	v_cvt_scalef32_pk_bf16_fp4 v10, v130, 1.0 op_sel:[1,1,0]
	s_add_u32 s26, s13, s26
	v_dot2_f32_bf16 v60, v4, v22, v60
	v_dot2c_f32_bf16_e32 v38, v6, v20
	s_addc_u32 s27, s12, s27
	v_dot2_f32_bf16 v60, v8, v26, v60
	v_dot2c_f32_bf16_e32 v38, v10, v24
	v_cvt_scalef32_pk_bf16_fp4 v4, v131, 1.0
	v_cvt_scalef32_pk_bf16_fp4 v6, v131, 1.0 op_sel:[1,0,0]
	v_cvt_scalef32_pk_bf16_fp4 v8, v131, 1.0 op_sel:[0,1,0]
	v_cvt_scalef32_pk_bf16_fp4 v10, v131, 1.0 op_sel:[1,1,0]
	v_cndmask_b32_e64 v2, v49, v41, s[46:47]
	v_dot2_f32_bf16 v60, v4, v30, v60
	v_dot2c_f32_bf16_e32 v38, v6, v28
	v_cndmask_b32_e64 v7, v43, v51, s[46:47]
	v_dot2_f32_bf16 v60, v8, v36, v60
	v_dot2c_f32_bf16_e32 v38, v10, v34
	ds_swizzle_b32 v7, v7 offset:swizzle(SWAP,8)
	s_nop 2
	v_add_f32_e32 v6, v60, v38
	v_lshl_add_u64 v[4:5], s[26:27], 0, v[32:33]
	global_load_dwordx4 v[128:131], v[4:5], off
	v_cndmask_b32_e64 v4, v41, v49, s[46:47]
	ds_swizzle_b32 v4, v4 offset:swizzle(SWAP,8)
	v_cndmask_b32_e64 v5, v42, v50, s[46:47]
	ds_swizzle_b32 v5, v5 offset:swizzle(SWAP,8)
	v_cndmask_b32_e64 v8, v44, v80, s[46:47]
	ds_swizzle_b32 v8, v8 offset:swizzle(SWAP,8)
	v_cndmask_b32_e64 v9, v45, v81, s[46:47]
	ds_swizzle_b32 v9, v9 offset:swizzle(SWAP,8)
	v_cndmask_b32_e64 v10, v46, v82, s[46:47]
	s_waitcnt lgkmcnt(3)
	v_add_f32_e32 v2, v2, v4
	v_cndmask_b32_e64 v4, v50, v42, s[46:47]
	ds_swizzle_b32 v10, v10 offset:swizzle(SWAP,8)
	v_cndmask_b32_e64 v11, v47, v62, s[46:47]
	s_waitcnt lgkmcnt(3)
	v_add_f32_e32 v4, v4, v5
	v_cndmask_b32_e64 v5, v51, v43, s[46:47]
	ds_swizzle_b32 v11, v11 offset:swizzle(SWAP,8)
	v_add_f32_e32 v5, v5, v7
	v_cndmask_b32_e64 v7, v80, v44, s[46:47]
	s_waitcnt lgkmcnt(3)
	v_add_f32_e32 v7, v7, v8
	v_cndmask_b32_e64 v8, v81, v45, s[46:47]
	s_waitcnt lgkmcnt(2)
	v_add_f32_e32 v8, v8, v9
	v_cndmask_b32_e64 v9, v82, v46, s[46:47]
	s_waitcnt lgkmcnt(1)
	v_add_f32_e32 v9, v9, v10
	v_cndmask_b32_e64 v10, v62, v47, s[46:47]
	s_waitcnt lgkmcnt(0)
	v_add_f32_e32 v10, v10, v11
	v_cndmask_b32_e64 v11, v6, v48, s[46:47]
	v_cndmask_b32_e64 v6, v48, v6, s[46:47]
	ds_swizzle_b32 v6, v6 offset:swizzle(SWAP,8)
	s_waitcnt lgkmcnt(0)
	v_add_f32_e32 v6, v11, v6
	v_cndmask_b32_e64 v11, v8, v2, s[44:45]
	v_cndmask_b32_e64 v2, v2, v8, s[44:45]
	v_cndmask_b32_e64 v8, v9, v4, s[44:45]
	v_cndmask_b32_e64 v4, v4, v9, s[44:45]
	ds_swizzle_b32 v4, v4 offset:swizzle(SWAP,4)
	ds_swizzle_b32 v2, v2 offset:swizzle(SWAP,4)
	s_waitcnt lgkmcnt(1)
	v_add_f32_e32 v4, v8, v4
	v_cndmask_b32_e64 v8, v10, v5, s[44:45]
	v_cndmask_b32_e64 v5, v5, v10, s[44:45]
	ds_swizzle_b32 v5, v5 offset:swizzle(SWAP,4)
	s_waitcnt lgkmcnt(1)
	v_add_f32_e32 v2, v11, v2
	s_waitcnt lgkmcnt(0)
	v_add_f32_e32 v5, v8, v5
	v_cndmask_b32_e64 v8, v6, v7, s[44:45]
	v_cndmask_b32_e64 v6, v7, v6, s[44:45]
	ds_swizzle_b32 v6, v6 offset:swizzle(SWAP,4)
	v_cndmask_b32_e64 v7, v5, v2, s[42:43]
	v_cndmask_b32_e64 v2, v2, v5, s[42:43]
	ds_swizzle_b32 v2, v2 offset:swizzle(SWAP,2)
	s_waitcnt lgkmcnt(1)
	v_add_f32_e32 v6, v8, v6
	v_cndmask_b32_e64 v5, v6, v4, s[42:43]
	v_cndmask_b32_e64 v4, v4, v6, s[42:43]
	ds_swizzle_b32 v4, v4 offset:swizzle(SWAP,2)
	s_waitcnt lgkmcnt(1)
	v_add_f32_e32 v2, v7, v2
	s_waitcnt lgkmcnt(0)
	v_add_f32_e32 v4, v5, v4
	v_cndmask_b32_e64 v5, v4, v2, s[40:41]
	v_cndmask_b32_e64 v2, v2, v4, s[40:41]
	ds_swizzle_b32 v2, v2 offset:swizzle(SWAP,1)
	s_waitcnt lgkmcnt(0)
	v_add_f32_e32 v2, v5, v2
	ds_swizzle_b32 v4, v2 offset:swizzle(SWAP,16)
	s_waitcnt lgkmcnt(0)
	v_add_f32_e32 v2, v2, v4
	v_mov_b32_e32 v4, v2
	s_nop 1
	v_permlane32_swap_b32_e32 v2, v4
	v_add_f32_e32 v6, v2, v4
	v_lshl_add_u32 v2, v40, 2, s14
	v_add_u32_e32 v4, 0xc0, v2
	ds_read2st64_b32 v[4:5], v4 offset0:9 offset1:17
	s_waitcnt lgkmcnt(0)
	v_mul_f32_e32 v4, v4, v6
	v_mul_f32_e32 v6, 0x3d372713, v4
	v_mul_f32_e32 v6, v4, v6
	v_fma_f32 v6, v4, v6, v4
	v_mul_f32_e32 v6, 0x3f4c422a, v6
	v_cmp_nlt_f32_e64 s[12:13], |v6|, s25
	s_and_saveexec_b64 s[26:27], s[12:13]
	s_xor_b64 s[12:13], exec, s[26:27]
	s_cbranch_execz .LBB0_1240
	v_add_f32_e64 v7, |v6|, |v6|
	v_mul_f32_e32 v8, 0x3fb8aa3b, v7
	v_rndne_f32_e32 v9, v8
	v_sub_f32_e32 v10, v8, v9
	v_fma_f32 v8, v7, s70, -v8
	v_fmac_f32_e32 v8, 0x32a5705f, v7
	v_add_f32_e32 v8, v10, v8
	v_cvt_i32_f32_e32 v9, v9
	v_exp_f32_e32 v8, v8
	v_cmp_ngt_f32_e64 s[40:41], s67, v7
	v_ldexp_f32 v8, v8, v9
	s_nop 0
	v_cndmask_b32_e64 v8, 0, v8, s[40:41]
	v_cmp_nlt_f32_e64 s[40:41], s68, v7
	s_nop 1
	v_cndmask_b32_e64 v7, v205, v8, s[40:41]
	v_add_f32_e32 v7, 1.0, v7
	v_rcp_f32_e32 v7, v7
	s_nop 0
	v_fma_f32 v7, v7, -2.0, 1.0
	s_andn2_saveexec_b64 s[12:13], s[12:13]
	s_cbranch_execnz .LBB0_1241
